# attention item prologue de-serialised: the four Q loads issued together with counted waits instead of load/vmcnt(0) four times
# speedup vs baseline: 1.0035x; 1.0011x over previous
.LBB0_246:
	s_lshl_b32 s1, s71, 2
	s_and_b32 s22, s1, 0xffffff00
	s_lshr_b32 s0, s71, 3
	s_bfe_u32 s56, s71, 0x30003
	s_or_b32 s24, s22, s72
	s_cmp_lt_i32 s24, 0x8000
	s_movk_i32 s22, 0xfff
	s_cselect_b32 s75, s22, 0x1fff
	s_bfe_u32 s0, s0, 0x10002
	s_andn2_b32 s74, s1, s75
	s_mul_i32 s0, s0, 0x1800000
	s_add_u32 s0, s96, s0
	s_addc_u32 s1, s97, 0
	s_lshl_b32 s22, s71, 4
	s_and_b32 s22, s22, 0x180
	s_add_u32 s22, s0, s22
	v_or_b32_e32 v162, s24, v167
	s_addc_u32 s23, s1, 0
	v_ashrrev_i32_e32 v163, 31, v162
	v_lshl_add_u64 v[12:13], s[22:23], 0, v[158:159]
	v_lshlrev_b64 v[0:1], 9, v[162:163]
	v_lshl_add_u64 v[8:9], v[12:13], 0, v[0:1]
	global_load_dwordx4 v[0:3], v[8:9], off
	v_or_b32_e32 v160, 8, v162
	v_ashrrev_i32_e32 v161, 31, v160
	global_load_dwordx4 v[64:67], v[8:9], off offset:64
	v_lshlrev_b64 v[72:73], 9, v[160:161]
	v_lshl_add_u64 v[72:73], v[12:13], 0, v[72:73]
	global_load_dwordx4 v[68:71], v[72:73], off
	global_load_dwordx4 v[76:79], v[72:73], off offset:64
	s_add_u32 s68, s22, 0x3000000
	s_addc_u32 s69, s23, 0
	s_lshl_b32 s98, s74, 9
	s_add_u32 s100, s68, s98
	s_addc_u32 s101, s69, 0
	s_add_u32 s98, s100, 0x3000000
	s_addc_u32 s99, s101, 0
	s_sub_i32 s76, s24, s74
	s_sub_i32 s0, s76, 64
	s_waitcnt vmcnt(7)
	v_add_u32_e32 v20, s0, v172
	v_min_i32_e32 v21, s75, v20
	s_waitcnt vmcnt(6)
	v_add_u32_e32 v24, s0, v173
	v_min_i32_e32 v25, s75, v24
	s_waitcnt vmcnt(5)
	v_add_u32_e32 v28, s0, v182
	v_min_i32_e32 v29, s75, v28
	s_waitcnt vmcnt(2)
	v_add_u32_e32 v40, s0, v166
	v_min_i32_e32 v32, s75, v40
	v_add_u32_e32 v41, 16, v40
	s_movk_i32 s1, 0xffef
	v_min_i32_e32 v41, s75, v41
	v_or_b32_e32 v128, 32, v166
	v_add_u32_e32 v56, s0, v128
	v_add_u32_e32 v149, s76, v155
	v_add_u32_e32 v150, s76, v172
	v_add_u32_e32 v151, s76, v173
	v_add_u32_e32 v252, s76, v182
	v_or_b32_e32 v251, s76, v167
	v_subrev_u32_e32 v250, s76, v251
	v_or_b32_e32 v144, 8, v251
	v_subrev_u32_e32 v249, s76, v144
	v_add_u32_e32 v196, 0x60, v155
	v_add_u32_e32 v168, 0x60, v172
	v_add_u32_e32 v193, 0x60, v173
	v_add_u32_e32 v194, 0x60, v182
	v_add_u32_e32 v186, s76, v206
	s_waitcnt vmcnt(3)
	v_lshlrev_b32_e32 v4, 16, v0
	v_and_b32_e32 v5, 0xffff0000, v0
	v_lshlrev_b32_e32 v0, 16, v1
	v_and_b32_e32 v1, 0xffff0000, v1
	v_pk_mul_f32 v[4:5], v[4:5], s[58:59] op_sel_hi:[1,0]
	v_pk_mul_f32 v[0:1], v[0:1], s[58:59] op_sel_hi:[1,0]
	v_cvt_pk_bf16_f32 v4, v4, v5
	v_cvt_pk_bf16_f32 v5, v0, v1
	v_lshlrev_b32_e32 v0, 16, v2
	v_and_b32_e32 v1, 0xffff0000, v2
	v_pk_mul_f32 v[0:1], v[0:1], s[58:59] op_sel_hi:[1,0]
	s_nop 0
	v_cvt_pk_bf16_f32 v6, v0, v1
	v_lshlrev_b32_e32 v0, 16, v3
	v_and_b32_e32 v1, 0xffff0000, v3
	v_pk_mul_f32 v[0:1], v[0:1], s[58:59] op_sel_hi:[1,0]
	s_nop 0
	v_cvt_pk_bf16_f32 v7, v0, v1
	s_waitcnt vmcnt(2)
	v_lshlrev_b32_e32 v8, 16, v64
	v_and_b32_e32 v9, 0xffff0000, v64
	v_lshlrev_b32_e32 v0, 16, v65
	v_and_b32_e32 v1, 0xffff0000, v65
	v_pk_mul_f32 v[8:9], v[8:9], s[58:59] op_sel_hi:[1,0]
	v_pk_mul_f32 v[0:1], v[0:1], s[58:59] op_sel_hi:[1,0]
	v_cvt_pk_bf16_f32 v8, v8, v9
	v_cvt_pk_bf16_f32 v9, v0, v1
	v_lshlrev_b32_e32 v0, 16, v66
	v_and_b32_e32 v1, 0xffff0000, v66
	v_pk_mul_f32 v[0:1], v[0:1], s[58:59] op_sel_hi:[1,0]
	s_nop 0
	v_cvt_pk_bf16_f32 v10, v0, v1
	v_lshlrev_b32_e32 v0, 16, v67
	v_and_b32_e32 v1, 0xffff0000, v67
	v_pk_mul_f32 v[0:1], v[0:1], s[58:59] op_sel_hi:[1,0]
	s_nop 0
	v_cvt_pk_bf16_f32 v11, v0, v1
	s_waitcnt vmcnt(1)
	v_lshlrev_b32_e32 v12, 16, v68
	v_and_b32_e32 v13, 0xffff0000, v68
	v_lshlrev_b32_e32 v0, 16, v69
	v_and_b32_e32 v1, 0xffff0000, v69
	v_pk_mul_f32 v[12:13], v[12:13], s[58:59] op_sel_hi:[1,0]
	v_pk_mul_f32 v[0:1], v[0:1], s[58:59] op_sel_hi:[1,0]
	v_cvt_pk_bf16_f32 v12, v12, v13
	v_cvt_pk_bf16_f32 v13, v0, v1
	v_lshlrev_b32_e32 v0, 16, v70
	v_and_b32_e32 v1, 0xffff0000, v70
	v_pk_mul_f32 v[0:1], v[0:1], s[58:59] op_sel_hi:[1,0]
	s_nop 0
	v_cvt_pk_bf16_f32 v14, v0, v1
	v_lshlrev_b32_e32 v0, 16, v71
	v_and_b32_e32 v1, 0xffff0000, v71
	v_pk_mul_f32 v[0:1], v[0:1], s[58:59] op_sel_hi:[1,0]
	s_nop 0
	v_cvt_pk_bf16_f32 v15, v0, v1
	s_waitcnt vmcnt(0)
	v_lshlrev_b32_e32 v16, 16, v76
	v_and_b32_e32 v17, 0xffff0000, v76
	v_pk_mul_f32 v[16:17], v[16:17], s[58:59] op_sel_hi:[1,0]
	s_nop 0
	v_cvt_pk_bf16_f32 v0, v16, v17
	v_lshlrev_b32_e32 v16, 16, v77
	v_and_b32_e32 v17, 0xffff0000, v77
	v_pk_mul_f32 v[16:17], v[16:17], s[58:59] op_sel_hi:[1,0]
	s_nop 0
	v_cvt_pk_bf16_f32 v1, v16, v17
	v_lshlrev_b32_e32 v16, 16, v78
	v_and_b32_e32 v17, 0xffff0000, v78
	v_pk_mul_f32 v[16:17], v[16:17], s[58:59] op_sel_hi:[1,0]
	s_nop 0
	v_cvt_pk_bf16_f32 v2, v16, v17
	v_lshlrev_b32_e32 v16, 16, v79
	v_and_b32_e32 v17, 0xffff0000, v79
	v_pk_mul_f32 v[16:17], v[16:17], s[58:59] op_sel_hi:[1,0]
	s_nop 0
	v_cvt_pk_bf16_f32 v3, v16, v17
	s_mov_b64 s[22:23], 0x6000000
	v_add_u32_e32 v16, s0, v155
	s_sub_i32 s22, 0x80, s76
	s_nop 0
	v_med3_i32 v16, v16, 0, s75
	v_cmp_lt_i32_e32 vcc, -1, v20
	s_nop 1
	v_cndmask_b32_e32 v20, 0, v21, vcc
	v_cmp_lt_i32_e32 vcc, -1, v24
	s_nop 1
	v_cndmask_b32_e32 v24, 0, v25, vcc
	v_cmp_lt_i32_e32 vcc, -1, v28
	s_nop 1
	v_cndmask_b32_e32 v28, 0, v29, vcc
	v_lshl_add_u32 v16, v16, 9, v152
	global_load_dwordx4 v[16:19], v16, s[98:99]
	v_lshl_add_u32 v20, v20, 9, v152
	v_cmp_lt_i32_e32 vcc, -1, v40
	global_load_dwordx4 v[20:23], v20, s[98:99]
	v_lshl_add_u32 v24, v24, 9, v152
	v_cndmask_b32_e32 v32, 0, v32, vcc
	v_cmp_lt_i32_e32 vcc, s1, v40
	global_load_dwordx4 v[24:27], v24, s[98:99]
	v_lshl_add_u32 v28, v28, 9, v152
	v_cndmask_b32_e32 v40, 0, v41, vcc
	global_load_dwordx4 v[28:31], v28, s[98:99]
	v_lshl_add_u32 v36, v32, 9, v158
	v_lshl_add_u32 v40, v40, 9, v158
	s_sub_i32 s1, s76, 32
	global_load_dwordx4 v[32:35], v36, s[100:101]
	s_nop 0
	global_load_dwordx4 v[36:39], v36, s[100:101] offset:64
	s_nop 0
	global_load_dwordx4 v[48:51], v40, s[100:101]
	global_load_dwordx4 v[52:55], v40, s[100:101] offset:64
	v_add_u32_e32 v40, s1, v155
	v_med3_i32 v40, v40, 0, s75
	v_lshl_add_u32 v40, v40, 9, v152
	global_load_dwordx4 v[76:79], v40, s[98:99]
	v_add_u32_e32 v40, s1, v172
	v_med3_i32 v40, v40, 0, s75
	v_lshl_add_u32 v40, v40, 9, v152
	global_load_dwordx4 v[84:87], v40, s[98:99]
	v_add_u32_e32 v40, s1, v173
	v_med3_i32 v40, v40, 0, s75
	v_lshl_add_u32 v40, v40, 9, v152
	global_load_dwordx4 v[88:91], v40, s[98:99]
	v_add_u32_e32 v40, s1, v182
	s_min_i32 s1, s0, 0
	s_sub_i32 s1, 0, s1
	v_med3_i32 v40, v40, 0, s75
	v_lshl_add_u32 v40, v40, 9, v152
	global_load_dwordx4 v[92:95], v40, s[98:99]
	v_min_i32_e32 v40, s75, v56
	v_cmp_lt_i32_e32 vcc, -1, v56
	v_add_u32_e32 v56, 16, v56
	s_nop 0
	v_cndmask_b32_e32 v40, 0, v40, vcc
	v_med3_i32 v56, v56, 0, s75
	v_lshl_add_u32 v44, v40, 9, v158
	v_lshl_add_u32 v60, v56, 9, v158
	global_load_dwordx4 v[40:43], v44, s[100:101]
	s_nop 0
	global_load_dwordx4 v[44:47], v44, s[100:101] offset:64
	s_nop 0
	global_load_dwordx4 v[56:59], v60, s[100:101]
	s_nop 0
	global_load_dwordx4 v[60:63], v60, s[100:101] offset:64
	s_waitcnt vmcnt(15)
	ds_write_b128 v241, v[16:19]
	s_waitcnt vmcnt(14)
	ds_write_b128 v242, v[20:23]
	s_waitcnt vmcnt(13)
	ds_write_b128 v243, v[24:27]
	s_waitcnt vmcnt(12)
	ds_write_b128 v244, v[28:31]
	v_or_b32_e32 v24, 16, v166
	v_add_u32_e32 v24, s76, v24
	v_med3_i32 v16, v149, 0, s75
	v_lshl_add_u32 v16, v16, 9, v152
	global_load_dwordx4 v[64:67], v16, s[98:99]
	s_sub_i32 s0, s75, s0
	v_med3_i32 v16, v150, 0, s75
	v_lshl_add_u32 v16, v16, 9, v152
	global_load_dwordx4 v[68:71], v16, s[98:99]
	v_max_i32_e32 v147, s1, v250
	v_max_i32_e32 v148, s1, v249
	v_med3_i32 v16, v151, 0, s75
	v_lshl_add_u32 v16, v16, 9, v152
	global_load_dwordx4 v[72:75], v16, s[98:99]
	v_med3_i32 v16, v252, 0, s75
	v_lshl_add_u32 v16, v16, 9, v152
	global_load_dwordx4 v[80:83], v16, s[98:99]
	v_add_u32_e32 v16, s76, v166
	v_med3_i32 v16, v16, 0, s75
	v_med3_i32 v24, v24, 0, s75
	v_lshl_add_u32 v20, v16, 9, v158
	v_lshl_add_u32 v28, v24, 9, v158
	global_load_dwordx4 v[16:19], v20, s[100:101]
	s_nop 0
	global_load_dwordx4 v[20:23], v20, s[100:101] offset:64
	s_nop 0
	global_load_dwordx4 v[24:27], v28, s[100:101]
	s_nop 0
	global_load_dwordx4 v[28:31], v28, s[100:101] offset:64
	ds_read_b64_tr_b16 v[98:99], v169 offset:2304
	ds_read_b64_tr_b16 v[96:97], v169
	ds_read_b64_tr_b16 v[100:101], v169 offset:32
	ds_read_b64_tr_b16 v[102:103], v169 offset:2336
	ds_read_b64_tr_b16 v[116:117], v169 offset:64
	ds_read_b64_tr_b16 v[118:119], v169 offset:2368
	ds_read_b64_tr_b16 v[134:135], v169 offset:96
	ds_read_b64_tr_b16 v[136:137], v169 offset:2400
	s_waitcnt vmcnt(15)
	ds_write_b128 v241, v[76:79] offset:4608
	s_waitcnt vmcnt(14)
	ds_write_b128 v242, v[84:87] offset:4608
	s_waitcnt vmcnt(13)
	ds_write_b128 v243, v[88:91] offset:4608
	s_waitcnt vmcnt(12)
	ds_write_b128 v244, v[92:95] offset:4608
	v_mfma_f32_16x16x32_bf16 v[76:79], v[32:35], v[4:7], 0
	v_mfma_f32_16x16x32_bf16 v[32:35], v[32:35], v[12:15], 0
	v_mfma_f32_16x16x32_bf16 v[76:79], v[36:39], v[8:11], v[76:79]
	v_mfma_f32_16x16x32_bf16 v[84:87], v[48:51], v[4:7], 0
	v_mfma_f32_16x16x32_bf16 v[32:35], v[36:39], v[0:3], v[32:35]
	v_mfma_f32_16x16x32_bf16 v[36:39], v[48:51], v[12:15], 0
	v_add_u32_e32 v48, s22, v251
	v_min3_i32 v48, v48, s0, v245
	v_sub_u32_e32 v49, v154, v147
	v_sub_u32_e32 v146, v48, v147
	v_add_u32_e32 v48, s22, v144
	v_min3_i32 v48, v48, s0, v245
	v_add_u32_e32 v51, 1, v49
	v_sub_u32_e32 v145, v48, v148
	v_cmp_gt_u32_e64 s[0:1], v51, v146
	v_cmp_gt_u32_e32 vcc, v49, v146
	s_nop 0
	v_cndmask_b32_e64 v77, v77, v246, s[0:1]
	s_nop 0
	v_cndmask_b32_e32 v76, v76, v246, vcc
	v_mfma_f32_16x16x32_bf16 v[84:87], v[52:55], v[8:11], v[84:87]
	v_max_f32_e32 v48, v76, v77
	v_add_u32_e32 v51, 2, v49
	v_cmp_gt_u32_e64 s[22:23], v51, v146
	v_mfma_f32_16x16x32_bf16 v[36:39], v[52:55], v[0:3], v[36:39]
	v_add_u32_e32 v52, 3, v49
	v_cmp_gt_u32_e64 s[24:25], v52, v146
	v_cndmask_b32_e64 v78, v78, v246, s[22:23]
	v_sub_u32_e32 v50, v154, v148
	v_cndmask_b32_e64 v79, v79, v246, s[24:25]
	v_max3_f32 v48, v48, v78, v79
	v_add_u32_e32 v51, 16, v49
	v_add_u32_e32 v52, 17, v49
	v_cmp_gt_u32_e64 s[26:27], v51, v146
	v_cmp_gt_u32_e64 s[28:29], v52, v146
	v_cmp_gt_u32_e64 s[38:39], v50, v145
	v_cndmask_b32_e64 v84, v84, v246, s[26:27]
	v_cndmask_b32_e64 v85, v85, v246, s[28:29]
	v_max3_f32 v48, v48, v84, v85
	v_add_u32_e32 v51, 18, v49
	v_add_u32_e32 v49, 19, v49
	v_cmp_gt_u32_e64 s[30:31], v51, v146
	v_cmp_gt_u32_e64 s[34:35], v49, v146
	v_add_u32_e32 v52, 3, v50
	v_cndmask_b32_e64 v86, v86, v246, s[30:31]
	v_cndmask_b32_e64 v87, v87, v246, s[34:35]
	v_max3_f32 v48, v48, v86, v87
	v_add_u32_e32 v51, 1, v50
	v_cmp_gt_u32_e64 s[40:41], v51, v145
	v_cndmask_b32_e64 v32, v32, v246, s[38:39]
	s_nop 0
	v_cndmask_b32_e64 v33, v33, v246, s[40:41]
	v_max_f32_e32 v49, v32, v33
	v_add_u32_e32 v51, 2, v50
	v_cmp_gt_u32_e64 s[42:43], v51, v145
	v_cmp_gt_u32_e64 s[44:45], v52, v145
	s_nop 0
	v_cndmask_b32_e64 v34, v34, v246, s[42:43]
	v_cndmask_b32_e64 v35, v35, v246, s[44:45]
	v_max3_f32 v49, v49, v34, v35
	v_add_u32_e32 v51, 16, v50
	v_add_u32_e32 v52, 17, v50
	v_cmp_gt_u32_e64 s[46:47], v51, v145
	v_cmp_gt_u32_e64 s[48:49], v52, v145
	s_nop 0
	v_cndmask_b32_e64 v36, v36, v246, s[46:47]
	v_cndmask_b32_e64 v37, v37, v246, s[48:49]
	v_max3_f32 v49, v49, v36, v37
	v_add_u32_e32 v51, 18, v50
	v_add_u32_e32 v50, 19, v50
	v_cmp_gt_u32_e64 s[50:51], v51, v145
	v_cmp_gt_u32_e64 s[52:53], v50, v145
	s_nop 0
	v_cndmask_b32_e64 v38, v38, v246, s[50:51]
	v_cndmask_b32_e64 v39, v39, v246, s[52:53]
	v_max3_f32 v49, v49, v38, v39
	v_mov_b32_e32 v50, v48
	s_nop 1
	v_permlane32_swap_b32_e32 v50, v48
	v_max_f32_e32 v48, v48, v50
	v_mov_b32_e32 v50, v49
	s_nop 1
	v_permlane32_swap_b32_e32 v50, v49
	v_max_f32_e32 v49, v49, v50
	v_mov_b32_e32 v50, v48
	s_nop 1
	v_permlane16_swap_b32_e32 v50, v48
	v_max_f32_e32 v48, v48, v50
	v_mov_b32_e32 v50, v49
	s_nop 1
	v_permlane16_swap_b32_e32 v50, v49
	v_max_f32_e32 v129, s73, v48
	v_sub_f32_e32 v48, 0xf149f2ca, v129
	v_max_f32_e32 v49, v49, v50
	v_exp_f32_e32 v50, v48
	v_sub_f32_e32 v48, v76, v129
	v_exp_f32_e32 v48, v48
	v_sub_f32_e32 v52, v77, v129
	v_max_f32_e32 v131, s73, v49
	v_exp_f32_e32 v52, v52
	v_sub_f32_e32 v36, v36, v131
	v_sub_f32_e32 v53, v78, v129
	v_exp_f32_e32 v36, v36
	v_exp_f32_e32 v53, v53
	v_sub_f32_e32 v54, v79, v129
	v_cndmask_b32_e64 v51, v48, 0, vcc
	v_exp_f32_e32 v54, v54
	v_sub_f32_e32 v55, v84, v129
	v_exp_f32_e32 v55, v55
	v_sub_f32_e32 v76, v85, v129
	v_add_f32_e32 v48, v52, v51
	v_exp_f32_e32 v76, v76
	v_sub_f32_e32 v77, v86, v129
	v_cvt_pk_bf16_f32 v52, v51, v52
	v_cndmask_b32_e64 v51, v36, 0, s[46:47]
	v_sub_f32_e32 v36, v37, v131
	v_exp_f32_e32 v77, v77
	v_sub_f32_e32 v78, v87, v129
	v_exp_f32_e32 v36, v36
	v_add_f32_e32 v48, v53, v48
	v_exp_f32_e32 v78, v78
	v_add_f32_e32 v48, v54, v48
	v_sub_f32_e32 v32, v32, v131
	v_add_f32_e32 v48, v55, v48
	v_exp_f32_e32 v32, v32
	v_sub_f32_e32 v33, v33, v131
	v_add_f32_e32 v48, v76, v48
	v_cvt_pk_bf16_f32 v53, v53, v54
	v_cvt_pk_bf16_f32 v54, v55, v76
	v_exp_f32_e32 v33, v33
	v_sub_f32_e32 v34, v34, v131
	v_cndmask_b32_e64 v76, v36, 0, s[48:49]
	v_sub_f32_e32 v36, v38, v131
	v_add_f32_e32 v48, v77, v48
	v_exp_f32_e32 v34, v34
	v_sub_f32_e32 v35, v35, v131
	v_exp_f32_e32 v36, v36
	v_add_f32_e32 v130, v78, v48
	v_exp_f32_e32 v35, v35
	v_mul_f32_e32 v48, 0, v50
	v_fmac_f32_e32 v130, 0, v50
	v_cndmask_b32_e64 v50, v32, 0, s[38:39]
	v_cvt_pk_bf16_f32 v55, v77, v78
	v_add_f32_e32 v32, v33, v50
	v_cndmask_b32_e64 v77, v36, 0, s[50:51]
	v_sub_f32_e32 v36, v39, v131
	v_sub_f32_e32 v49, 0xf149f2ca, v131
	v_add_f32_e32 v32, v34, v32
	v_exp_f32_e32 v36, v36
	v_exp_f32_e32 v49, v49
	v_add_f32_e32 v32, v35, v32
	v_add_f32_e32 v32, v51, v32
	v_add_f32_e32 v32, v76, v32
	v_add_f32_e32 v32, v77, v32
	v_cndmask_b32_e64 v39, v36, 0, s[52:53]
	v_add_f32_e32 v132, v39, v32
	v_mul_f32_e32 v32, 0, v49
	v_fmac_f32_e32 v132, 0, v49
	v_cvt_pk_bf16_f32 v36, v50, v33
	v_cvt_pk_bf16_f32 v37, v34, v35
	v_cvt_pk_bf16_f32 v38, v51, v76
	v_cvt_pk_bf16_f32 v39, v77, v39
	v_mov_b32_e32 v49, v48
	v_mov_b32_e32 v50, v48
	v_mov_b32_e32 v51, v48
	v_mov_b32_e32 v33, v32
	v_mov_b32_e32 v34, v32
	v_mov_b32_e32 v35, v32
	s_waitcnt lgkmcnt(6)
	v_mfma_f32_16x16x32_bf16 v[112:115], v[116:119], v[52:55], v[48:51]
	v_mfma_f32_16x16x32_bf16 v[124:127], v[96:99], v[36:39], v[32:35]
	v_mfma_f32_16x16x32_bf16 v[108:111], v[100:103], v[36:39], v[32:35]
	v_mfma_f32_16x16x32_bf16 v[116:119], v[116:119], v[36:39], v[32:35]
	s_waitcnt lgkmcnt(4)
	v_mfma_f32_16x16x32_bf16 v[88:91], v[134:137], v[36:39], v[32:35]
	s_nop 2
	v_add_u32_e32 v32, 32, v155
	v_add_u32_e32 v32, s76, v32
	v_mfma_f32_16x16x32_bf16 v[120:123], v[96:99], v[52:55], v[48:51]
	s_nop 0
	v_med3_i32 v32, v32, 0, s75
	v_lshl_add_u32 v32, v32, 9, v152
	global_load_dwordx4 v[76:79], v32, s[98:99]
	v_add_u32_e32 v32, 32, v172
	v_add_u32_e32 v32, s76, v32
	v_mfma_f32_16x16x32_bf16 v[104:107], v[100:103], v[52:55], v[48:51]
	s_nop 0
	v_med3_i32 v32, v32, 0, s75
	v_lshl_add_u32 v32, v32, 9, v152
	global_load_dwordx4 v[84:87], v32, s[98:99]
	v_add_u32_e32 v32, 32, v173
	v_add_u32_e32 v32, s76, v32
	v_mfma_f32_16x16x32_bf16 v[96:99], v[134:137], v[52:55], v[48:51]
	s_nop 0
	v_med3_i32 v32, v32, 0, s75
	v_lshl_add_u32 v32, v32, 9, v152
	global_load_dwordx4 v[92:95], v32, s[98:99]
	v_add_u32_e32 v32, 32, v182
	v_add_u32_e32 v32, s76, v32
	v_or_b32_e32 v48, 48, v166
	v_add_u32_e32 v48, s76, v48
	v_med3_i32 v32, v32, 0, s75
	v_lshl_add_u32 v32, v32, 9, v152
	global_load_dwordx4 v[100:103], v32, s[98:99]
	v_add_u32_e32 v32, s76, v128
	s_nop 0
	v_med3_i32 v32, v32, 0, s75
	v_med3_i32 v48, v48, 0, s75
	v_lshl_add_u32 v36, v32, 9, v158
	v_lshl_add_u32 v52, v48, 9, v158
	global_load_dwordx4 v[32:35], v36, s[100:101]
	s_nop 0
	global_load_dwordx4 v[36:39], v36, s[100:101] offset:64
	s_nop 0
	global_load_dwordx4 v[48:51], v52, s[100:101]
	s_nop 0
	global_load_dwordx4 v[52:55], v52, s[100:101] offset:64
	ds_read_b64_tr_b16 v[136:137], v169 offset:6912
	ds_read_b64_tr_b16 v[134:135], v169 offset:4608
	ds_read_b64_tr_b16 v[138:139], v169 offset:4640
	ds_read_b64_tr_b16 v[140:141], v169 offset:6944
	ds_read_b64_tr_b16 v[176:177], v169 offset:4672
	ds_read_b64_tr_b16 v[178:179], v169 offset:6976
	ds_read_b64_tr_b16 v[188:189], v169 offset:4704
	ds_read_b64_tr_b16 v[190:191], v169 offset:7008
	s_waitcnt vmcnt(15)
	ds_write_b128 v241, v[64:67]
	s_waitcnt vmcnt(14)
	ds_write_b128 v242, v[68:71]
	s_waitcnt vmcnt(13)
	ds_write_b128 v243, v[72:75]
	s_waitcnt vmcnt(12)
	ds_write_b128 v244, v[80:83]
	v_mfma_f32_16x16x32_bf16 v[64:67], v[40:43], v[4:7], 0
	v_mfma_f32_16x16x32_bf16 v[40:43], v[40:43], v[12:15], 0
	v_mfma_f32_16x16x32_bf16 v[64:67], v[44:47], v[8:11], v[64:67]
	v_mfma_f32_16x16x32_bf16 v[68:71], v[56:59], v[4:7], 0
	v_mfma_f32_16x16x32_bf16 v[40:43], v[44:47], v[0:3], v[40:43]
	v_mfma_f32_16x16x32_bf16 v[44:47], v[56:59], v[12:15], 0
	v_sub_u32_e32 v56, v187, v147
	v_add_u32_e32 v59, 1, v56
	s_nop 2
	v_cmp_gt_u32_e64 s[0:1], v59, v146
	v_cmp_gt_u32_e32 vcc, v56, v146
	s_nop 0
	v_cndmask_b32_e64 v65, v65, v246, s[0:1]
	s_nop 0
	v_cndmask_b32_e32 v64, v64, v246, vcc
	v_mfma_f32_16x16x32_bf16 v[68:71], v[60:63], v[8:11], v[68:71]
	v_max_f32_e32 v58, v64, v65
	v_add_u32_e32 v59, 2, v56
	v_cmp_gt_u32_e64 s[22:23], v59, v146
	v_mfma_f32_16x16x32_bf16 v[44:47], v[60:63], v[0:3], v[44:47]
	v_add_u32_e32 v60, 3, v56
	v_cmp_gt_u32_e64 s[24:25], v60, v146
	v_cndmask_b32_e64 v66, v66, v246, s[22:23]
	v_sub_u32_e32 v57, v187, v148
	v_cndmask_b32_e64 v67, v67, v246, s[24:25]
	v_max3_f32 v58, v58, v66, v67
	v_add_u32_e32 v59, 16, v56
	v_add_u32_e32 v60, 17, v56
	v_cmp_gt_u32_e64 s[26:27], v59, v146
	v_cmp_gt_u32_e64 s[28:29], v60, v146
	v_cmp_gt_u32_e64 s[38:39], v57, v145
	v_cndmask_b32_e64 v68, v68, v246, s[26:27]
	v_cndmask_b32_e64 v69, v69, v246, s[28:29]
	v_max3_f32 v58, v58, v68, v69
	v_add_u32_e32 v59, 18, v56
	v_add_u32_e32 v56, 19, v56
	v_cmp_gt_u32_e64 s[30:31], v59, v146
	v_cmp_gt_u32_e64 s[34:35], v56, v146
	v_add_u32_e32 v60, 3, v57
	v_cndmask_b32_e64 v70, v70, v246, s[30:31]
	v_cndmask_b32_e64 v71, v71, v246, s[34:35]
	v_max3_f32 v56, v58, v70, v71
	v_add_u32_e32 v59, 1, v57
	v_cmp_gt_u32_e64 s[40:41], v59, v145
	v_cndmask_b32_e64 v40, v40, v246, s[38:39]
	s_nop 0
	v_cndmask_b32_e64 v41, v41, v246, s[40:41]
	v_max_f32_e32 v58, v40, v41
	v_add_u32_e32 v59, 2, v57
	v_cmp_gt_u32_e64 s[42:43], v59, v145
	v_cmp_gt_u32_e64 s[44:45], v60, v145
	s_nop 0
	v_cndmask_b32_e64 v42, v42, v246, s[42:43]
	v_cndmask_b32_e64 v43, v43, v246, s[44:45]
	v_max3_f32 v58, v58, v42, v43
	v_add_u32_e32 v59, 16, v57
	v_add_u32_e32 v60, 17, v57
	v_cmp_gt_u32_e64 s[46:47], v59, v145
	v_cmp_gt_u32_e64 s[48:49], v60, v145
	s_nop 0
	v_cndmask_b32_e64 v44, v44, v246, s[46:47]
	v_cndmask_b32_e64 v45, v45, v246, s[48:49]
	v_max3_f32 v58, v58, v44, v45
	v_add_u32_e32 v59, 18, v57
	v_add_u32_e32 v57, 19, v57
	v_cmp_gt_u32_e64 s[50:51], v59, v145
	v_cmp_gt_u32_e64 s[52:53], v57, v145
	s_nop 0
	v_cndmask_b32_e64 v46, v46, v246, s[50:51]
	v_cndmask_b32_e64 v47, v47, v246, s[52:53]
	v_max3_f32 v57, v58, v46, v47
	v_mov_b32_e32 v58, v56
	s_nop 1
	v_permlane32_swap_b32_e32 v58, v56
	v_max_f32_e32 v56, v56, v58
	v_mov_b32_e32 v58, v57
	s_nop 1
	v_permlane32_swap_b32_e32 v58, v57
	v_max_f32_e32 v57, v57, v58
	v_mov_b32_e32 v58, v56
	s_nop 1
	v_permlane16_swap_b32_e32 v58, v56
	v_max_f32_e32 v56, v56, v58
	v_mov_b32_e32 v58, v57
	v_mov_b32_e32 v61, v57
	v_max_f32_e32 v128, v129, v56
	s_nop 0
	v_permlane16_swap_b32_e32 v58, v61
	v_sub_f32_e32 v56, v129, v128
	v_exp_f32_e32 v60, v56
	v_sub_f32_e32 v56, v64, v128
	v_max_f32_e32 v62, v57, v58
	v_exp_f32_e32 v56, v56
	v_sub_f32_e32 v58, v65, v128
	v_exp_f32_e32 v58, v58
	v_sub_f32_e32 v59, v66, v128
	v_exp_f32_e32 v59, v59
	v_sub_f32_e32 v63, v67, v128
	v_exp_f32_e32 v63, v63
	v_sub_f32_e32 v64, v68, v128
	v_exp_f32_e32 v64, v64
	v_sub_f32_e32 v65, v69, v128
	v_exp_f32_e32 v65, v65
	v_sub_f32_e32 v66, v70, v128
	v_add_f32_e32 v57, v58, v56
	v_exp_f32_e32 v66, v66
	v_sub_f32_e32 v67, v71, v128
	v_add_f32_e32 v57, v59, v57
	v_exp_f32_e32 v67, v67
	v_add_f32_e32 v57, v63, v57
	v_add_f32_e32 v57, v64, v57
	v_add_f32_e32 v57, v65, v57
	v_add_f32_e32 v57, v66, v57
	v_add_f32_e32 v129, v67, v57
	v_fmac_f32_e32 v129, v130, v60
	v_max3_f32 v130, v131, v62, v61
	v_sub_f32_e32 v40, v40, v130
	v_exp_f32_e32 v40, v40
	v_sub_f32_e32 v41, v41, v130
	v_exp_f32_e32 v41, v41
	v_sub_f32_e32 v42, v42, v130
	v_exp_f32_e32 v42, v42
	v_sub_f32_e32 v43, v43, v130
	v_exp_f32_e32 v43, v43
	v_sub_f32_e32 v44, v44, v130
	v_sub_f32_e32 v61, v131, v130
	v_exp_f32_e32 v44, v44
	v_sub_f32_e32 v45, v45, v130
	v_exp_f32_e32 v62, v61
	v_exp_f32_e32 v45, v45
	v_sub_f32_e32 v46, v46, v130
	v_add_f32_e32 v61, v41, v40
	v_exp_f32_e32 v46, v46
	v_sub_f32_e32 v47, v47, v130
	v_add_f32_e32 v61, v42, v61
	v_exp_f32_e32 v47, v47
	v_add_f32_e32 v61, v43, v61
	v_add_f32_e32 v61, v44, v61
	v_add_f32_e32 v61, v45, v61
	v_add_f32_e32 v61, v46, v61
	v_cvt_pk_bf16_f32 v56, v56, v58
	v_cvt_pk_bf16_f32 v57, v59, v63
	v_cvt_pk_bf16_f32 v58, v64, v65
	v_cvt_pk_bf16_f32 v59, v66, v67
	v_add_f32_e32 v131, v47, v61
	v_cvt_pk_bf16_f32 v40, v40, v41
	v_cvt_pk_bf16_f32 v41, v42, v43
	v_cvt_pk_bf16_f32 v42, v44, v45
	v_cvt_pk_bf16_f32 v43, v46, v47
	v_pk_mul_f32 v[46:47], v[122:123], v[60:61] op_sel_hi:[1,0]
	v_pk_mul_f32 v[44:45], v[120:121], v[60:61] op_sel_hi:[1,0]
	v_fmac_f32_e32 v131, v132, v62
	s_waitcnt lgkmcnt(10)
	v_mfma_f32_16x16x32_bf16 v[64:67], v[134:137], v[56:59], v[44:47]
	s_nop 2
	v_mul_f32_e64 v46, v126, v62
	v_mul_f32_e64 v47, v127, v62
	v_pk_mul_f32 v[44:45], v[124:125], v[62:63] op_sel_hi:[1,0]
	s_nop 1
	v_mfma_f32_16x16x32_bf16 v[68:71], v[134:137], v[40:43], v[44:47]
	s_nop 2
	v_mul_f32_e64 v46, v106, v60
	v_mul_f32_e64 v47, v107, v60
	v_pk_mul_f32 v[44:45], v[104:105], v[60:61] op_sel_hi:[1,0]
	s_waitcnt lgkmcnt(8)
	s_nop 0
	v_mfma_f32_16x16x32_bf16 v[104:107], v[138:141], v[56:59], v[44:47]
	s_nop 2
	v_mul_f32_e64 v46, v110, v62
	v_mul_f32_e64 v47, v111, v62
	v_pk_mul_f32 v[44:45], v[108:109], v[62:63] op_sel_hi:[1,0]
	s_nop 1
	v_mfma_f32_16x16x32_bf16 v[108:111], v[138:141], v[40:43], v[44:47]
	s_nop 2
	v_mul_f32_e64 v46, v114, v60
	v_mul_f32_e64 v47, v115, v60
	v_pk_mul_f32 v[44:45], v[112:113], v[60:61] op_sel_hi:[1,0]
	s_waitcnt lgkmcnt(6)
	s_nop 0
	v_mfma_f32_16x16x32_bf16 v[112:115], v[176:179], v[56:59], v[44:47]
	s_nop 2
	v_mul_f32_e64 v46, v118, v62
	v_mul_f32_e64 v47, v119, v62
	v_pk_mul_f32 v[44:45], v[116:117], v[62:63] op_sel_hi:[1,0]
	s_nop 1
	v_mfma_f32_16x16x32_bf16 v[116:119], v[176:179], v[40:43], v[44:47]
	s_nop 2
	v_mul_f32_e64 v46, v98, v60
	v_mul_f32_e64 v47, v99, v60
	v_pk_mul_f32 v[44:45], v[96:97], v[60:61] op_sel_hi:[1,0]
	s_waitcnt lgkmcnt(4)
	s_nop 0
	v_mfma_f32_16x16x32_bf16 v[120:123], v[188:191], v[56:59], v[44:47]
	v_or_b32_e32 v56, 0x50, v166
	v_add_u32_e32 v56, s76, v56
	s_nop 0
	v_pk_mul_f32 v[46:47], v[90:91], v[62:63] op_sel_hi:[1,0]
	v_pk_mul_f32 v[44:45], v[88:89], v[62:63] op_sel_hi:[1,0]
	s_nop 1
	v_mfma_f32_16x16x32_bf16 v[124:127], v[188:191], v[40:43], v[44:47]
	v_add_u32_e32 v40, 64, v155
	v_add_u32_e32 v40, s76, v40
	v_med3_i32 v40, v40, 0, s75
	v_lshl_add_u32 v40, v40, 9, v152
	global_load_dwordx4 v[72:75], v40, s[98:99]
	v_add_u32_e32 v40, 64, v172
	v_add_u32_e32 v40, s76, v40
	v_med3_i32 v40, v40, 0, s75
	v_lshl_add_u32 v40, v40, 9, v152
	global_load_dwordx4 v[80:83], v40, s[98:99]
	v_add_u32_e32 v40, 64, v173
	v_add_u32_e32 v40, s76, v40
	v_med3_i32 v40, v40, 0, s75
	v_lshl_add_u32 v40, v40, 9, v152
	global_load_dwordx4 v[88:91], v40, s[98:99]
	v_add_u32_e32 v40, 64, v182
	v_add_u32_e32 v40, s76, v40
	v_med3_i32 v40, v40, 0, s75
	v_lshl_add_u32 v40, v40, 9, v152
	global_load_dwordx4 v[96:99], v40, s[98:99]
	v_or_b32_e32 v40, 64, v166
	v_add_u32_e32 v40, s76, v40
	v_med3_i32 v40, v40, 0, s75
	v_med3_i32 v56, v56, 0, s75
	v_lshl_add_u32 v44, v40, 9, v158
	v_lshl_add_u32 v60, v56, 9, v158
	global_load_dwordx4 v[40:43], v44, s[100:101]
	s_nop 0
	global_load_dwordx4 v[44:47], v44, s[100:101] offset:64
	s_nop 0
	global_load_dwordx4 v[56:59], v60, s[100:101]
	s_nop 0
	global_load_dwordx4 v[60:63], v60, s[100:101] offset:64
	ds_read_b64_tr_b16 v[136:137], v169 offset:2304
	ds_read_b64_tr_b16 v[134:135], v169
	ds_read_b64_tr_b16 v[138:139], v169 offset:32
	ds_read_b64_tr_b16 v[140:141], v169 offset:2336
	ds_read_b64_tr_b16 v[176:177], v169 offset:64
	ds_read_b64_tr_b16 v[178:179], v169 offset:2368
	ds_read_b64_tr_b16 v[188:189], v169 offset:96
	ds_read_b64_tr_b16 v[190:191], v169 offset:2400
	s_waitcnt vmcnt(15)
	ds_write_b128 v241, v[76:79] offset:4608
	s_waitcnt vmcnt(14)
	ds_write_b128 v242, v[84:87] offset:4608
	s_waitcnt vmcnt(13)
	ds_write_b128 v243, v[92:95] offset:4608
	s_waitcnt vmcnt(12)
	ds_write_b128 v244, v[100:103] offset:4608
	v_mfma_f32_16x16x32_bf16 v[76:79], v[16:19], v[4:7], 0
	v_mfma_f32_16x16x32_bf16 v[16:19], v[16:19], v[12:15], 0
	v_mfma_f32_16x16x32_bf16 v[76:79], v[20:23], v[8:11], v[76:79]
	v_mfma_f32_16x16x32_bf16 v[84:87], v[24:27], v[4:7], 0
	v_mfma_f32_16x16x32_bf16 v[16:19], v[20:23], v[0:3], v[16:19]
	v_mfma_f32_16x16x32_bf16 v[20:23], v[24:27], v[12:15], 0
	v_sub_u32_e32 v24, v192, v147
	v_add_u32_e32 v27, 1, v24
	s_nop 2
	v_cmp_gt_u32_e64 s[0:1], v27, v146
	v_cmp_gt_u32_e32 vcc, v24, v146
	s_nop 0
	v_cndmask_b32_e64 v77, v77, v246, s[0:1]
	s_nop 0
	v_cndmask_b32_e32 v76, v76, v246, vcc
	v_mfma_f32_16x16x32_bf16 v[84:87], v[28:31], v[8:11], v[84:87]
	v_max_f32_e32 v26, v76, v77
	v_add_u32_e32 v27, 2, v24
	v_cmp_gt_u32_e64 s[22:23], v27, v146
	v_mfma_f32_16x16x32_bf16 v[20:23], v[28:31], v[0:3], v[20:23]
	v_add_u32_e32 v28, 3, v24
	v_cmp_gt_u32_e64 s[24:25], v28, v146
	v_cndmask_b32_e64 v78, v78, v246, s[22:23]
	v_sub_u32_e32 v25, v192, v148
	v_cndmask_b32_e64 v79, v79, v246, s[24:25]
	v_max3_f32 v26, v26, v78, v79
	v_add_u32_e32 v27, 16, v24
	v_add_u32_e32 v28, 17, v24
	v_cmp_gt_u32_e64 s[26:27], v27, v146
	v_cmp_gt_u32_e64 s[28:29], v28, v146
	v_cmp_gt_u32_e64 s[38:39], v25, v145
	v_cndmask_b32_e64 v84, v84, v246, s[26:27]
	v_cndmask_b32_e64 v85, v85, v246, s[28:29]
	v_max3_f32 v26, v26, v84, v85
	v_add_u32_e32 v27, 18, v24
	v_add_u32_e32 v24, 19, v24
	v_cmp_gt_u32_e64 s[30:31], v27, v146
	v_cmp_gt_u32_e64 s[34:35], v24, v146
	v_add_u32_e32 v28, 3, v25
	v_cndmask_b32_e64 v86, v86, v246, s[30:31]
	v_cndmask_b32_e64 v87, v87, v246, s[34:35]
	v_max3_f32 v24, v26, v86, v87
	v_add_u32_e32 v27, 1, v25
	v_cmp_gt_u32_e64 s[40:41], v27, v145
	v_cndmask_b32_e64 v16, v16, v246, s[38:39]
	s_nop 0
	v_cndmask_b32_e64 v17, v17, v246, s[40:41]
	v_max_f32_e32 v26, v16, v17
	v_add_u32_e32 v27, 2, v25
	v_cmp_gt_u32_e64 s[42:43], v27, v145
	v_cmp_gt_u32_e64 s[44:45], v28, v145
	s_nop 0
	v_cndmask_b32_e64 v18, v18, v246, s[42:43]
	v_cndmask_b32_e64 v19, v19, v246, s[44:45]
	v_max3_f32 v26, v26, v18, v19
	v_add_u32_e32 v27, 16, v25
	v_add_u32_e32 v28, 17, v25
	v_cmp_gt_u32_e64 s[46:47], v27, v145
	v_cmp_gt_u32_e64 s[48:49], v28, v145
	s_nop 0
	v_cndmask_b32_e64 v20, v20, v246, s[46:47]
	v_cndmask_b32_e64 v21, v21, v246, s[48:49]
	v_max3_f32 v26, v26, v20, v21
	v_add_u32_e32 v27, 18, v25
	v_add_u32_e32 v25, 19, v25
	v_cmp_gt_u32_e64 s[50:51], v27, v145
	v_cmp_gt_u32_e64 s[52:53], v25, v145
	s_nop 0
	v_cndmask_b32_e64 v22, v22, v246, s[50:51]
	v_cndmask_b32_e64 v23, v23, v246, s[52:53]
	v_max3_f32 v25, v26, v22, v23
	v_mov_b32_e32 v26, v24
	s_nop 1
	v_permlane32_swap_b32_e32 v26, v24
	v_max_f32_e32 v24, v24, v26
	v_mov_b32_e32 v26, v25
	s_nop 1
	v_permlane32_swap_b32_e32 v26, v25
	v_max_f32_e32 v25, v25, v26
	v_mov_b32_e32 v26, v24
	s_nop 1
	v_permlane16_swap_b32_e32 v26, v24
	v_max_f32_e32 v24, v24, v26
	v_mov_b32_e32 v26, v25
	v_mov_b32_e32 v28, v25
	v_max_f32_e32 v132, v128, v24
	s_nop 0
	v_permlane16_swap_b32_e32 v26, v28
	v_sub_f32_e32 v24, v128, v132
	v_exp_f32_e32 v92, v24
	v_sub_f32_e32 v24, v76, v132
	v_max_f32_e32 v29, v25, v26
	v_exp_f32_e32 v24, v24
	v_sub_f32_e32 v26, v77, v132
	v_exp_f32_e32 v26, v26
	v_sub_f32_e32 v27, v78, v132
	v_exp_f32_e32 v27, v27
	v_sub_f32_e32 v30, v79, v132
	v_exp_f32_e32 v30, v30
	v_sub_f32_e32 v31, v84, v132
	v_exp_f32_e32 v31, v31
	v_sub_f32_e32 v76, v85, v132
	v_exp_f32_e32 v76, v76
	v_sub_f32_e32 v77, v86, v132
	v_add_f32_e32 v25, v26, v24
	v_exp_f32_e32 v77, v77
	v_sub_f32_e32 v78, v87, v132
	v_add_f32_e32 v25, v27, v25
	v_exp_f32_e32 v78, v78
	v_add_f32_e32 v25, v30, v25
	v_add_f32_e32 v25, v31, v25
	v_add_f32_e32 v25, v76, v25
	v_add_f32_e32 v25, v77, v25
	v_add_f32_e32 v128, v78, v25
	v_fmac_f32_e32 v128, v129, v92
	v_max3_f32 v129, v130, v29, v28
	v_sub_f32_e32 v16, v16, v129
	v_exp_f32_e32 v16, v16
	v_sub_f32_e32 v17, v17, v129
	v_exp_f32_e32 v17, v17
	v_sub_f32_e32 v18, v18, v129
	v_exp_f32_e32 v18, v18
	v_sub_f32_e32 v19, v19, v129
	v_exp_f32_e32 v19, v19
	v_sub_f32_e32 v20, v20, v129
	v_sub_f32_e32 v28, v130, v129
	v_exp_f32_e32 v20, v20
	v_sub_f32_e32 v21, v21, v129
	v_cvt_pk_bf16_f32 v24, v24, v26
	v_cvt_pk_bf16_f32 v26, v31, v76
	v_exp_f32_e32 v76, v28
	v_exp_f32_e32 v21, v21
	v_sub_f32_e32 v22, v22, v129
	v_add_f32_e32 v28, v17, v16
	v_exp_f32_e32 v22, v22
	v_sub_f32_e32 v23, v23, v129
	v_add_f32_e32 v28, v18, v28
	v_exp_f32_e32 v23, v23
	v_add_f32_e32 v28, v19, v28
	v_add_f32_e32 v28, v20, v28
	v_add_f32_e32 v28, v21, v28
	v_add_f32_e32 v28, v22, v28
	v_cvt_pk_bf16_f32 v25, v27, v30
	v_cvt_pk_bf16_f32 v27, v77, v78
	v_add_f32_e32 v130, v23, v28
	v_cvt_pk_bf16_f32 v28, v16, v17
	v_cvt_pk_bf16_f32 v29, v18, v19
	v_pk_mul_f32 v[18:19], v[66:67], v[92:93] op_sel_hi:[1,0]
	v_pk_mul_f32 v[16:17], v[64:65], v[92:93] op_sel_hi:[1,0]
	v_pk_mul_f32 v[66:67], v[106:107], v[92:93] op_sel_hi:[1,0]
	v_pk_mul_f32 v[64:65], v[104:105], v[92:93] op_sel_hi:[1,0]
	v_cvt_pk_bf16_f32 v30, v20, v21
	v_cvt_pk_bf16_f32 v31, v22, v23
	s_waitcnt lgkmcnt(8)
	v_mfma_f32_16x16x32_bf16 v[104:107], v[138:141], v[24:27], v[64:67]
	v_fmac_f32_e32 v130, v131, v76
	v_pk_mul_f32 v[22:23], v[70:71], v[76:77] op_sel_hi:[1,0]
	v_pk_mul_f32 v[20:21], v[68:69], v[76:77] op_sel_hi:[1,0]
	v_pk_mul_f32 v[66:67], v[110:111], v[76:77] op_sel_hi:[1,0]
	v_pk_mul_f32 v[64:65], v[108:109], v[76:77] op_sel_hi:[1,0]
	v_mfma_f32_16x16x32_bf16 v[16:19], v[134:137], v[24:27], v[16:19]
	s_nop 0
	v_mfma_f32_16x16x32_bf16 v[108:111], v[138:141], v[28:31], v[64:67]
	s_nop 2
	v_mul_f32_e64 v66, v114, v92
	v_mul_f32_e64 v67, v115, v92
	v_pk_mul_f32 v[64:65], v[112:113], v[92:93] op_sel_hi:[1,0]
	v_mfma_f32_16x16x32_bf16 v[20:23], v[134:137], v[28:31], v[20:23]
	s_waitcnt lgkmcnt(6)
	v_mfma_f32_16x16x32_bf16 v[112:115], v[176:179], v[24:27], v[64:67]
	s_nop 2
	v_mul_f32_e64 v66, v118, v76
	v_mul_f32_e64 v67, v119, v76
	v_pk_mul_f32 v[64:65], v[116:117], v[76:77] op_sel_hi:[1,0]
	s_nop 1
	v_mfma_f32_16x16x32_bf16 v[116:119], v[176:179], v[28:31], v[64:67]
	s_nop 2
	v_mul_f32_e64 v66, v122, v92
	v_mul_f32_e64 v67, v123, v92
	v_pk_mul_f32 v[64:65], v[120:121], v[92:93] op_sel_hi:[1,0]
	s_waitcnt lgkmcnt(4)
	s_nop 0
	v_mfma_f32_16x16x32_bf16 v[120:123], v[188:191], v[24:27], v[64:67]
	v_mul_f32_e64 v26, v126, v76
	v_mul_f32_e64 v27, v127, v76
	v_pk_mul_f32 v[24:25], v[124:125], v[76:77] op_sel_hi:[1,0]
	v_or_b32_e32 v64, 0x70, v166
	s_nop 0
	v_mfma_f32_16x16x32_bf16 v[124:127], v[188:191], v[28:31], v[24:27]
	v_add_u32_e32 v64, s76, v64
	s_nop 0
	s_nop 0
	v_add_u32_e32 v24, s76, v196
	v_med3_i32 v24, v24, 0, s75
	v_lshl_add_u32 v24, v24, 9, v152
	global_load_dwordx4 v[76:79], v24, s[98:99]
	v_add_u32_e32 v24, s76, v168
	v_med3_i32 v24, v24, 0, s75
	v_lshl_add_u32 v24, v24, 9, v152
	global_load_dwordx4 v[84:87], v24, s[98:99]
	v_add_u32_e32 v24, s76, v193
	v_med3_i32 v24, v24, 0, s75
	v_lshl_add_u32 v24, v24, 9, v152
	global_load_dwordx4 v[92:95], v24, s[98:99]
	v_add_u32_e32 v24, s76, v194
	v_med3_i32 v24, v24, 0, s75
	v_lshl_add_u32 v24, v24, 9, v152
	global_load_dwordx4 v[100:103], v24, s[98:99]
	v_or_b32_e32 v24, 0x60, v166
	v_add_u32_e32 v24, s76, v24
	v_med3_i32 v24, v24, 0, s75
	v_med3_i32 v64, v64, 0, s75
	v_lshl_add_u32 v28, v24, 9, v158
	v_lshl_add_u32 v68, v64, 9, v158
	global_load_dwordx4 v[24:27], v28, s[100:101]
	s_nop 0
	global_load_dwordx4 v[28:31], v28, s[100:101] offset:64
	s_nop 0
	global_load_dwordx4 v[64:67], v68, s[100:101]
	s_nop 0
	global_load_dwordx4 v[68:71], v68, s[100:101] offset:64
	ds_read_b64_tr_b16 v[136:137], v169 offset:6912
	ds_read_b64_tr_b16 v[134:135], v169 offset:4608
	ds_read_b64_tr_b16 v[138:139], v169 offset:4640
	ds_read_b64_tr_b16 v[140:141], v169 offset:6944
	ds_read_b64_tr_b16 v[176:177], v169 offset:4672
	ds_read_b64_tr_b16 v[178:179], v169 offset:6976
	ds_read_b64_tr_b16 v[188:189], v169 offset:4704
	ds_read_b64_tr_b16 v[190:191], v169 offset:7008
	s_waitcnt vmcnt(15)
	ds_write_b128 v241, v[72:75]
	s_waitcnt vmcnt(14)
	ds_write_b128 v242, v[80:83]
	s_waitcnt vmcnt(13)
	ds_write_b128 v243, v[88:91]
	s_waitcnt vmcnt(12)
	ds_write_b128 v244, v[96:99]
	v_mfma_f32_16x16x32_bf16 v[72:75], v[32:35], v[4:7], 0
	v_mfma_f32_16x16x32_bf16 v[32:35], v[32:35], v[12:15], 0
	v_mfma_f32_16x16x32_bf16 v[72:75], v[36:39], v[8:11], v[72:75]
	v_mfma_f32_16x16x32_bf16 v[80:83], v[48:51], v[4:7], 0
	v_mfma_f32_16x16x32_bf16 v[32:35], v[36:39], v[0:3], v[32:35]
	v_mfma_f32_16x16x32_bf16 v[36:39], v[48:51], v[12:15], 0
	v_sub_u32_e32 v48, v197, v147
	v_add_u32_e32 v51, 1, v48
	s_nop 2
	v_cmp_gt_u32_e64 s[0:1], v51, v146
	v_cmp_gt_u32_e32 vcc, v48, v146
	s_nop 0
	v_cndmask_b32_e64 v73, v73, v246, s[0:1]
	s_nop 0
	v_cndmask_b32_e32 v72, v72, v246, vcc
	v_mfma_f32_16x16x32_bf16 v[80:83], v[52:55], v[8:11], v[80:83]
	v_max_f32_e32 v50, v72, v73
	v_add_u32_e32 v51, 2, v48
	v_cmp_gt_u32_e64 s[22:23], v51, v146
	v_mfma_f32_16x16x32_bf16 v[36:39], v[52:55], v[0:3], v[36:39]
	v_add_u32_e32 v52, 3, v48
	v_cmp_gt_u32_e64 s[24:25], v52, v146
	v_cndmask_b32_e64 v74, v74, v246, s[22:23]
	v_sub_u32_e32 v49, v197, v148
	v_cndmask_b32_e64 v75, v75, v246, s[24:25]
	v_max3_f32 v50, v50, v74, v75
	v_add_u32_e32 v51, 16, v48
	v_add_u32_e32 v52, 17, v48
	v_cmp_gt_u32_e64 s[26:27], v51, v146
	v_cmp_gt_u32_e64 s[28:29], v52, v146
	v_cmp_gt_u32_e64 s[38:39], v49, v145
	v_cndmask_b32_e64 v80, v80, v246, s[26:27]
	v_cndmask_b32_e64 v81, v81, v246, s[28:29]
	v_max3_f32 v50, v50, v80, v81
	v_add_u32_e32 v51, 18, v48
	v_add_u32_e32 v48, 19, v48
	v_cmp_gt_u32_e64 s[30:31], v51, v146
	v_cmp_gt_u32_e64 s[34:35], v48, v146
	v_add_u32_e32 v52, 3, v49
	v_cndmask_b32_e64 v82, v82, v246, s[30:31]
	v_cndmask_b32_e64 v83, v83, v246, s[34:35]
	v_max3_f32 v48, v50, v82, v83
	v_add_u32_e32 v51, 1, v49
	v_cmp_gt_u32_e64 s[40:41], v51, v145
	v_cndmask_b32_e64 v32, v32, v246, s[38:39]
	s_nop 0
	v_cndmask_b32_e64 v33, v33, v246, s[40:41]
	v_max_f32_e32 v50, v32, v33
	v_add_u32_e32 v51, 2, v49
	v_cmp_gt_u32_e64 s[42:43], v51, v145
	v_cmp_gt_u32_e64 s[44:45], v52, v145
	s_nop 0
	v_cndmask_b32_e64 v34, v34, v246, s[42:43]
	v_cndmask_b32_e64 v35, v35, v246, s[44:45]
	v_max3_f32 v50, v50, v34, v35
	v_add_u32_e32 v51, 16, v49
	v_add_u32_e32 v52, 17, v49
	v_cmp_gt_u32_e64 s[46:47], v51, v145
	v_cmp_gt_u32_e64 s[48:49], v52, v145
	s_nop 0
	v_cndmask_b32_e64 v36, v36, v246, s[46:47]
	v_cndmask_b32_e64 v37, v37, v246, s[48:49]
	v_max3_f32 v50, v50, v36, v37
	v_add_u32_e32 v51, 18, v49
	v_add_u32_e32 v49, 19, v49
	v_cmp_gt_u32_e64 s[50:51], v51, v145
	v_cmp_gt_u32_e64 s[52:53], v49, v145
	s_nop 0
	v_cndmask_b32_e64 v38, v38, v246, s[50:51]
	v_cndmask_b32_e64 v39, v39, v246, s[52:53]
	v_max3_f32 v49, v50, v38, v39
	v_mov_b32_e32 v50, v48
	s_nop 1
	v_permlane32_swap_b32_e32 v50, v48
	v_max_f32_e32 v48, v48, v50
	v_mov_b32_e32 v50, v49
	s_nop 1
	v_permlane32_swap_b32_e32 v50, v49
	v_max_f32_e32 v49, v49, v50
	v_mov_b32_e32 v50, v48
	s_nop 1
	v_permlane16_swap_b32_e32 v50, v48
	v_max_f32_e32 v48, v48, v50
	v_mov_b32_e32 v50, v49
	v_mov_b32_e32 v53, v49
	v_max_f32_e32 v131, v132, v48
	s_nop 0
	v_permlane16_swap_b32_e32 v50, v53
	v_sub_f32_e32 v48, v132, v131
	v_exp_f32_e32 v52, v48
	v_sub_f32_e32 v48, v72, v131
	v_max_f32_e32 v54, v49, v50
	v_exp_f32_e32 v48, v48
	v_sub_f32_e32 v50, v73, v131
	v_exp_f32_e32 v50, v50
	v_sub_f32_e32 v51, v74, v131
	v_exp_f32_e32 v51, v51
	v_sub_f32_e32 v55, v75, v131
	v_exp_f32_e32 v55, v55
	v_sub_f32_e32 v72, v80, v131
	v_exp_f32_e32 v72, v72
	v_sub_f32_e32 v73, v81, v131
	v_exp_f32_e32 v73, v73
	v_sub_f32_e32 v74, v82, v131
	v_add_f32_e32 v49, v50, v48
	v_exp_f32_e32 v74, v74
	v_sub_f32_e32 v75, v83, v131
	v_add_f32_e32 v49, v51, v49
	v_exp_f32_e32 v75, v75
	v_add_f32_e32 v49, v55, v49
	v_add_f32_e32 v49, v72, v49
	v_add_f32_e32 v49, v73, v49
	v_add_f32_e32 v49, v74, v49
	v_add_f32_e32 v132, v75, v49
	v_fmac_f32_e32 v132, v128, v52
	v_max3_f32 v128, v129, v54, v53
	v_sub_f32_e32 v32, v32, v128
	v_exp_f32_e32 v32, v32
	v_sub_f32_e32 v33, v33, v128
	v_exp_f32_e32 v33, v33
	v_sub_f32_e32 v34, v34, v128
	v_exp_f32_e32 v34, v34
	v_sub_f32_e32 v35, v35, v128
	v_exp_f32_e32 v35, v35
	v_sub_f32_e32 v36, v36, v128
	v_sub_f32_e32 v53, v129, v128
	v_exp_f32_e32 v36, v36
	v_sub_f32_e32 v37, v37, v128
	v_exp_f32_e32 v54, v53
	v_exp_f32_e32 v37, v37
	v_add_f32_e32 v53, v33, v32
	v_add_f32_e32 v53, v34, v53
	v_cvt_pk_bf16_f32 v49, v51, v55
	v_add_f32_e32 v53, v35, v53
	v_cndmask_b32_e64 v55, v36, 0, s[46:47]
	v_add_f32_e32 v36, v55, v53
	v_cndmask_b32_e64 v53, v37, 0, s[48:49]
	v_sub_f32_e32 v37, v38, v128
	v_exp_f32_e32 v37, v37
	v_cvt_pk_bf16_f32 v48, v48, v50
	v_cvt_pk_bf16_f32 v50, v72, v73
	v_add_f32_e32 v36, v53, v36
	v_cndmask_b32_e64 v72, v37, 0, s[50:51]
	v_sub_f32_e32 v37, v39, v128
	v_exp_f32_e32 v37, v37
	v_cvt_pk_bf16_f32 v51, v74, v75
	v_add_f32_e32 v36, v72, v36
	v_pk_mul_f32 v[18:19], v[18:19], v[52:53] op_sel_hi:[1,0]
	v_cndmask_b32_e64 v39, v37, 0, s[52:53]
	v_pk_mul_f32 v[16:17], v[16:17], v[52:53] op_sel_hi:[1,0]
	v_add_f32_e32 v129, v39, v36
	v_cvt_pk_bf16_f32 v36, v32, v33
	v_cvt_pk_bf16_f32 v37, v34, v35
	v_cvt_pk_bf16_f32 v38, v55, v53
	v_cvt_pk_bf16_f32 v39, v72, v39
	s_waitcnt lgkmcnt(10)
	v_mfma_f32_16x16x32_bf16 v[32:35], v[134:137], v[48:51], v[16:19]
	v_fmac_f32_e32 v129, v130, v54
	s_nop 1
	v_pk_mul_f32 v[18:19], v[22:23], v[54:55] op_sel_hi:[1,0]
	v_pk_mul_f32 v[16:17], v[20:21], v[54:55] op_sel_hi:[1,0]
	s_nop 1
	v_mfma_f32_16x16x32_bf16 v[96:99], v[134:137], v[36:39], v[16:19]
	s_nop 2
	v_mul_f32_e64 v18, v106, v52
	v_mul_f32_e64 v19, v107, v52
	v_pk_mul_f32 v[16:17], v[104:105], v[52:53] op_sel_hi:[1,0]
	s_waitcnt lgkmcnt(8)
	s_nop 0
	v_mfma_f32_16x16x32_bf16 v[104:107], v[138:141], v[48:51], v[16:19]
	s_nop 2
	v_mul_f32_e64 v18, v110, v54
	v_mul_f32_e64 v19, v111, v54
	v_pk_mul_f32 v[16:17], v[108:109], v[54:55] op_sel_hi:[1,0]
	s_nop 1
	v_mfma_f32_16x16x32_bf16 v[108:111], v[138:141], v[36:39], v[16:19]
	s_nop 2
	v_mul_f32_e64 v18, v114, v52
	v_mul_f32_e64 v19, v115, v52
	v_pk_mul_f32 v[16:17], v[112:113], v[52:53] op_sel_hi:[1,0]
	s_waitcnt lgkmcnt(6)
	s_nop 0
	v_mfma_f32_16x16x32_bf16 v[112:115], v[176:179], v[48:51], v[16:19]
	s_nop 2
	v_mul_f32_e64 v18, v118, v54
	v_mul_f32_e64 v19, v119, v54
	v_pk_mul_f32 v[16:17], v[116:117], v[54:55] op_sel_hi:[1,0]
	s_nop 1
	v_mfma_f32_16x16x32_bf16 v[116:119], v[176:179], v[36:39], v[16:19]
	s_nop 2
	v_mul_f32_e64 v18, v122, v52
	v_mul_f32_e64 v19, v123, v52
	v_pk_mul_f32 v[16:17], v[120:121], v[52:53] op_sel_hi:[1,0]
	s_waitcnt lgkmcnt(4)
	s_nop 0
	v_mfma_f32_16x16x32_bf16 v[120:123], v[188:191], v[48:51], v[16:19]
	v_or_b32_e32 v48, 0x90, v166
	v_add_u32_e32 v48, s76, v48
	s_nop 0
	v_pk_mul_f32 v[18:19], v[126:127], v[54:55] op_sel_hi:[1,0]
	v_pk_mul_f32 v[16:17], v[124:125], v[54:55] op_sel_hi:[1,0]
	s_nop 1
	v_mfma_f32_16x16x32_bf16 v[124:127], v[188:191], v[36:39], v[16:19]
	s_nop 2
	v_add_u32_e32 v16, 0x80, v149
	v_med3_i32 v16, v16, 0, s75
	v_lshl_add_u32 v16, v16, 9, v152
	global_load_dwordx4 v[36:39], v16, s[98:99]
	v_add_u32_e32 v16, 0x80, v150
	v_med3_i32 v16, v16, 0, s75
	v_lshl_add_u32 v16, v16, 9, v152
	global_load_dwordx4 v[72:75], v16, s[98:99]
	v_add_u32_e32 v16, 0x80, v151
	v_med3_i32 v16, v16, 0, s75
	v_lshl_add_u32 v16, v16, 9, v152
	global_load_dwordx4 v[80:83], v16, s[98:99]
	v_add_u32_e32 v16, 0x80, v252
	v_med3_i32 v16, v16, 0, s75
	v_lshl_add_u32 v16, v16, 9, v152
	global_load_dwordx4 v[88:91], v16, s[98:99]
	v_or_b32_e32 v16, 0x80, v166
	v_add_u32_e32 v16, s76, v16
	v_med3_i32 v16, v16, 0, s75
	v_med3_i32 v48, v48, 0, s75
	v_lshl_add_u32 v20, v16, 9, v158
	v_lshl_add_u32 v52, v48, 9, v158
	global_load_dwordx4 v[16:19], v20, s[100:101]
	s_nop 0
	global_load_dwordx4 v[20:23], v20, s[100:101] offset:64
	s_nop 0
	global_load_dwordx4 v[48:51], v52, s[100:101]
	s_nop 0
	global_load_dwordx4 v[52:55], v52, s[100:101] offset:64
	ds_read_b64_tr_b16 v[136:137], v169 offset:2304
	ds_read_b64_tr_b16 v[134:135], v169
	ds_read_b64_tr_b16 v[138:139], v169 offset:32
	ds_read_b64_tr_b16 v[140:141], v169 offset:2336
	ds_read_b64_tr_b16 v[188:189], v169 offset:64
	ds_read_b64_tr_b16 v[190:191], v169 offset:2368
	ds_read_b64_tr_b16 v[200:201], v169 offset:96
	ds_read_b64_tr_b16 v[202:203], v169 offset:2400
	s_waitcnt vmcnt(15)
	ds_write_b128 v241, v[76:79] offset:4608
	s_waitcnt vmcnt(14)
	ds_write_b128 v242, v[84:87] offset:4608
	s_waitcnt vmcnt(13)
	ds_write_b128 v243, v[92:95] offset:4608
	s_waitcnt vmcnt(12)
	ds_write_b128 v244, v[100:103] offset:4608
	v_mfma_f32_16x16x32_bf16 v[76:79], v[40:43], v[4:7], 0
	v_mfma_f32_16x16x32_bf16 v[40:43], v[40:43], v[12:15], 0
	v_mfma_f32_16x16x32_bf16 v[76:79], v[44:47], v[8:11], v[76:79]
	v_mfma_f32_16x16x32_bf16 v[84:87], v[56:59], v[4:7], 0
	v_mfma_f32_16x16x32_bf16 v[40:43], v[44:47], v[0:3], v[40:43]
	v_mfma_f32_16x16x32_bf16 v[44:47], v[56:59], v[12:15], 0
	v_sub_u32_e32 v56, v198, v147
	v_add_u32_e32 v59, 1, v56
	s_nop 2
	v_cmp_gt_u32_e64 s[0:1], v59, v146
	v_cmp_gt_u32_e32 vcc, v56, v146
	s_nop 0
	v_cndmask_b32_e64 v77, v77, v246, s[0:1]
	s_nop 0
	v_cndmask_b32_e32 v76, v76, v246, vcc
	v_mfma_f32_16x16x32_bf16 v[84:87], v[60:63], v[8:11], v[84:87]
	v_max_f32_e32 v58, v76, v77
	v_add_u32_e32 v59, 2, v56
	v_cmp_gt_u32_e64 s[22:23], v59, v146
	v_mfma_f32_16x16x32_bf16 v[44:47], v[60:63], v[0:3], v[44:47]
	v_add_u32_e32 v60, 3, v56
	v_cmp_gt_u32_e64 s[24:25], v60, v146
	v_cndmask_b32_e64 v78, v78, v246, s[22:23]
	v_sub_u32_e32 v57, v198, v148
	v_cndmask_b32_e64 v79, v79, v246, s[24:25]
	v_max3_f32 v58, v58, v78, v79
	v_add_u32_e32 v59, 16, v56
	v_add_u32_e32 v60, 17, v56
	v_cmp_gt_u32_e64 s[26:27], v59, v146
	v_cmp_gt_u32_e64 s[28:29], v60, v146
	v_cmp_gt_u32_e64 s[38:39], v57, v145
	v_cndmask_b32_e64 v84, v84, v246, s[26:27]
	v_cndmask_b32_e64 v85, v85, v246, s[28:29]
	v_max3_f32 v58, v58, v84, v85
	v_add_u32_e32 v59, 18, v56
	v_add_u32_e32 v56, 19, v56
	v_cmp_gt_u32_e64 s[30:31], v59, v146
	v_cmp_gt_u32_e64 s[34:35], v56, v146
	v_add_u32_e32 v60, 3, v57
	v_cndmask_b32_e64 v86, v86, v246, s[30:31]
	v_cndmask_b32_e64 v87, v87, v246, s[34:35]
	v_max3_f32 v56, v58, v86, v87
	v_add_u32_e32 v59, 1, v57
	v_cmp_gt_u32_e64 s[40:41], v59, v145
	v_cndmask_b32_e64 v40, v40, v246, s[38:39]
	s_nop 0
	v_cndmask_b32_e64 v41, v41, v246, s[40:41]
	v_max_f32_e32 v58, v40, v41
	v_add_u32_e32 v59, 2, v57
	v_cmp_gt_u32_e64 s[42:43], v59, v145
	v_cmp_gt_u32_e64 s[44:45], v60, v145
	s_nop 0
	v_cndmask_b32_e64 v42, v42, v246, s[42:43]
	v_cndmask_b32_e64 v43, v43, v246, s[44:45]
	v_max3_f32 v58, v58, v42, v43
	v_add_u32_e32 v59, 16, v57
	v_add_u32_e32 v60, 17, v57
	v_cmp_gt_u32_e64 s[46:47], v59, v145
	v_cmp_gt_u32_e64 s[48:49], v60, v145
	s_nop 0
	v_cndmask_b32_e64 v44, v44, v246, s[46:47]
	v_cndmask_b32_e64 v45, v45, v246, s[48:49]
	v_max3_f32 v58, v58, v44, v45
	v_add_u32_e32 v59, 18, v57
	v_add_u32_e32 v57, 19, v57
	v_cmp_gt_u32_e64 s[50:51], v59, v145
	v_cmp_gt_u32_e64 s[52:53], v57, v145
	s_nop 0
	v_cndmask_b32_e64 v46, v46, v246, s[50:51]
	v_cndmask_b32_e64 v47, v47, v246, s[52:53]
	v_max3_f32 v57, v58, v46, v47
	v_mov_b32_e32 v58, v56
	s_nop 1
	v_permlane32_swap_b32_e32 v58, v56
	v_max_f32_e32 v56, v56, v58
	v_mov_b32_e32 v58, v57
	s_nop 1
	v_permlane32_swap_b32_e32 v58, v57
	v_max_f32_e32 v57, v57, v58
	v_mov_b32_e32 v58, v56
	s_nop 1
	v_permlane16_swap_b32_e32 v58, v56
	v_max_f32_e32 v56, v56, v58
	v_mov_b32_e32 v58, v57
	s_nop 1
	v_permlane16_swap_b32_e32 v58, v57
	v_max_f32_e32 v175, v131, v56
	v_sub_f32_e32 v56, v131, v175
	v_max3_f32 v177, v128, v57, v58
	v_exp_f32_e32 v60, v56
	v_sub_f32_e32 v56, v76, v175
	v_sub_f32_e32 v40, v40, v177
	v_exp_f32_e32 v56, v56
	v_sub_f32_e32 v58, v77, v175
	v_exp_f32_e32 v40, v40
	v_sub_f32_e32 v41, v41, v177
	v_exp_f32_e32 v58, v58
	v_sub_f32_e32 v59, v78, v175
	v_exp_f32_e32 v41, v41
	v_sub_f32_e32 v42, v42, v177
	v_exp_f32_e32 v59, v59
	v_sub_f32_e32 v63, v79, v175
	v_exp_f32_e32 v42, v42
	v_sub_f32_e32 v43, v43, v177
	v_exp_f32_e32 v63, v63
	v_sub_f32_e32 v76, v84, v175
	v_exp_f32_e32 v43, v43
	v_sub_f32_e32 v44, v44, v177
	v_exp_f32_e32 v76, v76
	v_sub_f32_e32 v77, v85, v175
	v_sub_f32_e32 v61, v128, v177
	v_exp_f32_e32 v44, v44
	v_sub_f32_e32 v45, v45, v177
	v_exp_f32_e32 v77, v77
	v_sub_f32_e32 v78, v86, v175
	v_exp_f32_e32 v62, v61
	v_exp_f32_e32 v45, v45
	v_sub_f32_e32 v46, v46, v177
	v_add_f32_e32 v57, v58, v56
	v_exp_f32_e32 v78, v78
	v_sub_f32_e32 v79, v87, v175
	v_add_f32_e32 v61, v41, v40
	v_exp_f32_e32 v46, v46
	v_add_f32_e32 v57, v59, v57
	v_exp_f32_e32 v79, v79
	v_add_f32_e32 v61, v42, v61
	v_sub_f32_e32 v47, v47, v177
	v_add_f32_e32 v57, v63, v57
	v_add_f32_e32 v61, v43, v61
	v_exp_f32_e32 v47, v47
	v_add_f32_e32 v57, v76, v57
	v_add_f32_e32 v61, v44, v61
	v_add_f32_e32 v57, v77, v57
	v_add_f32_e32 v61, v45, v61
	v_add_f32_e32 v57, v78, v57
	v_add_f32_e32 v61, v46, v61
	v_add_f32_e32 v176, v79, v57
	v_cvt_pk_bf16_f32 v56, v56, v58
	v_cvt_pk_bf16_f32 v57, v59, v63
	v_cvt_pk_bf16_f32 v58, v76, v77
	v_cvt_pk_bf16_f32 v59, v78, v79
	v_pk_mul_f32 v[34:35], v[34:35], v[60:61] op_sel_hi:[1,0]
	v_pk_mul_f32 v[32:33], v[32:33], v[60:61] op_sel_hi:[1,0]
	v_add_f32_e32 v178, v47, v61
	v_cvt_pk_bf16_f32 v40, v40, v41
	v_cvt_pk_bf16_f32 v41, v42, v43
	v_cvt_pk_bf16_f32 v42, v44, v45
	v_cvt_pk_bf16_f32 v43, v46, v47
	s_waitcnt lgkmcnt(10)
	v_mfma_f32_16x16x32_bf16 v[44:47], v[134:137], v[56:59], v[32:35]
	v_fmac_f32_e32 v176, v132, v60
	v_fmac_f32_e32 v178, v129, v62
	s_nop 0
	v_pk_mul_f32 v[34:35], v[98:99], v[62:63] op_sel_hi:[1,0]
	v_pk_mul_f32 v[32:33], v[96:97], v[62:63] op_sel_hi:[1,0]
	s_nop 1
	v_mfma_f32_16x16x32_bf16 v[100:103], v[134:137], v[40:43], v[32:35]
	s_nop 2
	v_mul_f32_e64 v34, v106, v60
	v_mul_f32_e64 v35, v107, v60
	v_pk_mul_f32 v[32:33], v[104:105], v[60:61] op_sel_hi:[1,0]
	s_waitcnt lgkmcnt(8)
	s_nop 0
	v_mfma_f32_16x16x32_bf16 v[104:107], v[138:141], v[56:59], v[32:35]
	s_nop 2
	v_mul_f32_e64 v34, v110, v62
	v_mul_f32_e64 v35, v111, v62
	v_pk_mul_f32 v[32:33], v[108:109], v[62:63] op_sel_hi:[1,0]
	s_nop 1
	v_mfma_f32_16x16x32_bf16 v[108:111], v[138:141], v[40:43], v[32:35]
	s_nop 2
	v_mul_f32_e64 v34, v114, v60
	v_mul_f32_e64 v35, v115, v60
	v_pk_mul_f32 v[32:33], v[112:113], v[60:61] op_sel_hi:[1,0]
	s_waitcnt lgkmcnt(6)
	s_nop 0
	v_mfma_f32_16x16x32_bf16 v[112:115], v[188:191], v[56:59], v[32:35]
	s_nop 2
	v_mul_f32_e64 v34, v118, v62
	v_mul_f32_e64 v35, v119, v62
	v_pk_mul_f32 v[32:33], v[116:117], v[62:63] op_sel_hi:[1,0]
	s_nop 1
	v_mfma_f32_16x16x32_bf16 v[116:119], v[188:191], v[40:43], v[32:35]
	v_add_u32_e32 v188, s76, v207
	s_nop 1
	v_pk_mul_f32 v[34:35], v[122:123], v[60:61] op_sel_hi:[1,0]
	v_pk_mul_f32 v[32:33], v[120:121], v[60:61] op_sel_hi:[1,0]
	s_waitcnt lgkmcnt(4)
	s_nop 0
	v_mfma_f32_16x16x32_bf16 v[120:123], v[200:203], v[56:59], v[32:35]
	v_or_b32_e32 v56, 0xb0, v166
	v_add_u32_e32 v56, s76, v56
	s_nop 0
	v_pk_mul_f32 v[34:35], v[126:127], v[62:63] op_sel_hi:[1,0]
	v_pk_mul_f32 v[32:33], v[124:125], v[62:63] op_sel_hi:[1,0]
	s_nop 1
	v_mfma_f32_16x16x32_bf16 v[124:127], v[200:203], v[40:43], v[32:35]
	s_nop 2
	v_add_u32_e32 v32, 0xa0, v149
	v_med3_i32 v32, v32, 0, s75
	v_lshl_add_u32 v32, v32, 9, v152
	global_load_dwordx4 v[76:79], v32, s[98:99]
	v_add_u32_e32 v32, 0xa0, v150
	v_med3_i32 v32, v32, 0, s75
	v_lshl_add_u32 v32, v32, 9, v152
	global_load_dwordx4 v[84:87], v32, s[98:99]
	v_add_u32_e32 v32, 0xa0, v151
	v_med3_i32 v32, v32, 0, s75
	v_lshl_add_u32 v32, v32, 9, v152
	global_load_dwordx4 v[92:95], v32, s[98:99]
	v_add_u32_e32 v32, 0xa0, v252
	v_med3_i32 v32, v32, 0, s75
	v_lshl_add_u32 v32, v32, 9, v152
	global_load_dwordx4 v[96:99], v32, s[98:99]
	v_or_b32_e32 v32, 0xa0, v166
	v_add_u32_e32 v32, s76, v32
	v_med3_i32 v32, v32, 0, s75
	v_med3_i32 v56, v56, 0, s75
	v_lshl_add_u32 v40, v32, 9, v158
	v_lshl_add_u32 v60, v56, 9, v158
	global_load_dwordx4 v[32:35], v40, s[100:101]
	s_nop 0
	global_load_dwordx4 v[40:43], v40, s[100:101] offset:64
	s_nop 0
	global_load_dwordx4 v[56:59], v60, s[100:101]
	s_nop 0
	global_load_dwordx4 v[60:63], v60, s[100:101] offset:64
	ds_read_b64_tr_b16 v[142:143], v169 offset:6912
	ds_read_b64_tr_b16 v[140:141], v169 offset:4608
	ds_read_b64_tr_b16 v[136:137], v169 offset:4640
	ds_read_b64_tr_b16 v[138:139], v169 offset:6944
	ds_read_b64_tr_b16 v[132:133], v169 offset:4672
	ds_read_b64_tr_b16 v[134:135], v169 offset:6976
	ds_read_b64_tr_b16 v[128:129], v169 offset:4704
	ds_read_b64_tr_b16 v[130:131], v169 offset:7008
	s_waitcnt vmcnt(15)
	ds_write_b128 v241, v[36:39]
	s_waitcnt vmcnt(14)
	ds_write_b128 v242, v[72:75]
	s_waitcnt vmcnt(13)
	ds_write_b128 v243, v[80:83]
	s_waitcnt vmcnt(12)
	ds_write_b128 v244, v[88:91]
	v_mfma_f32_16x16x32_bf16 v[36:39], v[24:27], v[4:7], 0
	v_mfma_f32_16x16x32_bf16 v[24:27], v[24:27], v[12:15], 0
	v_mfma_f32_16x16x32_bf16 v[36:39], v[28:31], v[8:11], v[36:39]
	v_mfma_f32_16x16x32_bf16 v[72:75], v[64:67], v[4:7], 0
	v_mfma_f32_16x16x32_bf16 v[24:27], v[28:31], v[0:3], v[24:27]
	v_mfma_f32_16x16x32_bf16 v[28:31], v[64:67], v[12:15], 0
	v_sub_u32_e32 v64, v199, v147
	v_add_u32_e32 v67, 1, v64
	s_nop 2
	v_cmp_gt_u32_e64 s[0:1], v67, v146
	v_cmp_gt_u32_e32 vcc, v64, v146
	s_nop 0
	v_cndmask_b32_e64 v37, v37, v246, s[0:1]
	s_nop 0
	v_cndmask_b32_e32 v36, v36, v246, vcc
	v_mfma_f32_16x16x32_bf16 v[72:75], v[68:71], v[8:11], v[72:75]
	v_max_f32_e32 v66, v36, v37
	v_add_u32_e32 v67, 2, v64
	v_cmp_gt_u32_e64 s[22:23], v67, v146
	v_mfma_f32_16x16x32_bf16 v[28:31], v[68:71], v[0:3], v[28:31]
	v_add_u32_e32 v68, 3, v64
	v_cmp_gt_u32_e64 s[24:25], v68, v146
	v_cndmask_b32_e64 v38, v38, v246, s[22:23]
	v_sub_u32_e32 v65, v199, v148
	v_cndmask_b32_e64 v39, v39, v246, s[24:25]
	v_max3_f32 v66, v66, v38, v39
	v_add_u32_e32 v67, 16, v64
	v_add_u32_e32 v68, 17, v64
	v_cmp_gt_u32_e64 s[26:27], v67, v146
	v_cmp_gt_u32_e64 s[28:29], v68, v146
	v_cmp_gt_u32_e64 s[38:39], v65, v145
	v_cndmask_b32_e64 v72, v72, v246, s[26:27]
	v_cndmask_b32_e64 v73, v73, v246, s[28:29]
	v_max3_f32 v66, v66, v72, v73
	v_add_u32_e32 v67, 18, v64
	v_add_u32_e32 v64, 19, v64
	v_cmp_gt_u32_e64 s[30:31], v67, v146
	v_cmp_gt_u32_e64 s[34:35], v64, v146
	v_add_u32_e32 v68, 3, v65
	v_cndmask_b32_e64 v74, v74, v246, s[30:31]
	v_cndmask_b32_e64 v75, v75, v246, s[34:35]
	v_max3_f32 v64, v66, v74, v75
	v_add_u32_e32 v67, 1, v65
	v_cmp_gt_u32_e64 s[40:41], v67, v145
	v_cndmask_b32_e64 v24, v24, v246, s[38:39]
	s_nop 0
	v_cndmask_b32_e64 v25, v25, v246, s[40:41]
	v_max_f32_e32 v66, v24, v25
	v_add_u32_e32 v67, 2, v65
	v_cmp_gt_u32_e64 s[42:43], v67, v145
	v_cmp_gt_u32_e64 s[44:45], v68, v145
	s_nop 0
	v_cndmask_b32_e64 v26, v26, v246, s[42:43]
	v_cndmask_b32_e64 v27, v27, v246, s[44:45]
	v_max3_f32 v66, v66, v26, v27
	v_add_u32_e32 v67, 16, v65
	v_add_u32_e32 v68, 17, v65
	v_cmp_gt_u32_e64 s[46:47], v67, v145
	v_cmp_gt_u32_e64 s[48:49], v68, v145
	s_nop 0
	v_cndmask_b32_e64 v28, v28, v246, s[46:47]
	v_cndmask_b32_e64 v29, v29, v246, s[48:49]
	v_max3_f32 v66, v66, v28, v29
	v_add_u32_e32 v67, 18, v65
	v_add_u32_e32 v65, 19, v65
	v_cmp_gt_u32_e64 s[50:51], v67, v145
	v_cmp_gt_u32_e64 s[52:53], v65, v145
	s_nop 0
	v_cndmask_b32_e64 v30, v30, v246, s[50:51]
	v_cndmask_b32_e64 v31, v31, v246, s[52:53]
	v_max3_f32 v65, v66, v30, v31
	v_mov_b32_e32 v66, v64
	s_nop 1
	v_permlane32_swap_b32_e32 v66, v64
	v_max_f32_e32 v64, v64, v66
	v_mov_b32_e32 v66, v65
	s_nop 1
	v_permlane32_swap_b32_e32 v66, v65
	v_max_f32_e32 v65, v65, v66
	v_mov_b32_e32 v66, v64
	s_nop 1
	v_permlane16_swap_b32_e32 v66, v64
	v_max3_f32 v179, v175, v64, v66
	v_sub_f32_e32 v36, v36, v179
	v_exp_f32_e32 v36, v36
	v_sub_f32_e32 v37, v37, v179
	v_mov_b32_e32 v66, v65
	v_exp_f32_e32 v37, v37
	v_sub_f32_e32 v38, v38, v179
	v_permlane16_swap_b32_e32 v66, v65
	v_exp_f32_e32 v38, v38
	v_sub_f32_e32 v39, v39, v179
	v_exp_f32_e32 v39, v39
	v_sub_f32_e32 v67, v72, v179
	v_max_f32_e32 v65, v65, v66
	v_exp_f32_e32 v67, v67
	v_sub_f32_e32 v69, v73, v179
	v_exp_f32_e32 v69, v69
	v_sub_f32_e32 v70, v74, v179
	v_max_f32_e32 v181, v177, v65
	v_add_f32_e32 v66, v37, v36
	v_exp_f32_e32 v70, v70
	v_sub_f32_e32 v71, v75, v179
	v_sub_f32_e32 v24, v24, v181
	v_add_f32_e32 v66, v38, v66
	v_exp_f32_e32 v71, v71
	v_exp_f32_e32 v24, v24
	v_sub_f32_e32 v25, v25, v181
	v_add_f32_e32 v66, v39, v66
	v_exp_f32_e32 v25, v25
	v_sub_f32_e32 v26, v26, v181
	v_add_f32_e32 v66, v67, v66
	v_exp_f32_e32 v26, v26
	v_sub_f32_e32 v27, v27, v181
	v_add_f32_e32 v66, v69, v66
	v_exp_f32_e32 v27, v27
	v_sub_f32_e32 v28, v28, v181
	v_add_f32_e32 v66, v70, v66
	v_sub_f32_e32 v65, v177, v181
	v_exp_f32_e32 v28, v28
	v_sub_f32_e32 v29, v29, v181
	v_add_f32_e32 v180, v71, v66
	v_exp_f32_e32 v66, v65
	v_exp_f32_e32 v29, v29
	v_sub_f32_e32 v30, v30, v181
	v_add_f32_e32 v65, v25, v24
	v_exp_f32_e32 v30, v30
	v_sub_f32_e32 v31, v31, v181
	v_sub_f32_e32 v64, v175, v179
	v_add_f32_e32 v65, v26, v65
	v_exp_f32_e32 v31, v31
	v_exp_f32_e32 v64, v64
	v_add_f32_e32 v65, v27, v65
	v_add_f32_e32 v65, v28, v65
	v_add_f32_e32 v65, v29, v65
	v_add_f32_e32 v65, v30, v65
	v_cvt_pk_bf16_f32 v36, v36, v37
	v_cvt_pk_bf16_f32 v37, v38, v39
	v_cvt_pk_bf16_f32 v38, v67, v69
	v_cvt_pk_bf16_f32 v39, v70, v71
	v_add_f32_e32 v183, v31, v65
	v_cvt_pk_bf16_f32 v24, v24, v25
	v_cvt_pk_bf16_f32 v25, v26, v27
	v_cvt_pk_bf16_f32 v26, v28, v29
	v_cvt_pk_bf16_f32 v27, v30, v31
	v_pk_mul_f32 v[30:31], v[46:47], v[64:65] op_sel_hi:[1,0]
	v_pk_mul_f32 v[28:29], v[44:45], v[64:65] op_sel_hi:[1,0]
	v_fmac_f32_e32 v180, v176, v64
	v_fmac_f32_e32 v183, v178, v66
	s_waitcnt lgkmcnt(10)
	v_mfma_f32_16x16x32_bf16 v[68:71], v[140:143], v[36:39], v[28:31]
	s_nop 2
	v_mul_f32_e64 v30, v102, v66
	v_mul_f32_e64 v31, v103, v66
	v_pk_mul_f32 v[28:29], v[100:101], v[66:67] op_sel_hi:[1,0]
	s_nop 1
	v_mfma_f32_16x16x32_bf16 v[72:75], v[140:143], v[24:27], v[28:31]
	s_nop 2
	v_mul_f32_e64 v30, v106, v64
	v_mul_f32_e64 v31, v107, v64
	v_pk_mul_f32 v[28:29], v[104:105], v[64:65] op_sel_hi:[1,0]
	s_waitcnt lgkmcnt(8)
	s_nop 0
	v_mfma_f32_16x16x32_bf16 v[80:83], v[136:139], v[36:39], v[28:31]
	s_nop 2
	v_mul_f32_e64 v30, v110, v66
	v_mul_f32_e64 v31, v111, v66
	v_pk_mul_f32 v[28:29], v[108:109], v[66:67] op_sel_hi:[1,0]
	s_nop 1
	v_mfma_f32_16x16x32_bf16 v[108:111], v[136:139], v[24:27], v[28:31]
	s_nop 2
	v_mul_f32_e64 v30, v114, v64
	v_mul_f32_e64 v31, v115, v64
	v_pk_mul_f32 v[28:29], v[112:113], v[64:65] op_sel_hi:[1,0]
	s_waitcnt lgkmcnt(6)
	s_nop 0
	v_mfma_f32_16x16x32_bf16 v[112:115], v[132:135], v[36:39], v[28:31]
	s_nop 2
	v_mul_f32_e64 v30, v118, v66
	v_mul_f32_e64 v31, v119, v66
	v_pk_mul_f32 v[28:29], v[116:117], v[66:67] op_sel_hi:[1,0]
	s_nop 1
	v_mfma_f32_16x16x32_bf16 v[116:119], v[132:135], v[24:27], v[28:31]
	s_nop 2
	v_mul_f32_e64 v30, v122, v64
	v_mul_f32_e64 v31, v123, v64
	v_pk_mul_f32 v[28:29], v[120:121], v[64:65] op_sel_hi:[1,0]
	s_waitcnt lgkmcnt(4)
	s_nop 0
	v_mfma_f32_16x16x32_bf16 v[120:123], v[128:131], v[36:39], v[28:31]
	s_nop 2
	v_mul_f32_e64 v30, v126, v66
	v_mul_f32_e64 v31, v127, v66
	v_pk_mul_f32 v[28:29], v[124:125], v[66:67] op_sel_hi:[1,0]
	s_nop 1
	v_mfma_f32_16x16x32_bf16 v[124:127], v[128:131], v[24:27], v[28:31]
	v_add_u32_e32 v24, 0xc0, v149
	v_med3_i32 v24, v24, 0, s75
	v_lshl_add_u32 v24, v24, 9, v152
	global_load_dwordx4 v[64:67], v24, s[98:99]
	v_add_u32_e32 v24, 0xc0, v150
	v_med3_i32 v24, v24, 0, s75
	v_lshl_add_u32 v24, v24, 9, v152
	global_load_dwordx4 v[88:91], v24, s[98:99]
	v_add_u32_e32 v24, 0xc0, v151
	v_med3_i32 v24, v24, 0, s75
	v_lshl_add_u32 v24, v24, 9, v152
	global_load_dwordx4 v[100:103], v24, s[98:99]
	v_add_u32_e32 v24, 0xc0, v252
	v_med3_i32 v24, v24, 0, s75
	v_lshl_add_u32 v24, v24, 9, v152
	global_load_dwordx4 v[104:107], v24, s[98:99]
	v_or_b32_e32 v24, 0xc0, v166
	v_add_u32_e32 v24, s76, v24
	v_med3_i32 v24, v24, 0, s75
	v_lshl_add_u32 v24, v24, 9, v158
	global_load_dwordx4 v[36:39], v24, s[100:101]
	global_load_dwordx4 v[44:47], v24, s[100:101] offset:64
	v_or_b32_e32 v24, 0xd0, v166
	v_add_u32_e32 v24, s76, v24
	v_med3_i32 v24, v24, 0, s75
	v_lshl_add_u32 v28, v24, 9, v158
	global_load_dwordx4 v[24:27], v28, s[100:101]
	s_nop 0
	global_load_dwordx4 v[28:31], v28, s[100:101] offset:64
	ds_read_b64_tr_b16 v[142:143], v169 offset:2304
	ds_read_b64_tr_b16 v[140:141], v169
	ds_read_b64_tr_b16 v[136:137], v169 offset:32
	ds_read_b64_tr_b16 v[138:139], v169 offset:2336
	ds_read_b64_tr_b16 v[132:133], v169 offset:64
	ds_read_b64_tr_b16 v[134:135], v169 offset:2368
	ds_read_b64_tr_b16 v[128:129], v169 offset:96
	ds_read_b64_tr_b16 v[130:131], v169 offset:2400
	s_waitcnt vmcnt(15)
	ds_write_b128 v241, v[76:79] offset:4608
	s_waitcnt vmcnt(14)
	ds_write_b128 v242, v[84:87] offset:4608
	s_waitcnt vmcnt(13)
	ds_write_b128 v243, v[92:95] offset:4608
	s_waitcnt vmcnt(12)
	ds_write_b128 v244, v[96:99] offset:4608
	v_mfma_f32_16x16x32_bf16 v[76:79], v[16:19], v[4:7], 0
	v_mfma_f32_16x16x32_bf16 v[16:19], v[16:19], v[12:15], 0
	v_mfma_f32_16x16x32_bf16 v[76:79], v[20:23], v[8:11], v[76:79]
	v_mfma_f32_16x16x32_bf16 v[84:87], v[48:51], v[4:7], 0
	v_mfma_f32_16x16x32_bf16 v[16:19], v[20:23], v[0:3], v[16:19]
	v_mfma_f32_16x16x32_bf16 v[20:23], v[48:51], v[12:15], 0
	v_add_u32_e32 v49, 0xc0, v154
	v_sub_u32_e32 v48, v49, v147
	v_add_u32_e32 v51, 1, v48
	s_nop 1
	v_cmp_gt_u32_e64 s[0:1], v51, v146
	v_cmp_gt_u32_e32 vcc, v48, v146
	s_nop 0
	v_cndmask_b32_e64 v77, v77, v246, s[0:1]
	s_nop 0
	v_cndmask_b32_e32 v76, v76, v246, vcc
	v_mfma_f32_16x16x32_bf16 v[84:87], v[52:55], v[8:11], v[84:87]
	v_max_f32_e32 v50, v76, v77
	v_add_u32_e32 v51, 2, v48
	v_cmp_gt_u32_e64 s[22:23], v51, v146
	v_mfma_f32_16x16x32_bf16 v[20:23], v[52:55], v[0:3], v[20:23]
	v_add_u32_e32 v52, 3, v48
	v_cmp_gt_u32_e64 s[24:25], v52, v146
	v_cndmask_b32_e64 v78, v78, v246, s[22:23]
	v_sub_u32_e32 v49, v49, v148
	v_cndmask_b32_e64 v79, v79, v246, s[24:25]
	v_max3_f32 v50, v50, v78, v79
	v_add_u32_e32 v51, 16, v48
	v_add_u32_e32 v52, 17, v48
	v_cmp_gt_u32_e64 s[26:27], v51, v146
	v_cmp_gt_u32_e64 s[28:29], v52, v146
	v_cmp_gt_u32_e64 s[38:39], v49, v145
	v_cndmask_b32_e64 v84, v84, v246, s[26:27]
	v_cndmask_b32_e64 v85, v85, v246, s[28:29]
	v_max3_f32 v50, v50, v84, v85
	v_add_u32_e32 v51, 18, v48
	v_add_u32_e32 v48, 19, v48
	v_cmp_gt_u32_e64 s[30:31], v51, v146
	v_cmp_gt_u32_e64 s[34:35], v48, v146
	v_add_u32_e32 v52, 3, v49
	v_cndmask_b32_e64 v86, v86, v246, s[30:31]
	v_cndmask_b32_e64 v87, v87, v246, s[34:35]
	v_max3_f32 v48, v50, v86, v87
	v_add_u32_e32 v51, 1, v49
	v_cmp_gt_u32_e64 s[40:41], v51, v145
	v_cndmask_b32_e64 v16, v16, v246, s[38:39]
	s_nop 0
	v_cndmask_b32_e64 v17, v17, v246, s[40:41]
	v_max_f32_e32 v50, v16, v17
	v_add_u32_e32 v51, 2, v49
	v_cmp_gt_u32_e64 s[42:43], v51, v145
	v_cmp_gt_u32_e64 s[44:45], v52, v145
	s_nop 0
	v_cndmask_b32_e64 v18, v18, v246, s[42:43]
	v_cndmask_b32_e64 v19, v19, v246, s[44:45]
	v_max3_f32 v50, v50, v18, v19
	v_add_u32_e32 v51, 16, v49
	v_add_u32_e32 v52, 17, v49
	v_cmp_gt_u32_e64 s[46:47], v51, v145
	v_cmp_gt_u32_e64 s[48:49], v52, v145
	s_nop 0
	v_cndmask_b32_e64 v20, v20, v246, s[46:47]
	v_cndmask_b32_e64 v21, v21, v246, s[48:49]
	v_max3_f32 v50, v50, v20, v21
	v_add_u32_e32 v51, 18, v49
	v_add_u32_e32 v49, 19, v49
	v_cmp_gt_u32_e64 s[50:51], v51, v145
	v_cmp_gt_u32_e64 s[52:53], v49, v145
	s_nop 0
	v_cndmask_b32_e64 v22, v22, v246, s[50:51]
	v_cndmask_b32_e64 v23, v23, v246, s[52:53]
	v_max3_f32 v49, v50, v22, v23
	v_mov_b32_e32 v50, v48
	s_nop 1
	v_permlane32_swap_b32_e32 v50, v48
	v_max_f32_e32 v48, v48, v50
	v_mov_b32_e32 v50, v49
	s_nop 1
	v_permlane32_swap_b32_e32 v50, v49
	v_max_f32_e32 v49, v49, v50
	v_mov_b32_e32 v50, v48
	s_nop 1
	v_permlane16_swap_b32_e32 v50, v48
	v_max_f32_e32 v48, v48, v50
	v_mov_b32_e32 v50, v49
	s_nop 1
	v_permlane16_swap_b32_e32 v50, v49
	v_max_f32_e32 v175, v179, v48
	v_sub_f32_e32 v48, v179, v175
	v_max3_f32 v177, v181, v49, v50
	v_exp_f32_e32 v52, v48
	v_sub_f32_e32 v48, v76, v175
	v_sub_f32_e32 v16, v16, v177
	v_exp_f32_e32 v48, v48
	v_sub_f32_e32 v50, v77, v175
	v_exp_f32_e32 v16, v16
	v_sub_f32_e32 v17, v17, v177
	v_exp_f32_e32 v50, v50
	v_sub_f32_e32 v51, v78, v175
	v_exp_f32_e32 v17, v17
	v_sub_f32_e32 v18, v18, v177
	v_exp_f32_e32 v51, v51
	v_sub_f32_e32 v55, v79, v175
	v_exp_f32_e32 v18, v18
	v_sub_f32_e32 v19, v19, v177
	v_exp_f32_e32 v55, v55
	v_sub_f32_e32 v76, v84, v175
	v_exp_f32_e32 v19, v19
	v_sub_f32_e32 v20, v20, v177
	v_exp_f32_e32 v76, v76
	v_sub_f32_e32 v77, v85, v175
	v_sub_f32_e32 v53, v181, v177
	v_exp_f32_e32 v20, v20
	v_sub_f32_e32 v21, v21, v177
	v_exp_f32_e32 v77, v77
	v_sub_f32_e32 v78, v86, v175
	v_exp_f32_e32 v54, v53
	v_exp_f32_e32 v21, v21
	v_sub_f32_e32 v22, v22, v177
	v_add_f32_e32 v49, v50, v48
	v_exp_f32_e32 v78, v78
	v_sub_f32_e32 v79, v87, v175
	v_add_f32_e32 v53, v17, v16
	v_exp_f32_e32 v22, v22
	v_sub_f32_e32 v23, v23, v177
	v_add_f32_e32 v49, v51, v49
	v_exp_f32_e32 v79, v79
	v_add_f32_e32 v53, v18, v53
	v_exp_f32_e32 v23, v23
	v_add_f32_e32 v49, v55, v49
	v_add_f32_e32 v53, v19, v53
	v_add_f32_e32 v49, v76, v49
	v_add_f32_e32 v53, v20, v53
	v_add_f32_e32 v49, v77, v49
	v_add_f32_e32 v53, v21, v53
	v_add_f32_e32 v49, v78, v49
	v_add_f32_e32 v53, v22, v53
	v_add_f32_e32 v176, v79, v49
	v_cvt_pk_bf16_f32 v48, v48, v50
	v_cvt_pk_bf16_f32 v49, v51, v55
	v_cvt_pk_bf16_f32 v50, v76, v77
	v_cvt_pk_bf16_f32 v51, v78, v79
	v_add_f32_e32 v178, v23, v53
	v_cvt_pk_bf16_f32 v16, v16, v17
	v_cvt_pk_bf16_f32 v17, v18, v19
	v_cvt_pk_bf16_f32 v18, v20, v21
	v_cvt_pk_bf16_f32 v19, v22, v23
	v_pk_mul_f32 v[22:23], v[70:71], v[52:53] op_sel_hi:[1,0]
	v_pk_mul_f32 v[20:21], v[68:69], v[52:53] op_sel_hi:[1,0]
	v_fmac_f32_e32 v176, v180, v52
	v_fmac_f32_e32 v178, v183, v54
	s_waitcnt lgkmcnt(10)
	v_mfma_f32_16x16x32_bf16 v[76:79], v[140:143], v[48:51], v[20:23]
	v_add_u32_e32 v180, 0x100, v149
	v_add_u32_e32 v179, 0x100, v150
	s_nop 0
	v_pk_mul_f32 v[22:23], v[74:75], v[54:55] op_sel_hi:[1,0]
	v_pk_mul_f32 v[20:21], v[72:73], v[54:55] op_sel_hi:[1,0]
	s_nop 1
	v_mfma_f32_16x16x32_bf16 v[92:95], v[140:143], v[16:19], v[20:23]
	s_nop 2
	v_mul_f32_e64 v22, v82, v52
	v_mul_f32_e64 v23, v83, v52
	v_pk_mul_f32 v[20:21], v[80:81], v[52:53] op_sel_hi:[1,0]
	s_waitcnt lgkmcnt(8)
	s_nop 0
	v_mfma_f32_16x16x32_bf16 v[96:99], v[136:139], v[48:51], v[20:23]
	s_nop 2
	v_mul_f32_e64 v22, v110, v54
	v_mul_f32_e64 v23, v111, v54
	v_pk_mul_f32 v[20:21], v[108:109], v[54:55] op_sel_hi:[1,0]
	s_nop 1
	v_mfma_f32_16x16x32_bf16 v[108:111], v[136:139], v[16:19], v[20:23]
	s_nop 2
	v_mul_f32_e64 v22, v114, v52
	v_mul_f32_e64 v23, v115, v52
	v_pk_mul_f32 v[20:21], v[112:113], v[52:53] op_sel_hi:[1,0]
	s_waitcnt lgkmcnt(6)
	s_nop 0
	v_mfma_f32_16x16x32_bf16 v[112:115], v[132:135], v[48:51], v[20:23]
	s_nop 2
	v_mul_f32_e64 v22, v118, v54
	v_mul_f32_e64 v23, v119, v54
	v_pk_mul_f32 v[20:21], v[116:117], v[54:55] op_sel_hi:[1,0]
	s_nop 1
	v_mfma_f32_16x16x32_bf16 v[116:119], v[132:135], v[16:19], v[20:23]
	s_nop 2
	v_mul_f32_e64 v22, v122, v52
	v_mul_f32_e64 v23, v123, v52
	v_pk_mul_f32 v[20:21], v[120:121], v[52:53] op_sel_hi:[1,0]
	s_waitcnt lgkmcnt(4)
	s_nop 0
	v_mfma_f32_16x16x32_bf16 v[120:123], v[128:131], v[48:51], v[20:23]
	s_nop 2
	v_mul_f32_e64 v22, v126, v54
	v_mul_f32_e64 v23, v127, v54
	v_pk_mul_f32 v[20:21], v[124:125], v[54:55] op_sel_hi:[1,0]
	s_nop 1
	v_mfma_f32_16x16x32_bf16 v[124:127], v[128:131], v[16:19], v[20:23]
	v_add_u32_e32 v16, 0xe0, v149
	v_med3_i32 v16, v16, 0, s75
	v_lshl_add_u32 v16, v16, 9, v152
	global_load_dwordx4 v[68:71], v16, s[98:99]
	v_add_u32_e32 v16, 0xe0, v150
	v_med3_i32 v16, v16, 0, s75
	v_lshl_add_u32 v16, v16, 9, v152
	global_load_dwordx4 v[72:75], v16, s[98:99]
	v_add_u32_e32 v16, 0xe0, v151
	v_med3_i32 v16, v16, 0, s75
	v_lshl_add_u32 v16, v16, 9, v152
	global_load_dwordx4 v[80:83], v16, s[98:99]
	v_add_u32_e32 v16, 0xe0, v252
	v_med3_i32 v16, v16, 0, s75
	v_lshl_add_u32 v16, v16, 9, v152
	global_load_dwordx4 v[84:87], v16, s[98:99]
	v_or_b32_e32 v16, 0xe0, v166
	v_add_u32_e32 v16, s76, v16
	v_med3_i32 v16, v16, 0, s75
	v_lshl_add_u32 v16, v16, 9, v158
	global_load_dwordx4 v[48:51], v16, s[100:101]
	global_load_dwordx4 v[52:55], v16, s[100:101] offset:64
	v_or_b32_e32 v16, 0xf0, v166
	v_add_u32_e32 v16, s76, v16
	v_med3_i32 v16, v16, 0, s75
	v_lshl_add_u32 v20, v16, 9, v158
	global_load_dwordx4 v[16:19], v20, s[100:101]
	s_nop 0
	global_load_dwordx4 v[20:23], v20, s[100:101] offset:64
	ds_read_b64_tr_b16 v[142:143], v169 offset:6912
	ds_read_b64_tr_b16 v[140:141], v169 offset:4608
	ds_read_b64_tr_b16 v[136:137], v169 offset:4640
	ds_read_b64_tr_b16 v[138:139], v169 offset:6944
	ds_read_b64_tr_b16 v[132:133], v169 offset:4672
	ds_read_b64_tr_b16 v[134:135], v169 offset:6976
	ds_read_b64_tr_b16 v[128:129], v169 offset:4704
	ds_read_b64_tr_b16 v[130:131], v169 offset:7008
	s_waitcnt vmcnt(15)
	ds_write_b128 v241, v[64:67]
	s_waitcnt vmcnt(14)
	ds_write_b128 v242, v[88:91]
	s_waitcnt vmcnt(13)
	ds_write_b128 v243, v[100:103]
	s_waitcnt vmcnt(12)
	ds_write_b128 v244, v[104:107]
	v_mfma_f32_16x16x32_bf16 v[64:67], v[32:35], v[4:7], 0
	v_mfma_f32_16x16x32_bf16 v[32:35], v[32:35], v[12:15], 0
	v_mfma_f32_16x16x32_bf16 v[64:67], v[40:43], v[8:11], v[64:67]
	v_mfma_f32_16x16x32_bf16 v[88:91], v[56:59], v[4:7], 0
	v_mfma_f32_16x16x32_bf16 v[32:35], v[40:43], v[0:3], v[32:35]
	v_mfma_f32_16x16x32_bf16 v[40:43], v[56:59], v[12:15], 0
	v_add_u32_e32 v57, 0xe0, v154
	v_sub_u32_e32 v56, v57, v147
	v_add_u32_e32 v59, 1, v56
	s_nop 1
	v_cmp_gt_u32_e64 s[0:1], v59, v146
	v_cmp_gt_u32_e32 vcc, v56, v146
	s_nop 0
	v_cndmask_b32_e64 v65, v65, v246, s[0:1]
	s_nop 0
	v_cndmask_b32_e32 v64, v64, v246, vcc
	v_mfma_f32_16x16x32_bf16 v[88:91], v[60:63], v[8:11], v[88:91]
	v_max_f32_e32 v58, v64, v65
	v_add_u32_e32 v59, 2, v56
	v_cmp_gt_u32_e64 s[22:23], v59, v146
	v_mfma_f32_16x16x32_bf16 v[40:43], v[60:63], v[0:3], v[40:43]
	v_add_u32_e32 v60, 3, v56
	v_cmp_gt_u32_e64 s[24:25], v60, v146
	v_cndmask_b32_e64 v66, v66, v246, s[22:23]
	v_sub_u32_e32 v57, v57, v148
	v_cndmask_b32_e64 v67, v67, v246, s[24:25]
	v_max3_f32 v58, v58, v66, v67
	v_add_u32_e32 v59, 16, v56
	v_add_u32_e32 v60, 17, v56
	v_cmp_gt_u32_e64 s[26:27], v59, v146
	v_cmp_gt_u32_e64 s[28:29], v60, v146
	v_cmp_gt_u32_e64 s[38:39], v57, v145
	v_cndmask_b32_e64 v88, v88, v246, s[26:27]
	v_cndmask_b32_e64 v89, v89, v246, s[28:29]
	v_max3_f32 v58, v58, v88, v89
	v_add_u32_e32 v59, 18, v56
	v_add_u32_e32 v56, 19, v56
	v_cmp_gt_u32_e64 s[30:31], v59, v146
	v_cmp_gt_u32_e64 s[34:35], v56, v146
	v_add_u32_e32 v60, 3, v57
	v_cndmask_b32_e64 v90, v90, v246, s[30:31]
	v_cndmask_b32_e64 v91, v91, v246, s[34:35]
	v_max3_f32 v56, v58, v90, v91
	v_add_u32_e32 v59, 1, v57
	v_cmp_gt_u32_e64 s[40:41], v59, v145
	v_cndmask_b32_e64 v32, v32, v246, s[38:39]
	s_nop 0
	v_cndmask_b32_e64 v33, v33, v246, s[40:41]
	v_max_f32_e32 v58, v32, v33
	v_add_u32_e32 v59, 2, v57
	v_cmp_gt_u32_e64 s[42:43], v59, v145
	v_cmp_gt_u32_e64 s[44:45], v60, v145
	s_nop 0
	v_cndmask_b32_e64 v34, v34, v246, s[42:43]
	v_cndmask_b32_e64 v35, v35, v246, s[44:45]
	v_max3_f32 v58, v58, v34, v35
	v_add_u32_e32 v59, 16, v57
	v_add_u32_e32 v60, 17, v57
	v_cmp_gt_u32_e64 s[46:47], v59, v145
	v_cmp_gt_u32_e64 s[48:49], v60, v145
	s_nop 0
	v_cndmask_b32_e64 v40, v40, v246, s[46:47]
	v_cndmask_b32_e64 v41, v41, v246, s[48:49]
	v_max3_f32 v58, v58, v40, v41
	v_add_u32_e32 v59, 18, v57
	v_add_u32_e32 v57, 19, v57
	v_cmp_gt_u32_e64 s[50:51], v59, v145
	v_cmp_gt_u32_e64 s[52:53], v57, v145
	s_nop 0
	v_cndmask_b32_e64 v42, v42, v246, s[50:51]
	v_cndmask_b32_e64 v43, v43, v246, s[52:53]
	v_max3_f32 v57, v58, v42, v43
	v_mov_b32_e32 v58, v56
	s_nop 1
	v_permlane32_swap_b32_e32 v58, v56
	v_max_f32_e32 v56, v56, v58
	v_mov_b32_e32 v58, v57
	s_nop 1
	v_permlane32_swap_b32_e32 v58, v57
	v_max_f32_e32 v57, v57, v58
	v_mov_b32_e32 v58, v56
	s_nop 1
	v_permlane16_swap_b32_e32 v58, v56
	v_max_f32_e32 v56, v56, v58
	v_mov_b32_e32 v58, v57
	s_nop 1
	v_permlane16_swap_b32_e32 v58, v57
	v_max_f32_e32 v181, v175, v56
	v_sub_f32_e32 v56, v175, v181
	v_max3_f32 v184, v177, v57, v58
	v_exp_f32_e32 v60, v56
	v_sub_f32_e32 v56, v64, v181
	v_sub_f32_e32 v32, v32, v184
	v_exp_f32_e32 v56, v56
	v_sub_f32_e32 v58, v65, v181
	v_exp_f32_e32 v32, v32
	v_sub_f32_e32 v33, v33, v184
	v_exp_f32_e32 v58, v58
	v_sub_f32_e32 v59, v66, v181
	v_exp_f32_e32 v33, v33
	v_sub_f32_e32 v34, v34, v184
	v_exp_f32_e32 v59, v59
	v_sub_f32_e32 v63, v67, v181
	v_exp_f32_e32 v34, v34
	v_sub_f32_e32 v35, v35, v184
	v_exp_f32_e32 v63, v63
	v_sub_f32_e32 v64, v88, v181
	v_exp_f32_e32 v35, v35
	v_sub_f32_e32 v40, v40, v184
	v_exp_f32_e32 v64, v64
	v_sub_f32_e32 v65, v89, v181
	v_sub_f32_e32 v61, v177, v184
	v_exp_f32_e32 v40, v40
	v_sub_f32_e32 v41, v41, v184
	v_exp_f32_e32 v65, v65
	v_sub_f32_e32 v66, v90, v181
	v_exp_f32_e32 v62, v61
	v_exp_f32_e32 v41, v41
	v_sub_f32_e32 v42, v42, v184
	v_add_f32_e32 v57, v58, v56
	v_exp_f32_e32 v66, v66
	v_sub_f32_e32 v67, v91, v181
	v_add_f32_e32 v61, v33, v32
	v_exp_f32_e32 v42, v42
	v_sub_f32_e32 v43, v43, v184
	v_add_f32_e32 v57, v59, v57
	v_exp_f32_e32 v67, v67
	v_add_f32_e32 v61, v34, v61
	v_exp_f32_e32 v43, v43
	v_add_f32_e32 v57, v63, v57
	v_add_f32_e32 v61, v35, v61
	v_add_f32_e32 v57, v64, v57
	v_add_f32_e32 v61, v40, v61
	v_add_f32_e32 v57, v65, v57
	v_add_f32_e32 v61, v41, v61
	v_add_f32_e32 v57, v66, v57
	v_add_f32_e32 v61, v42, v61
	v_add_f32_e32 v183, v67, v57
	v_cvt_pk_bf16_f32 v56, v56, v58
	v_cvt_pk_bf16_f32 v57, v59, v63
	v_cvt_pk_bf16_f32 v58, v64, v65
	v_cvt_pk_bf16_f32 v59, v66, v67
	v_add_f32_e32 v185, v43, v61
	v_cvt_pk_bf16_f32 v32, v32, v33
	v_cvt_pk_bf16_f32 v33, v34, v35
	v_cvt_pk_bf16_f32 v34, v40, v41
	v_cvt_pk_bf16_f32 v35, v42, v43
	v_pk_mul_f32 v[42:43], v[78:79], v[60:61] op_sel_hi:[1,0]
	v_pk_mul_f32 v[40:41], v[76:77], v[60:61] op_sel_hi:[1,0]
	v_fmac_f32_e32 v185, v178, v62
	s_waitcnt lgkmcnt(10)
	v_mfma_f32_16x16x32_bf16 v[100:103], v[140:143], v[56:59], v[40:43]
	v_add_u32_e32 v178, 0x100, v151
	v_fmac_f32_e32 v183, v176, v60
	v_add_u32_e32 v177, 0x100, v252
	v_pk_mul_f32 v[42:43], v[94:95], v[62:63] op_sel_hi:[1,0]
	v_pk_mul_f32 v[40:41], v[92:93], v[62:63] op_sel_hi:[1,0]
	s_nop 1
	v_mfma_f32_16x16x32_bf16 v[92:95], v[140:143], v[32:35], v[40:43]
	s_nop 2
	v_mul_f32_e64 v42, v98, v60
	v_mul_f32_e64 v43, v99, v60
	v_pk_mul_f32 v[40:41], v[96:97], v[60:61] op_sel_hi:[1,0]
	s_waitcnt lgkmcnt(8)
	s_nop 0
	v_mfma_f32_16x16x32_bf16 v[104:107], v[136:139], v[56:59], v[40:43]
	s_nop 2
	v_mul_f32_e64 v42, v110, v62
	v_mul_f32_e64 v43, v111, v62
	v_pk_mul_f32 v[40:41], v[108:109], v[62:63] op_sel_hi:[1,0]
	s_nop 1
	v_mfma_f32_16x16x32_bf16 v[108:111], v[136:139], v[32:35], v[40:43]
	s_nop 2
	v_mul_f32_e64 v42, v114, v60
	v_mul_f32_e64 v43, v115, v60
	v_pk_mul_f32 v[40:41], v[112:113], v[60:61] op_sel_hi:[1,0]
	s_waitcnt lgkmcnt(6)
	s_nop 0
	v_mfma_f32_16x16x32_bf16 v[112:115], v[132:135], v[56:59], v[40:43]
	s_nop 2
	v_mul_f32_e64 v42, v118, v62
	v_mul_f32_e64 v43, v119, v62
	v_pk_mul_f32 v[40:41], v[116:117], v[62:63] op_sel_hi:[1,0]
	s_nop 1
	v_mfma_f32_16x16x32_bf16 v[116:119], v[132:135], v[32:35], v[40:43]
	s_nop 2
	v_mul_f32_e64 v42, v122, v60
	v_mul_f32_e64 v43, v123, v60
	v_pk_mul_f32 v[40:41], v[120:121], v[60:61] op_sel_hi:[1,0]
	s_waitcnt lgkmcnt(4)
	s_nop 0
	v_mfma_f32_16x16x32_bf16 v[120:123], v[128:131], v[56:59], v[40:43]
	s_nop 2
	v_mul_f32_e64 v42, v126, v62
	v_mul_f32_e64 v43, v127, v62
	v_pk_mul_f32 v[40:41], v[124:125], v[62:63] op_sel_hi:[1,0]
	s_nop 1
	v_mfma_f32_16x16x32_bf16 v[124:127], v[128:131], v[32:35], v[40:43]
	v_med3_i32 v32, v180, 0, s75
	v_lshl_add_u32 v32, v32, 9, v152
	global_load_dwordx4 v[56:59], v32, s[98:99]
	v_med3_i32 v32, v179, 0, s75
	v_lshl_add_u32 v32, v32, 9, v152
	global_load_dwordx4 v[60:63], v32, s[98:99]
	v_med3_i32 v32, v178, 0, s75
	v_lshl_add_u32 v32, v32, 9, v152
	global_load_dwordx4 v[88:91], v32, s[98:99]
	v_med3_i32 v32, v177, 0, s75
	v_lshl_add_u32 v32, v32, 9, v152
	global_load_dwordx4 v[96:99], v32, s[98:99]
	v_or_b32_e32 v32, 0x100, v166
	v_add_u32_e32 v32, s76, v32
	v_med3_i32 v32, v32, 0, s75
	v_lshl_add_u32 v32, v32, 9, v158
	global_load_dwordx4 v[76:79], v32, s[100:101]
	global_load_dwordx4 v[64:67], v32, s[100:101] offset:64
	v_or_b32_e32 v32, 0x110, v166
	v_add_u32_e32 v32, s76, v32
	v_med3_i32 v32, v32, 0, s75
	v_lshl_add_u32 v32, v32, 9, v158
	global_load_dwordx4 v[40:43], v32, s[100:101]
	s_nop 0
	global_load_dwordx4 v[32:35], v32, s[100:101] offset:64
	ds_read_b64_tr_b16 v[142:143], v169 offset:2304
	ds_read_b64_tr_b16 v[140:141], v169
	ds_read_b64_tr_b16 v[136:137], v169 offset:32
	ds_read_b64_tr_b16 v[138:139], v169 offset:2336
	ds_read_b64_tr_b16 v[132:133], v169 offset:64
	ds_read_b64_tr_b16 v[134:135], v169 offset:2368
	ds_read_b64_tr_b16 v[128:129], v169 offset:96
	ds_read_b64_tr_b16 v[130:131], v169 offset:2400
	s_waitcnt vmcnt(15)
	ds_write_b128 v241, v[68:71] offset:4608
	s_waitcnt vmcnt(14)
	ds_write_b128 v242, v[72:75] offset:4608
	s_waitcnt vmcnt(13)
	ds_write_b128 v243, v[80:83] offset:4608
	s_waitcnt vmcnt(12)
	ds_write_b128 v244, v[84:87] offset:4608
	v_mfma_f32_16x16x32_bf16 v[68:71], v[36:39], v[4:7], 0
	v_mfma_f32_16x16x32_bf16 v[72:75], v[24:27], v[4:7], 0
	v_mfma_f32_16x16x32_bf16 v[24:27], v[24:27], v[12:15], 0
	v_mfma_f32_16x16x32_bf16 v[68:71], v[44:47], v[8:11], v[68:71]
	v_mfma_f32_16x16x32_bf16 v[72:75], v[28:31], v[8:11], v[72:75]
	v_mfma_f32_16x16x32_bf16 v[24:27], v[28:31], v[0:3], v[24:27]
	v_add_u32_e32 v29, 0x100, v154
	v_sub_u32_e32 v28, v29, v147
	v_add_u32_e32 v31, 1, v28
	v_mfma_f32_16x16x32_bf16 v[36:39], v[36:39], v[12:15], 0
	s_nop 1
	v_cmp_gt_u32_e64 s[0:1], v31, v146
	v_cmp_gt_u32_e32 vcc, v28, v146
	s_nop 0
	v_cndmask_b32_e64 v69, v69, v246, s[0:1]
	s_nop 0
	v_cndmask_b32_e32 v68, v68, v246, vcc
	v_mfma_f32_16x16x32_bf16 v[36:39], v[44:47], v[0:3], v[36:39]
	v_max_f32_e32 v30, v68, v69
	v_add_u32_e32 v31, 2, v28
	v_add_u32_e32 v44, 3, v28
	v_cmp_gt_u32_e64 s[22:23], v31, v146
	v_cmp_gt_u32_e64 s[24:25], v44, v146
	v_sub_u32_e32 v29, v29, v148
	v_cndmask_b32_e64 v70, v70, v246, s[22:23]
	v_cndmask_b32_e64 v71, v71, v246, s[24:25]
	v_max3_f32 v30, v30, v70, v71
	v_add_u32_e32 v31, 16, v28
	v_add_u32_e32 v44, 17, v28
	v_cmp_gt_u32_e64 s[26:27], v31, v146
	v_cmp_gt_u32_e64 s[28:29], v44, v146
	v_cmp_gt_u32_e64 s[38:39], v29, v145
	v_cndmask_b32_e64 v72, v72, v246, s[26:27]
	v_cndmask_b32_e64 v73, v73, v246, s[28:29]
	v_max3_f32 v30, v30, v72, v73
	v_add_u32_e32 v31, 18, v28
	v_add_u32_e32 v28, 19, v28
	v_cmp_gt_u32_e64 s[30:31], v31, v146
	v_cmp_gt_u32_e64 s[34:35], v28, v146
	v_add_u32_e32 v44, 3, v29
	v_cndmask_b32_e64 v74, v74, v246, s[30:31]
	v_cndmask_b32_e64 v75, v75, v246, s[34:35]
	v_max3_f32 v28, v30, v74, v75
	v_add_u32_e32 v31, 1, v29
	v_cmp_gt_u32_e64 s[40:41], v31, v145
	v_cndmask_b32_e64 v36, v36, v246, s[38:39]
	s_nop 0
	v_cndmask_b32_e64 v37, v37, v246, s[40:41]
	v_max_f32_e32 v30, v36, v37
	v_add_u32_e32 v31, 2, v29
	v_cmp_gt_u32_e64 s[42:43], v31, v145
	v_cmp_gt_u32_e64 s[44:45], v44, v145
	s_nop 0
	v_cndmask_b32_e64 v38, v38, v246, s[42:43]
	v_cndmask_b32_e64 v39, v39, v246, s[44:45]
	v_max3_f32 v30, v30, v38, v39
	v_add_u32_e32 v31, 16, v29
	v_add_u32_e32 v44, 17, v29
	v_cmp_gt_u32_e64 s[46:47], v31, v145
	v_cmp_gt_u32_e64 s[48:49], v44, v145
	s_nop 0
	v_cndmask_b32_e64 v24, v24, v246, s[46:47]
	v_cndmask_b32_e64 v25, v25, v246, s[48:49]
	v_max3_f32 v30, v30, v24, v25
	v_add_u32_e32 v31, 18, v29
	v_add_u32_e32 v29, 19, v29
	v_cmp_gt_u32_e64 s[50:51], v31, v145
	v_cmp_gt_u32_e64 s[52:53], v29, v145
	s_nop 0
	v_cndmask_b32_e64 v26, v26, v246, s[50:51]
	v_cndmask_b32_e64 v27, v27, v246, s[52:53]
	v_max3_f32 v29, v30, v26, v27
	v_mov_b32_e32 v30, v28
	s_nop 1
	v_permlane32_swap_b32_e32 v30, v28
	v_max_f32_e32 v28, v28, v30
	v_mov_b32_e32 v30, v29
	s_nop 1
	v_permlane32_swap_b32_e32 v30, v29
	v_max_f32_e32 v29, v29, v30
	v_mov_b32_e32 v30, v28
	s_nop 1
	v_permlane16_swap_b32_e32 v30, v28
	v_max_f32_e32 v28, v28, v30
	v_mov_b32_e32 v30, v29
	v_max_f32_e32 v175, v181, v28
	s_nop 0
	v_permlane16_swap_b32_e32 v30, v29
	v_sub_f32_e32 v28, v181, v175
	v_exp_f32_e32 v44, v28
	v_sub_f32_e32 v28, v68, v175
	v_max_f32_e32 v46, v29, v30
	v_exp_f32_e32 v28, v28
	v_sub_f32_e32 v30, v69, v175
	v_exp_f32_e32 v30, v30
	v_sub_f32_e32 v31, v70, v175
	v_exp_f32_e32 v31, v31
	v_sub_f32_e32 v47, v71, v175
	v_max_f32_e32 v181, v184, v46
	v_exp_f32_e32 v47, v47
	v_sub_f32_e32 v68, v72, v175
	v_sub_f32_e32 v36, v36, v181
	v_exp_f32_e32 v68, v68
	v_sub_f32_e32 v69, v73, v175
	v_exp_f32_e32 v36, v36
	v_sub_f32_e32 v37, v37, v181
	v_exp_f32_e32 v69, v69
	v_sub_f32_e32 v70, v74, v175
	v_exp_f32_e32 v37, v37
	v_sub_f32_e32 v38, v38, v181
	v_add_f32_e32 v29, v30, v28
	v_exp_f32_e32 v70, v70
	v_sub_f32_e32 v71, v75, v175
	v_exp_f32_e32 v38, v38
	v_sub_f32_e32 v39, v39, v181
	v_add_f32_e32 v29, v31, v29
	v_exp_f32_e32 v71, v71
	v_exp_f32_e32 v39, v39
	v_sub_f32_e32 v24, v24, v181
	v_add_f32_e32 v29, v47, v29
	v_sub_f32_e32 v45, v184, v181
	v_exp_f32_e32 v24, v24
	v_sub_f32_e32 v25, v25, v181
	v_add_f32_e32 v29, v68, v29
	v_exp_f32_e32 v46, v45
	v_exp_f32_e32 v25, v25
	v_add_f32_e32 v29, v69, v29
	v_add_f32_e32 v45, v37, v36
	v_add_f32_e32 v29, v70, v29
	v_add_f32_e32 v45, v38, v45
	v_add_f32_e32 v176, v71, v29
	v_cvt_pk_bf16_f32 v29, v31, v47
	v_add_f32_e32 v45, v39, v45
	v_cndmask_b32_e64 v47, v24, 0, s[46:47]
	v_add_f32_e32 v24, v47, v45
	v_cndmask_b32_e64 v45, v25, 0, s[48:49]
	v_sub_f32_e32 v25, v26, v181
	v_exp_f32_e32 v25, v25
	v_cvt_pk_bf16_f32 v28, v28, v30
	v_cvt_pk_bf16_f32 v30, v68, v69
	v_add_f32_e32 v24, v45, v24
	v_cndmask_b32_e64 v68, v25, 0, s[50:51]
	v_sub_f32_e32 v25, v27, v181
	v_exp_f32_e32 v25, v25
	v_add_f32_e32 v24, v68, v24
	v_fmac_f32_e32 v176, v183, v44
	v_cvt_pk_bf16_f32 v31, v70, v71
	v_cndmask_b32_e64 v27, v25, 0, s[52:53]
	v_add_f32_e32 v183, v27, v24
	v_cvt_pk_bf16_f32 v24, v36, v37
	v_cvt_pk_bf16_f32 v25, v38, v39
	v_pk_mul_f32 v[38:39], v[102:103], v[44:45] op_sel_hi:[1,0]
	v_pk_mul_f32 v[36:37], v[100:101], v[44:45] op_sel_hi:[1,0]
	v_cvt_pk_bf16_f32 v26, v47, v45
	v_cvt_pk_bf16_f32 v27, v68, v27
	s_waitcnt lgkmcnt(10)
	v_mfma_f32_16x16x32_bf16 v[80:83], v[140:143], v[28:31], v[36:39]
	v_fmac_f32_e32 v183, v185, v46
	v_add_u32_e32 v184, s76, v204
	v_add_u32_e32 v185, s76, v205
	v_pk_mul_f32 v[38:39], v[94:95], v[46:47] op_sel_hi:[1,0]
	v_pk_mul_f32 v[36:37], v[92:93], v[46:47] op_sel_hi:[1,0]
	s_nop 1
	v_mfma_f32_16x16x32_bf16 v[84:87], v[140:143], v[24:27], v[36:39]
	s_nop 2
	v_mul_f32_e64 v38, v106, v44
	v_mul_f32_e64 v39, v107, v44
	v_pk_mul_f32 v[36:37], v[104:105], v[44:45] op_sel_hi:[1,0]
	s_waitcnt lgkmcnt(8)
	s_nop 0
	v_mfma_f32_16x16x32_bf16 v[104:107], v[136:139], v[28:31], v[36:39]
	s_nop 2
	v_mul_f32_e64 v38, v110, v46
	v_mul_f32_e64 v39, v111, v46
	v_pk_mul_f32 v[36:37], v[108:109], v[46:47] op_sel_hi:[1,0]
	s_nop 1
	v_mfma_f32_16x16x32_bf16 v[108:111], v[136:139], v[24:27], v[36:39]
	s_nop 2
	v_mul_f32_e64 v38, v114, v44
	v_mul_f32_e64 v39, v115, v44
	v_pk_mul_f32 v[36:37], v[112:113], v[44:45] op_sel_hi:[1,0]
	s_waitcnt lgkmcnt(6)
	s_nop 0
	v_mfma_f32_16x16x32_bf16 v[112:115], v[132:135], v[28:31], v[36:39]
	s_nop 2
	v_mul_f32_e64 v38, v118, v46
	v_mul_f32_e64 v39, v119, v46
	v_pk_mul_f32 v[36:37], v[116:117], v[46:47] op_sel_hi:[1,0]
	s_nop 1
	v_mfma_f32_16x16x32_bf16 v[116:119], v[132:135], v[24:27], v[36:39]
	s_nop 2
	v_mul_f32_e64 v38, v122, v44
	v_mul_f32_e64 v39, v123, v44
	v_pk_mul_f32 v[36:37], v[120:121], v[44:45] op_sel_hi:[1,0]
	s_waitcnt lgkmcnt(4)
	s_nop 0
	v_mfma_f32_16x16x32_bf16 v[120:123], v[128:131], v[28:31], v[36:39]
	v_mul_f32_e64 v30, v126, v46
	v_mul_f32_e64 v31, v127, v46
	v_pk_mul_f32 v[28:29], v[124:125], v[46:47] op_sel_hi:[1,0]
	s_nop 1
	v_mfma_f32_16x16x32_bf16 v[124:127], v[128:131], v[24:27], v[28:31]
	v_add_u32_e32 v24, 0x120, v149
	v_med3_i32 v24, v24, 0, s75
	v_lshl_add_u32 v24, v24, 9, v152
	global_load_dwordx4 v[28:31], v24, s[98:99]
	v_add_u32_e32 v24, 0x120, v150
	v_med3_i32 v24, v24, 0, s75
	v_lshl_add_u32 v24, v24, 9, v152
	global_load_dwordx4 v[44:47], v24, s[98:99]
	v_add_u32_e32 v24, 0x120, v151
	v_med3_i32 v24, v24, 0, s75
	v_lshl_add_u32 v24, v24, 9, v152
	global_load_dwordx4 v[92:95], v24, s[98:99]
	v_add_u32_e32 v24, 0x120, v252
	v_med3_i32 v24, v24, 0, s75
	v_lshl_add_u32 v24, v24, 9, v152
	global_load_dwordx4 v[100:103], v24, s[98:99]
	v_or_b32_e32 v24, 0x120, v166
	v_add_u32_e32 v24, s76, v24
	v_med3_i32 v24, v24, 0, s75
	v_lshl_add_u32 v24, v24, 9, v158
	global_load_dwordx4 v[72:75], v24, s[100:101]
	global_load_dwordx4 v[68:71], v24, s[100:101] offset:64
	v_or_b32_e32 v24, 0x130, v166
	v_add_u32_e32 v24, s76, v24
	v_med3_i32 v24, v24, 0, s75
	v_lshl_add_u32 v24, v24, 9, v158
	global_load_dwordx4 v[36:39], v24, s[100:101]
	s_nop 0
	global_load_dwordx4 v[24:27], v24, s[100:101] offset:64
	ds_read_b64_tr_b16 v[142:143], v169 offset:6912
	ds_read_b64_tr_b16 v[140:141], v169 offset:4608
	ds_read_b64_tr_b16 v[136:137], v169 offset:4640
	ds_read_b64_tr_b16 v[138:139], v169 offset:6944
	ds_read_b64_tr_b16 v[132:133], v169 offset:4672
	ds_read_b64_tr_b16 v[134:135], v169 offset:6976
	ds_read_b64_tr_b16 v[128:129], v169 offset:4704
	ds_read_b64_tr_b16 v[130:131], v169 offset:7008
	s_waitcnt vmcnt(15)
	ds_write_b128 v241, v[56:59]
	s_waitcnt vmcnt(14)
	ds_write_b128 v242, v[60:63]
	s_waitcnt vmcnt(13)
	ds_write_b128 v243, v[88:91]
	s_waitcnt vmcnt(12)
	ds_write_b128 v244, v[96:99]
	v_mfma_f32_16x16x32_bf16 v[56:59], v[48:51], v[4:7], 0
	v_mfma_f32_16x16x32_bf16 v[60:63], v[16:19], v[4:7], 0
	v_mfma_f32_16x16x32_bf16 v[16:19], v[16:19], v[12:15], 0
	v_mfma_f32_16x16x32_bf16 v[56:59], v[52:55], v[8:11], v[56:59]
	v_mfma_f32_16x16x32_bf16 v[60:63], v[20:23], v[8:11], v[60:63]
	v_mfma_f32_16x16x32_bf16 v[16:19], v[20:23], v[0:3], v[16:19]
	v_sub_u32_e32 v20, v195, v147
	v_add_u32_e32 v23, 1, v20
	s_nop 3
	v_mfma_f32_16x16x32_bf16 v[48:51], v[48:51], v[12:15], 0
	v_cmp_gt_u32_e64 s[0:1], v23, v146
	v_cmp_gt_u32_e32 vcc, v20, v146
	s_nop 0
	v_cndmask_b32_e64 v57, v57, v246, s[0:1]
	s_nop 0
	v_cndmask_b32_e32 v56, v56, v246, vcc
	v_mfma_f32_16x16x32_bf16 v[48:51], v[52:55], v[0:3], v[48:51]
	v_max_f32_e32 v22, v56, v57
	v_add_u32_e32 v23, 2, v20
	v_add_u32_e32 v52, 3, v20
	v_cmp_gt_u32_e64 s[22:23], v23, v146
	v_cmp_gt_u32_e64 s[24:25], v52, v146
	v_sub_u32_e32 v21, v195, v148
	v_cndmask_b32_e64 v58, v58, v246, s[22:23]
	v_cndmask_b32_e64 v59, v59, v246, s[24:25]
	v_max3_f32 v22, v22, v58, v59
	v_add_u32_e32 v23, 16, v20
	v_add_u32_e32 v52, 17, v20
	v_cmp_gt_u32_e64 s[26:27], v23, v146
	v_cmp_gt_u32_e64 s[28:29], v52, v146
	v_cmp_gt_u32_e64 s[38:39], v21, v145
	v_cndmask_b32_e64 v60, v60, v246, s[26:27]
	v_cndmask_b32_e64 v61, v61, v246, s[28:29]
	v_max3_f32 v22, v22, v60, v61
	v_add_u32_e32 v23, 18, v20
	v_add_u32_e32 v20, 19, v20
	v_cmp_gt_u32_e64 s[30:31], v23, v146
	v_cmp_gt_u32_e64 s[34:35], v20, v146
	v_add_u32_e32 v52, 3, v21
	v_cndmask_b32_e64 v62, v62, v246, s[30:31]
	v_cndmask_b32_e64 v63, v63, v246, s[34:35]
	v_max3_f32 v20, v22, v62, v63
	v_add_u32_e32 v23, 1, v21
	v_cmp_gt_u32_e64 s[40:41], v23, v145
	v_cndmask_b32_e64 v48, v48, v246, s[38:39]
	s_nop 0
	v_cndmask_b32_e64 v49, v49, v246, s[40:41]
	v_max_f32_e32 v22, v48, v49
	v_add_u32_e32 v23, 2, v21
	v_cmp_gt_u32_e64 s[42:43], v23, v145
	v_cmp_gt_u32_e64 s[44:45], v52, v145
	s_nop 0
	v_cndmask_b32_e64 v50, v50, v246, s[42:43]
	v_cndmask_b32_e64 v51, v51, v246, s[44:45]
	v_max3_f32 v22, v22, v50, v51
	v_add_u32_e32 v23, 16, v21
	v_add_u32_e32 v52, 17, v21
	v_cmp_gt_u32_e64 s[46:47], v23, v145
	v_cmp_gt_u32_e64 s[48:49], v52, v145
	s_nop 0
	v_cndmask_b32_e64 v16, v16, v246, s[46:47]
	v_cndmask_b32_e64 v17, v17, v246, s[48:49]
	v_max3_f32 v22, v22, v16, v17
	v_add_u32_e32 v23, 18, v21
	v_add_u32_e32 v21, 19, v21
	v_cmp_gt_u32_e64 s[50:51], v23, v145
	v_cmp_gt_u32_e64 s[52:53], v21, v145
	s_nop 0
	v_cndmask_b32_e64 v18, v18, v246, s[50:51]
	v_cndmask_b32_e64 v19, v19, v246, s[52:53]
	v_max3_f32 v21, v22, v18, v19
	v_mov_b32_e32 v22, v20
	s_nop 1
	v_permlane32_swap_b32_e32 v22, v20
	v_max_f32_e32 v20, v20, v22
	v_mov_b32_e32 v22, v21
	s_nop 1
	v_permlane32_swap_b32_e32 v22, v21
	v_max_f32_e32 v21, v21, v22
	v_mov_b32_e32 v22, v20
	s_nop 1
	v_permlane16_swap_b32_e32 v22, v20
	v_max3_f32 v149, v175, v20, v22
	v_sub_f32_e32 v20, v175, v149
	v_exp_f32_e32 v88, v20
	v_sub_f32_e32 v20, v56, v149
	v_sub_f32_e32 v56, v61, v149
	v_exp_f32_e32 v56, v56
	v_exp_f32_e32 v20, v20
	v_sub_f32_e32 v23, v57, v149
	v_exp_f32_e32 v23, v23
	v_sub_f32_e32 v53, v58, v149
	v_cndmask_b32_e64 v58, v56, 0, s[28:29]
	v_sub_f32_e32 v56, v62, v149
	v_mov_b32_e32 v22, v21
	v_exp_f32_e32 v53, v53
	v_sub_f32_e32 v54, v59, v149
	v_exp_f32_e32 v56, v56
	v_permlane16_swap_b32_e32 v22, v21
	v_exp_f32_e32 v54, v54
	v_sub_f32_e32 v55, v60, v149
	v_exp_f32_e32 v55, v55
	v_max_f32_e32 v21, v21, v22
	v_add_f32_e32 v22, v23, v20
	v_cndmask_b32_e64 v59, v56, 0, s[30:31]
	v_sub_f32_e32 v56, v63, v149
	v_add_f32_e32 v22, v53, v22
	v_exp_f32_e32 v56, v56
	v_add_f32_e32 v22, v54, v22
	v_add_f32_e32 v22, v55, v22
	v_add_f32_e32 v22, v58, v22
	v_max_f32_e32 v151, v181, v21
	v_add_f32_e32 v22, v59, v22
	v_cndmask_b32_e64 v60, v56, 0, s[34:35]
	v_cvt_pk_bf16_f32 v56, v20, v23
	v_sub_f32_e32 v20, v181, v151
	v_add_f32_e32 v150, v60, v22
	v_cvt_pk_bf16_f32 v59, v59, v60
	v_exp_f32_e32 v60, v20
	v_sub_f32_e32 v20, v48, v151
	v_exp_f32_e32 v20, v20
	v_sub_f32_e32 v22, v49, v151
	v_exp_f32_e32 v22, v22
	v_sub_f32_e32 v23, v50, v151
	v_exp_f32_e32 v23, v23
	v_sub_f32_e32 v48, v51, v151
	v_exp_f32_e32 v48, v48
	v_sub_f32_e32 v16, v16, v151
	v_exp_f32_e32 v16, v16
	v_sub_f32_e32 v17, v17, v151
	v_exp_f32_e32 v17, v17
	v_add_f32_e32 v21, v22, v20
	v_add_f32_e32 v21, v23, v21
	v_add_f32_e32 v21, v48, v21
	v_cndmask_b32_e64 v49, v16, 0, s[46:47]
	v_add_f32_e32 v16, v49, v21
	v_cndmask_b32_e64 v21, v17, 0, s[48:49]
	v_sub_f32_e32 v17, v18, v151
	v_exp_f32_e32 v17, v17
	v_add_f32_e32 v16, v21, v16
	v_cvt_pk_bf16_f32 v18, v49, v21
	v_cvt_pk_bf16_f32 v57, v53, v54
	v_cndmask_b32_e64 v50, v17, 0, s[50:51]
	v_sub_f32_e32 v17, v19, v151
	v_exp_f32_e32 v17, v17
	v_add_f32_e32 v16, v50, v16
	v_cvt_pk_bf16_f32 v58, v55, v58
	v_fmac_f32_e32 v150, v176, v88
	v_cndmask_b32_e64 v19, v17, 0, s[52:53]
	v_add_f32_e32 v175, v19, v16
	v_cvt_pk_bf16_f32 v16, v20, v22
	v_cvt_pk_bf16_f32 v17, v23, v48
	v_cvt_pk_bf16_f32 v19, v50, v19
	v_pk_mul_f32 v[50:51], v[86:87], v[60:61] op_sel_hi:[1,0]
	v_pk_mul_f32 v[48:49], v[84:85], v[60:61] op_sel_hi:[1,0]
	v_pk_mul_f32 v[22:23], v[82:83], v[88:89] op_sel_hi:[1,0]
	v_pk_mul_f32 v[20:21], v[80:81], v[88:89] op_sel_hi:[1,0]
	s_waitcnt lgkmcnt(10)
	v_mfma_f32_16x16x32_bf16 v[52:55], v[140:143], v[16:19], v[48:51]
	v_fmac_f32_e32 v175, v183, v60
	s_nop 1
	v_pk_mul_f32 v[50:51], v[106:107], v[88:89] op_sel_hi:[1,0]
	v_pk_mul_f32 v[48:49], v[104:105], v[88:89] op_sel_hi:[1,0]
	v_mfma_f32_16x16x32_bf16 v[20:23], v[140:143], v[56:59], v[20:23]
	s_waitcnt lgkmcnt(8)
	v_mfma_f32_16x16x32_bf16 v[104:107], v[136:139], v[56:59], v[48:51]
	s_nop 2
	v_mul_f32_e64 v50, v110, v60
	v_mul_f32_e64 v51, v111, v60
	v_pk_mul_f32 v[48:49], v[108:109], v[60:61] op_sel_hi:[1,0]
	s_nop 1
	v_mfma_f32_16x16x32_bf16 v[108:111], v[136:139], v[16:19], v[48:51]
	s_nop 2
	v_mul_f32_e64 v50, v114, v88
	v_mul_f32_e64 v51, v115, v88
	v_pk_mul_f32 v[48:49], v[112:113], v[88:89] op_sel_hi:[1,0]
	s_waitcnt lgkmcnt(6)
	s_nop 0
	v_mfma_f32_16x16x32_bf16 v[112:115], v[132:135], v[56:59], v[48:51]
	s_nop 2
	v_mul_f32_e64 v50, v118, v60
	v_mul_f32_e64 v51, v119, v60
	v_pk_mul_f32 v[48:49], v[116:117], v[60:61] op_sel_hi:[1,0]
	s_nop 1
	v_mfma_f32_16x16x32_bf16 v[116:119], v[132:135], v[16:19], v[48:51]
	s_nop 2
	v_mul_f32_e64 v50, v122, v88
	v_mul_f32_e64 v51, v123, v88
	v_pk_mul_f32 v[48:49], v[120:121], v[88:89] op_sel_hi:[1,0]
	s_waitcnt lgkmcnt(4)
	s_nop 0
	v_mfma_f32_16x16x32_bf16 v[120:123], v[128:131], v[56:59], v[48:51]
	v_add_u32_e32 v56, 0xffffff00, v206
	v_add_u32_e32 v56, s76, v56
	s_nop 0
	v_pk_mul_f32 v[50:51], v[126:127], v[60:61] op_sel_hi:[1,0]
	v_pk_mul_f32 v[48:49], v[124:125], v[60:61] op_sel_hi:[1,0]
	s_nop 1
	v_mfma_f32_16x16x32_bf16 v[124:127], v[128:131], v[16:19], v[48:51]
	v_add_u32_e32 v16, 0xffffff00, v204
	v_add_u32_e32 v16, s76, v16
	s_nop 0
	v_add_u32_e32 v48, 0xffffff00, v205
	v_add_u32_e32 v48, s76, v48
	v_med3_i32 v16, v16, 0, s75
	v_med3_i32 v48, v48, 0, s75
	v_med3_i32 v56, v56, 0, s75
	v_lshl_add_u32 v56, v56, 9, v152
	global_load_dwordx4 v[88:91], v56, s[98:99]
	v_add_u32_e32 v56, 0xffffff00, v207
	v_add_u32_e32 v56, s76, v56
	v_med3_i32 v56, v56, 0, s75
	v_lshl_add_u32 v56, v56, 9, v152
	global_load_dwordx4 v[96:99], v56, s[98:99]
	v_add_u32_e32 v56, s76, v208
	v_lshl_add_u32 v16, v16, 9, v152
	v_lshl_add_u32 v48, v48, 9, v152
	v_med3_i32 v56, v56, 0, s75
	v_lshl_add_u32 v56, v56, 9, v158
	global_load_dwordx4 v[16:19], v16, s[98:99]
	s_nop 0
	global_load_dwordx4 v[48:51], v48, s[98:99]
	s_nop 0
	global_load_dwordx4 v[84:87], v56, s[100:101]
	global_load_dwordx4 v[80:83], v56, s[100:101] offset:64
	v_or_b32_e32 v56, 0xffffff40, v209
	v_add_u32_e32 v56, s76, v56
	v_med3_i32 v56, v56, 0, s75
	v_lshl_add_u32 v56, v56, 9, v158
	global_load_dwordx4 v[60:63], v56, s[100:101]
	s_nop 0
	global_load_dwordx4 v[56:59], v56, s[100:101] offset:64
	ds_read_b64_tr_b16 v[142:143], v169 offset:2304
	ds_read_b64_tr_b16 v[140:141], v169
	ds_read_b64_tr_b16 v[136:137], v169 offset:32
	ds_read_b64_tr_b16 v[138:139], v169 offset:2336
	ds_read_b64_tr_b16 v[132:133], v169 offset:64
	ds_read_b64_tr_b16 v[134:135], v169 offset:2368
	ds_read_b64_tr_b16 v[128:129], v169 offset:96
	ds_read_b64_tr_b16 v[130:131], v169 offset:2400
	s_waitcnt vmcnt(15)
	ds_write_b128 v241, v[28:31] offset:4608
	s_waitcnt vmcnt(14)
	ds_write_b128 v242, v[44:47] offset:4608
	s_waitcnt vmcnt(13)
	ds_write_b128 v243, v[92:95] offset:4608
	s_waitcnt vmcnt(12)
	ds_write_b128 v244, v[100:103] offset:4608
	v_mfma_f32_16x16x32_bf16 v[28:31], v[76:79], v[4:7], 0
	v_mfma_f32_16x16x32_bf16 v[44:47], v[40:43], v[4:7], 0
	v_mfma_f32_16x16x32_bf16 v[40:43], v[40:43], v[12:15], 0
	v_mfma_f32_16x16x32_bf16 v[28:31], v[64:67], v[8:11], v[28:31]
	v_mfma_f32_16x16x32_bf16 v[44:47], v[32:35], v[8:11], v[44:47]
	v_mfma_f32_16x16x32_bf16 v[32:35], v[32:35], v[0:3], v[40:43]
	s_nop 4
	v_sub_u32_e32 v40, v210, v147
	v_mfma_f32_16x16x32_bf16 v[76:79], v[76:79], v[12:15], 0
	v_add_u32_e32 v43, 1, v40
	v_cmp_gt_u32_e64 s[0:1], v43, v146
	v_cmp_gt_u32_e32 vcc, v40, v146
	s_nop 0
	v_cndmask_b32_e64 v29, v29, v246, s[0:1]
	s_nop 0
	v_cndmask_b32_e32 v28, v28, v246, vcc
	v_mfma_f32_16x16x32_bf16 v[64:67], v[64:67], v[0:3], v[76:79]
	v_max_f32_e32 v42, v28, v29
	v_add_u32_e32 v43, 2, v40
	v_cmp_gt_u32_e64 s[22:23], v43, v146
	v_add_u32_e32 v76, 3, v40
	v_cmp_gt_u32_e64 s[24:25], v76, v146
	v_cndmask_b32_e64 v30, v30, v246, s[22:23]
	v_sub_u32_e32 v41, v210, v148
	v_cndmask_b32_e64 v31, v31, v246, s[24:25]
	v_max3_f32 v42, v42, v30, v31
	v_add_u32_e32 v43, 16, v40
	v_add_u32_e32 v76, 17, v40
	v_cmp_gt_u32_e64 s[26:27], v43, v146
	v_cmp_gt_u32_e64 s[28:29], v76, v146
	v_cmp_gt_u32_e64 s[38:39], v41, v145
	v_cndmask_b32_e64 v44, v44, v246, s[26:27]
	v_cndmask_b32_e64 v45, v45, v246, s[28:29]
	v_max3_f32 v42, v42, v44, v45
	v_add_u32_e32 v43, 18, v40
	v_add_u32_e32 v40, 19, v40
	v_cmp_gt_u32_e64 s[30:31], v43, v146
	v_cmp_gt_u32_e64 s[34:35], v40, v146
	v_add_u32_e32 v76, 3, v41
	v_cndmask_b32_e64 v46, v46, v246, s[30:31]
	v_cndmask_b32_e64 v47, v47, v246, s[34:35]
	v_max3_f32 v40, v42, v46, v47
	v_add_u32_e32 v43, 1, v41
	v_cmp_gt_u32_e64 s[40:41], v43, v145
	v_cndmask_b32_e64 v64, v64, v246, s[38:39]
	s_nop 0
	v_cndmask_b32_e64 v65, v65, v246, s[40:41]
	v_max_f32_e32 v42, v64, v65
	v_add_u32_e32 v43, 2, v41
	v_cmp_gt_u32_e64 s[42:43], v43, v145
	v_cmp_gt_u32_e64 s[44:45], v76, v145
	s_nop 0
	v_cndmask_b32_e64 v66, v66, v246, s[42:43]
	v_cndmask_b32_e64 v67, v67, v246, s[44:45]
	v_max3_f32 v42, v42, v66, v67
	v_add_u32_e32 v43, 16, v41
	v_add_u32_e32 v76, 17, v41
	v_cmp_gt_u32_e64 s[46:47], v43, v145
	v_cmp_gt_u32_e64 s[48:49], v76, v145
	s_nop 0
	v_cndmask_b32_e64 v32, v32, v246, s[46:47]
	v_cndmask_b32_e64 v33, v33, v246, s[48:49]
	v_max3_f32 v42, v42, v32, v33
	v_add_u32_e32 v43, 18, v41
	v_add_u32_e32 v41, 19, v41
	v_cmp_gt_u32_e64 s[50:51], v43, v145
	v_cmp_gt_u32_e64 s[52:53], v41, v145
	s_nop 0
	v_cndmask_b32_e64 v34, v34, v246, s[50:51]
	v_cndmask_b32_e64 v35, v35, v246, s[52:53]
	v_max3_f32 v41, v42, v34, v35
	v_mov_b32_e32 v42, v40
	s_nop 1
	v_permlane32_swap_b32_e32 v42, v40
	v_max_f32_e32 v40, v40, v42
	v_mov_b32_e32 v42, v41
	s_nop 1
	v_permlane32_swap_b32_e32 v42, v41
	v_max_f32_e32 v41, v41, v42
	v_mov_b32_e32 v42, v40
	s_nop 1
	v_permlane16_swap_b32_e32 v42, v40
	v_max3_f32 v176, v149, v40, v42
	v_sub_f32_e32 v28, v28, v176
	v_mov_b32_e32 v42, v41
	v_exp_f32_e32 v28, v28
	v_sub_f32_e32 v29, v29, v176
	v_permlane16_swap_b32_e32 v42, v41
	v_exp_f32_e32 v29, v29
	v_sub_f32_e32 v30, v30, v176
	v_exp_f32_e32 v30, v30
	v_sub_f32_e32 v31, v31, v176
	v_max_f32_e32 v41, v41, v42
	v_exp_f32_e32 v31, v31
	v_sub_f32_e32 v42, v44, v176
	v_sub_f32_e32 v40, v149, v176
	v_exp_f32_e32 v42, v42
	v_sub_f32_e32 v43, v45, v176
	v_exp_f32_e32 v76, v40
	v_exp_f32_e32 v43, v43
	v_sub_f32_e32 v44, v46, v176
	v_add_f32_e32 v40, v29, v28
	v_exp_f32_e32 v44, v44
	v_sub_f32_e32 v45, v47, v176
	v_add_f32_e32 v40, v30, v40
	v_exp_f32_e32 v45, v45
	v_add_f32_e32 v40, v31, v40
	v_add_f32_e32 v40, v42, v40
	v_add_f32_e32 v40, v43, v40
	v_add_f32_e32 v40, v44, v40
	v_add_f32_e32 v149, v45, v40
	v_fmac_f32_e32 v149, v150, v76
	v_max_f32_e32 v150, v151, v41
	v_sub_f32_e32 v40, v151, v150
	v_cvt_pk_bf16_f32 v28, v28, v29
	v_cvt_pk_bf16_f32 v29, v30, v31
	v_cvt_pk_bf16_f32 v31, v44, v45
	v_exp_f32_e32 v44, v40
	v_sub_f32_e32 v40, v64, v150
	v_cvt_pk_bf16_f32 v30, v42, v43
	v_exp_f32_e32 v40, v40
	v_sub_f32_e32 v42, v65, v150
	v_exp_f32_e32 v42, v42
	v_sub_f32_e32 v43, v66, v150
	v_exp_f32_e32 v43, v43
	v_sub_f32_e32 v45, v67, v150
	v_exp_f32_e32 v45, v45
	v_sub_f32_e32 v32, v32, v150
	v_exp_f32_e32 v32, v32
	v_sub_f32_e32 v33, v33, v150
	v_exp_f32_e32 v33, v33
	v_add_f32_e32 v41, v42, v40
	v_add_f32_e32 v41, v43, v41
	v_add_f32_e32 v41, v45, v41
	v_cndmask_b32_e64 v46, v32, 0, s[46:47]
	v_add_f32_e32 v32, v46, v41
	v_cndmask_b32_e64 v41, v33, 0, s[48:49]
	v_sub_f32_e32 v33, v34, v150
	v_exp_f32_e32 v33, v33
	v_add_f32_e32 v32, v41, v32
	v_pk_mul_f32 v[22:23], v[22:23], v[76:77] op_sel_hi:[1,0]
	v_pk_mul_f32 v[20:21], v[20:21], v[76:77] op_sel_hi:[1,0]
	v_cndmask_b32_e64 v47, v33, 0, s[50:51]
	v_sub_f32_e32 v33, v35, v150
	v_exp_f32_e32 v33, v33
	v_add_f32_e32 v32, v47, v32
	v_cvt_pk_bf16_f32 v34, v46, v41
	v_cndmask_b32_e64 v35, v33, 0, s[52:53]
	v_add_f32_e32 v151, v35, v32
	v_cvt_pk_bf16_f32 v32, v40, v42
	v_cvt_pk_bf16_f32 v33, v43, v45
	v_cvt_pk_bf16_f32 v35, v47, v35
	s_waitcnt lgkmcnt(10)
	v_mfma_f32_16x16x32_bf16 v[40:43], v[140:143], v[28:31], v[20:23]
	v_fmac_f32_e32 v151, v175, v44
	s_nop 1
	v_pk_mul_f32 v[22:23], v[54:55], v[44:45] op_sel_hi:[1,0]
	v_pk_mul_f32 v[20:21], v[52:53], v[44:45] op_sel_hi:[1,0]
	s_nop 1
	v_mfma_f32_16x16x32_bf16 v[92:95], v[140:143], v[32:35], v[20:23]
	s_nop 2
	v_mul_f32_e64 v22, v106, v76
	v_mul_f32_e64 v23, v107, v76
	v_pk_mul_f32 v[20:21], v[104:105], v[76:77] op_sel_hi:[1,0]
	s_waitcnt lgkmcnt(8)
	s_nop 0
	v_mfma_f32_16x16x32_bf16 v[104:107], v[136:139], v[28:31], v[20:23]
	s_nop 2
	v_mul_f32_e64 v22, v110, v44
	v_mul_f32_e64 v23, v111, v44
	v_pk_mul_f32 v[20:21], v[108:109], v[44:45] op_sel_hi:[1,0]
	s_nop 1
	v_mfma_f32_16x16x32_bf16 v[108:111], v[136:139], v[32:35], v[20:23]
	s_nop 2
	v_mul_f32_e64 v22, v114, v76
	v_mul_f32_e64 v23, v115, v76
	v_pk_mul_f32 v[20:21], v[112:113], v[76:77] op_sel_hi:[1,0]
	s_waitcnt lgkmcnt(6)
	s_nop 0
	v_mfma_f32_16x16x32_bf16 v[112:115], v[132:135], v[28:31], v[20:23]
	s_nop 2
	v_mul_f32_e64 v22, v118, v44
	v_mul_f32_e64 v23, v119, v44
	v_pk_mul_f32 v[20:21], v[116:117], v[44:45] op_sel_hi:[1,0]
	s_nop 1
	v_mfma_f32_16x16x32_bf16 v[116:119], v[132:135], v[32:35], v[20:23]
	s_nop 2
	v_mul_f32_e64 v22, v122, v76
	v_mul_f32_e64 v23, v123, v76
	v_pk_mul_f32 v[20:21], v[120:121], v[76:77] op_sel_hi:[1,0]
	s_waitcnt lgkmcnt(4)
	s_nop 0
	v_mfma_f32_16x16x32_bf16 v[120:123], v[128:131], v[28:31], v[20:23]
	s_nop 2
	v_mul_f32_e64 v22, v126, v44
	v_mul_f32_e64 v23, v127, v44
	v_pk_mul_f32 v[20:21], v[124:125], v[44:45] op_sel_hi:[1,0]
	s_nop 1
	v_mfma_f32_16x16x32_bf16 v[124:127], v[128:131], v[32:35], v[20:23]
	s_nop 2
	v_add_u32_e32 v20, 0xffffff80, v204
	v_add_u32_e32 v20, s76, v20
	v_med3_i32 v20, v20, 0, s75
	v_lshl_add_u32 v20, v20, 9, v152
	global_load_dwordx4 v[32:35], v20, s[98:99]
	v_add_u32_e32 v20, 0xffffff80, v205
	v_add_u32_e32 v20, s76, v20
	v_med3_i32 v20, v20, 0, s75
	v_lshl_add_u32 v20, v20, 9, v152
	global_load_dwordx4 v[64:67], v20, s[98:99]
	v_add_u32_e32 v20, 0xffffff80, v206
	v_add_u32_e32 v20, s76, v20
	v_med3_i32 v20, v20, 0, s75
	v_lshl_add_u32 v20, v20, 9, v152
	global_load_dwordx4 v[76:79], v20, s[98:99]
	v_add_u32_e32 v20, 0xffffff80, v207
	v_add_u32_e32 v20, s76, v20
	v_med3_i32 v20, v20, 0, s75
	v_lshl_add_u32 v20, v20, 9, v152
	global_load_dwordx4 v[100:103], v20, s[98:99]
	v_or_b32_e32 v20, 0xffffff80, v209
	v_add_u32_e32 v20, s76, v20
	v_med3_i32 v20, v20, 0, s75
	v_lshl_add_u32 v20, v20, 9, v158
	global_load_dwordx4 v[52:55], v20, s[100:101]
	global_load_dwordx4 v[44:47], v20, s[100:101] offset:64
	v_add_u32_e32 v20, s76, v211
	v_med3_i32 v20, v20, 0, s75
	v_lshl_add_u32 v20, v20, 9, v158
	global_load_dwordx4 v[28:31], v20, s[100:101]
	s_nop 0
	global_load_dwordx4 v[20:23], v20, s[100:101] offset:64
	ds_read_b64_tr_b16 v[142:143], v169 offset:6912
	ds_read_b64_tr_b16 v[140:141], v169 offset:4608
	ds_read_b64_tr_b16 v[136:137], v169 offset:4640
	ds_read_b64_tr_b16 v[138:139], v169 offset:6944
	ds_read_b64_tr_b16 v[132:133], v169 offset:4672
	ds_read_b64_tr_b16 v[134:135], v169 offset:6976
	ds_read_b64_tr_b16 v[128:129], v169 offset:4704
	ds_read_b64_tr_b16 v[130:131], v169 offset:7008
	s_waitcnt vmcnt(13)
	ds_write_b128 v241, v[16:19]
	s_waitcnt vmcnt(12)
	ds_write_b128 v242, v[48:51]
	ds_write_b128 v243, v[88:91]
	ds_write_b128 v244, v[96:99]
	v_mfma_f32_16x16x32_bf16 v[16:19], v[72:75], v[4:7], 0
	v_mfma_f32_16x16x32_bf16 v[48:51], v[36:39], v[4:7], 0
	v_mfma_f32_16x16x32_bf16 v[36:39], v[36:39], v[12:15], 0
	v_mfma_f32_16x16x32_bf16 v[16:19], v[68:71], v[8:11], v[16:19]
	v_mfma_f32_16x16x32_bf16 v[48:51], v[24:27], v[8:11], v[48:51]
	v_mfma_f32_16x16x32_bf16 v[24:27], v[24:27], v[0:3], v[36:39]
	s_nop 4
	v_sub_u32_e32 v36, v212, v147
	v_mfma_f32_16x16x32_bf16 v[72:75], v[72:75], v[12:15], 0
	v_add_u32_e32 v39, 1, v36
	v_cmp_gt_u32_e64 s[0:1], v39, v146
	v_cmp_gt_u32_e32 vcc, v36, v146
	s_nop 0
	v_cndmask_b32_e64 v17, v17, v246, s[0:1]
	s_nop 0
	v_cndmask_b32_e32 v16, v16, v246, vcc
	v_mfma_f32_16x16x32_bf16 v[68:71], v[68:71], v[0:3], v[72:75]
	v_max_f32_e32 v38, v16, v17
	v_add_u32_e32 v39, 2, v36
	v_cmp_gt_u32_e64 s[22:23], v39, v146
	v_add_u32_e32 v72, 3, v36
	v_cmp_gt_u32_e64 s[24:25], v72, v146
	v_cndmask_b32_e64 v18, v18, v246, s[22:23]
	v_sub_u32_e32 v37, v212, v148
	v_cndmask_b32_e64 v19, v19, v246, s[24:25]
	v_max3_f32 v38, v38, v18, v19
	v_add_u32_e32 v39, 16, v36
	v_add_u32_e32 v72, 17, v36
	v_cmp_gt_u32_e64 s[26:27], v39, v146
	v_cmp_gt_u32_e64 s[28:29], v72, v146
	v_cmp_gt_u32_e64 s[38:39], v37, v145
	v_cndmask_b32_e64 v48, v48, v246, s[26:27]
	v_cndmask_b32_e64 v49, v49, v246, s[28:29]
	v_max3_f32 v38, v38, v48, v49
	v_add_u32_e32 v39, 18, v36
	v_add_u32_e32 v36, 19, v36
	v_cmp_gt_u32_e64 s[30:31], v39, v146
	v_cmp_gt_u32_e64 s[34:35], v36, v146
	v_add_u32_e32 v72, 3, v37
	v_cndmask_b32_e64 v50, v50, v246, s[30:31]
	v_cndmask_b32_e64 v51, v51, v246, s[34:35]
	v_max3_f32 v36, v38, v50, v51
	v_add_u32_e32 v39, 1, v37
	v_cmp_gt_u32_e64 s[40:41], v39, v145
	v_cndmask_b32_e64 v68, v68, v246, s[38:39]
	s_nop 0
	v_cndmask_b32_e64 v69, v69, v246, s[40:41]
	v_max_f32_e32 v38, v68, v69
	v_add_u32_e32 v39, 2, v37
	v_cmp_gt_u32_e64 s[42:43], v39, v145
	v_cmp_gt_u32_e64 s[44:45], v72, v145
	s_nop 0
	v_cndmask_b32_e64 v70, v70, v246, s[42:43]
	v_cndmask_b32_e64 v71, v71, v246, s[44:45]
	v_max3_f32 v38, v38, v70, v71
	v_add_u32_e32 v39, 16, v37
	v_add_u32_e32 v72, 17, v37
	v_cmp_gt_u32_e64 s[46:47], v39, v145
	v_cmp_gt_u32_e64 s[48:49], v72, v145
	s_nop 0
	v_cndmask_b32_e64 v24, v24, v246, s[46:47]
	v_cndmask_b32_e64 v25, v25, v246, s[48:49]
	v_max3_f32 v38, v38, v24, v25
	v_add_u32_e32 v39, 18, v37
	v_add_u32_e32 v37, 19, v37
	v_cmp_gt_u32_e64 s[50:51], v39, v145
	v_cmp_gt_u32_e64 s[52:53], v37, v145
	s_nop 0
	v_cndmask_b32_e64 v26, v26, v246, s[50:51]
	v_cndmask_b32_e64 v27, v27, v246, s[52:53]
	v_max3_f32 v37, v38, v26, v27
	v_mov_b32_e32 v38, v36
	s_nop 1
	v_permlane32_swap_b32_e32 v38, v36
	v_max_f32_e32 v36, v36, v38
	v_mov_b32_e32 v38, v37
	s_nop 1
	v_permlane32_swap_b32_e32 v38, v37
	v_max_f32_e32 v37, v37, v38
	v_mov_b32_e32 v38, v36
	s_nop 1
	v_permlane16_swap_b32_e32 v38, v36
	v_max3_f32 v145, v176, v36, v38
	v_sub_f32_e32 v16, v16, v145
	v_mov_b32_e32 v38, v37
	v_exp_f32_e32 v16, v16
	v_sub_f32_e32 v17, v17, v145
	v_permlane16_swap_b32_e32 v38, v37
	v_exp_f32_e32 v17, v17
	v_sub_f32_e32 v18, v18, v145
	v_exp_f32_e32 v18, v18
	v_sub_f32_e32 v19, v19, v145
	v_max_f32_e32 v37, v37, v38
	v_exp_f32_e32 v19, v19
	v_sub_f32_e32 v38, v48, v145
	v_sub_f32_e32 v36, v176, v145
	v_exp_f32_e32 v38, v38
	v_sub_f32_e32 v39, v49, v145
	v_exp_f32_e32 v88, v36
	v_exp_f32_e32 v39, v39
	v_sub_f32_e32 v48, v50, v145
	v_add_f32_e32 v36, v17, v16
	v_exp_f32_e32 v48, v48
	v_sub_f32_e32 v49, v51, v145
	v_add_f32_e32 v36, v18, v36
	v_exp_f32_e32 v49, v49
	v_add_f32_e32 v36, v19, v36
	v_add_f32_e32 v36, v38, v36
	v_add_f32_e32 v36, v39, v36
	v_add_f32_e32 v36, v48, v36
	v_max_f32_e32 v147, v150, v37
	v_add_f32_e32 v146, v49, v36
	v_sub_f32_e32 v36, v150, v147
	v_cvt_pk_bf16_f32 v16, v16, v17
	v_cvt_pk_bf16_f32 v17, v18, v19
	v_cvt_pk_bf16_f32 v19, v48, v49
	v_exp_f32_e32 v48, v36
	v_sub_f32_e32 v36, v68, v147
	v_cvt_pk_bf16_f32 v18, v38, v39
	v_exp_f32_e32 v36, v36
	v_sub_f32_e32 v38, v69, v147
	v_exp_f32_e32 v38, v38
	v_sub_f32_e32 v39, v70, v147
	v_exp_f32_e32 v39, v39
	v_sub_f32_e32 v49, v71, v147
	v_exp_f32_e32 v49, v49
	v_sub_f32_e32 v24, v24, v147
	v_exp_f32_e32 v24, v24
	v_sub_f32_e32 v25, v25, v147
	v_exp_f32_e32 v25, v25
	v_add_f32_e32 v37, v38, v36
	v_add_f32_e32 v37, v39, v37
	v_add_f32_e32 v37, v49, v37
	v_cndmask_b32_e64 v50, v24, 0, s[46:47]
	v_add_f32_e32 v24, v50, v37
	v_cndmask_b32_e64 v37, v25, 0, s[48:49]
	v_sub_f32_e32 v25, v26, v147
	v_exp_f32_e32 v25, v25
	v_add_f32_e32 v24, v37, v24
	v_cvt_pk_bf16_f32 v26, v50, v37
	v_cmp_lt_i32_e32 vcc, -1, v184
	v_cndmask_b32_e64 v51, v25, 0, s[50:51]
	v_sub_f32_e32 v25, v27, v147
	v_exp_f32_e32 v25, v25
	v_add_f32_e32 v24, v51, v24
	v_fmac_f32_e32 v146, v149, v88
	s_add_i32 s0, s76, 0xffffff00
	v_cndmask_b32_e64 v27, v25, 0, s[52:53]
	v_add_f32_e32 v183, v27, v24
	v_cvt_pk_bf16_f32 v24, v36, v38
	v_cvt_pk_bf16_f32 v25, v39, v49
	v_cvt_pk_bf16_f32 v27, v51, v27
	v_pk_mul_f32 v[38:39], v[42:43], v[88:89] op_sel_hi:[1,0]
	v_pk_mul_f32 v[36:37], v[40:41], v[88:89] op_sel_hi:[1,0]
	v_pk_mul_f32 v[42:43], v[94:95], v[48:49] op_sel_hi:[1,0]
	v_pk_mul_f32 v[40:41], v[92:93], v[48:49] op_sel_hi:[1,0]
	s_waitcnt lgkmcnt(10)
	v_mfma_f32_16x16x32_bf16 v[36:39], v[140:143], v[16:19], v[36:39]
	v_fmac_f32_e32 v183, v151, v48
	s_min_i32 s1, s0, 0
	s_sub_i32 s1, 3, s1
	v_mfma_f32_16x16x32_bf16 v[68:71], v[140:143], v[24:27], v[40:43]
	s_ashr_i32 s1, s1, 2
	s_sub_i32 s22, 0x200, s76
	s_sub_i32 s0, s75, s0
	v_pk_mul_f32 v[42:43], v[106:107], v[88:89] op_sel_hi:[1,0]
	v_pk_mul_f32 v[40:41], v[104:105], v[88:89] op_sel_hi:[1,0]
	s_ashr_i32 s0, s0, 2
	s_cmp_lt_i32 s76, 0
	s_waitcnt lgkmcnt(8)
	v_mfma_f32_16x16x32_bf16 v[72:75], v[136:139], v[16:19], v[40:43]
	s_nop 2
	v_mul_f32_e64 v42, v110, v48
	v_mul_f32_e64 v43, v111, v48
	v_pk_mul_f32 v[40:41], v[108:109], v[48:49] op_sel_hi:[1,0]
	s_nop 1
	v_mfma_f32_16x16x32_bf16 v[104:107], v[136:139], v[24:27], v[40:43]
	s_nop 2
	v_mul_f32_e64 v42, v114, v88
	v_mul_f32_e64 v43, v115, v88
	v_pk_mul_f32 v[40:41], v[112:113], v[88:89] op_sel_hi:[1,0]
	s_waitcnt lgkmcnt(6)
	s_nop 0
	v_mfma_f32_16x16x32_bf16 v[108:111], v[132:135], v[16:19], v[40:43]
	s_nop 2
	v_mul_f32_e64 v42, v118, v48
	v_mul_f32_e64 v43, v119, v48
	v_pk_mul_f32 v[40:41], v[116:117], v[48:49] op_sel_hi:[1,0]
	s_nop 1
	v_mfma_f32_16x16x32_bf16 v[112:115], v[132:135], v[24:27], v[40:43]
	s_nop 2
	v_mul_f32_e64 v42, v122, v88
	v_mul_f32_e64 v43, v123, v88
	v_pk_mul_f32 v[40:41], v[120:121], v[88:89] op_sel_hi:[1,0]
	s_waitcnt lgkmcnt(4)
	s_nop 0
	v_mfma_f32_16x16x32_bf16 v[116:119], v[128:131], v[16:19], v[40:43]
	v_mul_f32_e64 v18, v126, v48
	v_mul_f32_e64 v19, v127, v48
	v_pk_mul_f32 v[16:17], v[124:125], v[48:49] op_sel_hi:[1,0]
	s_nop 1
	v_mfma_f32_16x16x32_bf16 v[128:131], v[128:131], v[24:27], v[16:19]
	s_nop 2
	v_min_i32_e32 v16, s75, v184
	v_cndmask_b32_e32 v16, 0, v16, vcc
	v_lshl_add_u32 v16, v16, 9, v152
	global_load_dwordx4 v[88:91], v16, s[98:99]
	v_med3_i32 v16, v185, 0, s75
	v_lshl_add_u32 v16, v16, 9, v152
	global_load_dwordx4 v[92:95], v16, s[98:99]
	v_med3_i32 v16, v186, 0, s75
	v_lshl_add_u32 v16, v16, 9, v152
	global_load_dwordx4 v[120:123], v16, s[98:99]
	v_med3_i32 v16, v188, 0, s75
	v_lshl_add_u32 v16, v16, 9, v152
	global_load_dwordx4 v[124:127], v16, s[98:99]
	v_add_u32_e32 v16, s76, v209
	v_med3_i32 v16, v16, 0, s75
	v_lshl_add_u32 v16, v16, 9, v158
	global_load_dwordx4 v[48:51], v16, s[100:101]
	global_load_dwordx4 v[40:43], v16, s[100:101] offset:64
	v_or_b32_e32 v16, 64, v209
	v_add_u32_e32 v16, s76, v16
	v_med3_i32 v16, v16, 0, s75
	v_lshl_add_u32 v16, v16, 9, v158
	global_load_dwordx4 v[24:27], v16, s[100:101]
	s_nop 0
	global_load_dwordx4 v[16:19], v16, s[100:101] offset:64
	ds_read_b64_tr_b16 v[98:99], v169 offset:2304
	ds_read_b64_tr_b16 v[96:97], v169
	ds_read_b64_tr_b16 v[140:141], v169 offset:32
	ds_read_b64_tr_b16 v[142:143], v169 offset:2336
	ds_read_b64_tr_b16 v[136:137], v169 offset:64
	ds_read_b64_tr_b16 v[138:139], v169 offset:2368
	ds_read_b64_tr_b16 v[132:133], v169 offset:96
	ds_read_b64_tr_b16 v[134:135], v169 offset:2400
	s_waitcnt vmcnt(15)
	ds_write_b128 v241, v[32:35] offset:4608
	s_waitcnt vmcnt(14)
	ds_write_b128 v242, v[64:67] offset:4608
	s_waitcnt vmcnt(13)
	ds_write_b128 v243, v[76:79] offset:4608
	s_waitcnt vmcnt(12)
	ds_write_b128 v244, v[100:103] offset:4608
	v_mfma_f32_16x16x32_bf16 v[64:67], v[60:63], v[4:7], 0
	v_mfma_f32_16x16x32_bf16 v[60:63], v[60:63], v[12:15], 0
	v_mfma_f32_16x16x32_bf16 v[32:35], v[84:87], v[4:7], 0
	v_mfma_f32_16x16x32_bf16 v[64:67], v[56:59], v[8:11], v[64:67]
	v_mfma_f32_16x16x32_bf16 v[56:59], v[56:59], v[0:3], v[60:63]
	s_nop 4
	v_ashrrev_i32_e32 v60, 2, v250
	v_max_i32_e32 v176, s1, v60
	v_add_u32_e32 v60, s22, v251
	v_ashrrev_i32_e32 v60, 2, v60
	v_min3_i32 v60, v60, s0, v247
	v_mfma_f32_16x16x32_bf16 v[32:35], v[80:83], v[8:11], v[32:35]
	v_sub_u32_e32 v175, v60, v176
	v_ashrrev_i32_e32 v60, 2, v249
	v_max_i32_e32 v181, s1, v60
	v_add_u32_e32 v60, s22, v144
	v_sub_u32_e32 v61, v154, v176
	v_ashrrev_i32_e32 v60, 2, v60
	v_mfma_f32_16x16x32_bf16 v[76:79], v[84:87], v[12:15], 0
	v_min3_i32 v60, v60, s0, v247
	v_add_u32_e32 v63, 1, v61
	v_sub_u32_e32 v252, v60, v181
	v_cmp_gt_u32_e64 s[0:1], v63, v175
	v_cmp_gt_u32_e32 vcc, v61, v175
	s_nop 0
	v_cndmask_b32_e64 v33, v33, v246, s[0:1]
	s_nop 0
	v_cndmask_b32_e32 v32, v32, v246, vcc
	v_mfma_f32_16x16x32_bf16 v[76:79], v[80:83], v[0:3], v[76:79]
	v_max_f32_e32 v60, v32, v33
	v_add_u32_e32 v63, 2, v61
	v_add_u32_e32 v80, 3, v61
	v_cmp_gt_u32_e64 s[22:23], v63, v175
	v_cmp_gt_u32_e64 s[24:25], v80, v175
	v_sub_u32_e32 v62, v154, v181
	v_cndmask_b32_e64 v34, v34, v246, s[22:23]
	v_cndmask_b32_e64 v35, v35, v246, s[24:25]
	v_max3_f32 v60, v60, v34, v35
	v_add_u32_e32 v63, 16, v61
	v_add_u32_e32 v80, 17, v61
	v_cmp_gt_u32_e64 s[26:27], v63, v175
	v_cmp_gt_u32_e64 s[28:29], v80, v175
	v_cmp_gt_u32_e64 s[38:39], v62, v252
	v_cndmask_b32_e64 v64, v64, v246, s[26:27]
	v_cndmask_b32_e64 v65, v65, v246, s[28:29]
	v_max3_f32 v60, v60, v64, v65
	v_add_u32_e32 v63, 18, v61
	v_add_u32_e32 v61, 19, v61
	v_cmp_gt_u32_e64 s[30:31], v63, v175
	v_cmp_gt_u32_e64 s[34:35], v61, v175
	v_add_u32_e32 v80, 3, v62
	v_cndmask_b32_e64 v66, v66, v246, s[30:31]
	v_cndmask_b32_e64 v67, v67, v246, s[34:35]
	v_max3_f32 v60, v60, v66, v67
	v_add_u32_e32 v63, 1, v62
	v_cmp_gt_u32_e64 s[40:41], v63, v252
	v_cndmask_b32_e64 v76, v76, v246, s[38:39]
	s_nop 0
	v_cndmask_b32_e64 v77, v77, v246, s[40:41]
	v_max_f32_e32 v61, v76, v77
	v_add_u32_e32 v63, 2, v62
	v_cmp_gt_u32_e64 s[42:43], v63, v252
	v_cmp_gt_u32_e64 s[44:45], v80, v252
	s_nop 0
	v_cndmask_b32_e64 v78, v78, v246, s[42:43]
	v_cndmask_b32_e64 v79, v79, v246, s[44:45]
	v_max3_f32 v61, v61, v78, v79
	v_add_u32_e32 v63, 16, v62
	v_add_u32_e32 v80, 17, v62
	v_cmp_gt_u32_e64 s[46:47], v63, v252
	v_cmp_gt_u32_e64 s[48:49], v80, v252
	s_nop 0
	v_cndmask_b32_e64 v56, v56, v246, s[46:47]
	v_cndmask_b32_e64 v57, v57, v246, s[48:49]
	v_max3_f32 v61, v61, v56, v57
	v_add_u32_e32 v63, 18, v62
	v_add_u32_e32 v62, 19, v62
	v_cmp_gt_u32_e64 s[50:51], v63, v252
	v_cmp_gt_u32_e64 s[52:53], v62, v252
	s_nop 0
	v_cndmask_b32_e64 v58, v58, v246, s[50:51]
	v_cndmask_b32_e64 v59, v59, v246, s[52:53]
	v_max3_f32 v61, v61, v58, v59
	v_mov_b32_e32 v62, v60
	s_nop 1
	v_permlane32_swap_b32_e32 v62, v60
	v_max_f32_e32 v60, v60, v62
	v_mov_b32_e32 v62, v61
	s_nop 1
	v_permlane32_swap_b32_e32 v62, v61
	v_max_f32_e32 v61, v61, v62
	v_mov_b32_e32 v62, v60
	s_nop 1
	v_permlane16_swap_b32_e32 v62, v60
	v_max3_f32 v148, v145, v60, v62
	v_sub_f32_e32 v32, v32, v148
	v_exp_f32_e32 v32, v32
	v_sub_f32_e32 v33, v33, v148
	v_exp_f32_e32 v33, v33
	v_sub_f32_e32 v34, v34, v148
	v_mov_b32_e32 v62, v61
	v_exp_f32_e32 v34, v34
	v_sub_f32_e32 v35, v35, v148
	v_permlane16_swap_b32_e32 v62, v61
	v_exp_f32_e32 v35, v35
	v_sub_f32_e32 v63, v64, v148
	v_exp_f32_e32 v63, v63
	v_sub_f32_e32 v64, v65, v148
	v_max_f32_e32 v61, v61, v62
	v_exp_f32_e32 v64, v64
	v_sub_f32_e32 v65, v66, v148
	v_add_f32_e32 v62, v33, v32
	v_exp_f32_e32 v65, v65
	v_sub_f32_e32 v66, v67, v148
	v_add_f32_e32 v62, v34, v62
	v_exp_f32_e32 v66, v66
	v_add_f32_e32 v62, v35, v62
	v_add_f32_e32 v62, v63, v62
	v_add_f32_e32 v62, v64, v62
	v_max_f32_e32 v150, v147, v61
	v_add_f32_e32 v62, v65, v62
	v_sub_f32_e32 v61, v147, v150
	v_add_f32_e32 v149, v66, v62
	v_exp_f32_e32 v62, v61
	v_sub_f32_e32 v61, v76, v150
	v_cvt_pk_bf16_f32 v32, v32, v33
	v_cvt_pk_bf16_f32 v33, v34, v35
	v_cvt_pk_bf16_f32 v34, v63, v64
	v_exp_f32_e32 v61, v61
	v_sub_f32_e32 v64, v77, v150
	v_cvt_pk_bf16_f32 v35, v65, v66
	v_exp_f32_e32 v64, v64
	v_sub_f32_e32 v65, v78, v150
	v_exp_f32_e32 v65, v65
	v_sub_f32_e32 v66, v79, v150
	v_exp_f32_e32 v66, v66
	v_sub_f32_e32 v56, v56, v150
	v_exp_f32_e32 v56, v56
	v_sub_f32_e32 v57, v57, v150
	v_exp_f32_e32 v57, v57
	v_add_f32_e32 v63, v64, v61
	v_add_f32_e32 v63, v65, v63
	v_add_f32_e32 v63, v66, v63
	v_cndmask_b32_e64 v67, v56, 0, s[46:47]
	v_add_f32_e32 v56, v67, v63
	v_cndmask_b32_e64 v63, v57, 0, s[48:49]
	v_sub_f32_e32 v57, v58, v150
	v_exp_f32_e32 v57, v57
	v_sub_f32_e32 v60, v145, v148
	v_exp_f32_e32 v60, v60
	v_add_f32_e32 v56, v63, v56
	v_cndmask_b32_e64 v76, v57, 0, s[50:51]
	v_sub_f32_e32 v57, v59, v150
	v_exp_f32_e32 v57, v57
	v_add_f32_e32 v56, v76, v56
	v_pk_mul_f32 v[38:39], v[38:39], v[60:61] op_sel_hi:[1,0]
	v_pk_mul_f32 v[36:37], v[36:37], v[60:61] op_sel_hi:[1,0]
	v_cndmask_b32_e64 v59, v57, 0, s[52:53]
	v_add_f32_e32 v151, v59, v56
	v_cvt_pk_bf16_f32 v56, v61, v64
	v_cvt_pk_bf16_f32 v57, v65, v66
	v_cvt_pk_bf16_f32 v58, v67, v63
	v_cvt_pk_bf16_f32 v59, v76, v59
	s_waitcnt lgkmcnt(10)
	v_mfma_f32_16x16x32_bf16 v[80:83], v[96:99], v[32:35], v[36:39]
	v_fmac_f32_e32 v149, v146, v60
	v_fmac_f32_e32 v151, v183, v62
	s_nop 0
	v_pk_mul_f32 v[38:39], v[70:71], v[62:63] op_sel_hi:[1,0]
	v_pk_mul_f32 v[36:37], v[68:69], v[62:63] op_sel_hi:[1,0]
	s_nop 1
	v_mfma_f32_16x16x32_bf16 v[84:87], v[96:99], v[56:59], v[36:39]
	s_nop 2
	v_mul_f32_e64 v38, v74, v60
	v_mul_f32_e64 v39, v75, v60
	v_pk_mul_f32 v[36:37], v[72:73], v[60:61] op_sel_hi:[1,0]
	s_waitcnt lgkmcnt(8)
	s_nop 0
	v_mfma_f32_16x16x32_bf16 v[96:99], v[140:143], v[32:35], v[36:39]
	s_nop 2
	v_mul_f32_e64 v38, v106, v62
	v_mul_f32_e64 v39, v107, v62
	v_pk_mul_f32 v[36:37], v[104:105], v[62:63] op_sel_hi:[1,0]
	s_nop 1
	v_mfma_f32_16x16x32_bf16 v[100:103], v[140:143], v[56:59], v[36:39]
	s_nop 2
	v_mul_f32_e64 v38, v110, v60
	v_mul_f32_e64 v39, v111, v60
	v_pk_mul_f32 v[36:37], v[108:109], v[60:61] op_sel_hi:[1,0]
	s_waitcnt lgkmcnt(6)
	s_nop 0
	v_mfma_f32_16x16x32_bf16 v[104:107], v[136:139], v[32:35], v[36:39]
	s_nop 2
	v_mul_f32_e64 v38, v114, v62
	v_mul_f32_e64 v39, v115, v62
	v_pk_mul_f32 v[36:37], v[112:113], v[62:63] op_sel_hi:[1,0]
	s_nop 1
	v_mfma_f32_16x16x32_bf16 v[108:111], v[136:139], v[56:59], v[36:39]
	s_nop 2
	v_mul_f32_e64 v38, v118, v60
	v_mul_f32_e64 v39, v119, v60
	v_pk_mul_f32 v[36:37], v[116:117], v[60:61] op_sel_hi:[1,0]
	s_waitcnt lgkmcnt(4)
	s_nop 0
	v_mfma_f32_16x16x32_bf16 v[112:115], v[132:135], v[32:35], v[36:39]
	v_mul_f32_e64 v34, v130, v62
	v_mul_f32_e64 v35, v131, v62
	v_pk_mul_f32 v[32:33], v[128:129], v[62:63] op_sel_hi:[1,0]
	s_nop 1
	v_mfma_f32_16x16x32_bf16 v[116:119], v[132:135], v[56:59], v[32:35]
	s_nop 2
	v_add_u32_e32 v32, 0x80, v184
	v_med3_i32 v32, v32, 0, s75
	v_lshl_add_u32 v32, v32, 9, v152
	global_load_dwordx4 v[64:67], v32, s[98:99]
	v_add_u32_e32 v32, 0x80, v185
	v_med3_i32 v32, v32, 0, s75
	v_lshl_add_u32 v32, v32, 9, v152
	global_load_dwordx4 v[68:71], v32, s[98:99]
	v_add_u32_e32 v32, 0x80, v186
	v_med3_i32 v32, v32, 0, s75
	v_lshl_add_u32 v32, v32, 9, v152
	global_load_dwordx4 v[72:75], v32, s[98:99]
	v_add_u32_e32 v32, 0x80, v188
	v_med3_i32 v32, v32, 0, s75
	v_lshl_add_u32 v32, v32, 9, v152
	global_load_dwordx4 v[76:79], v32, s[98:99]
	v_or_b32_e32 v32, 0x80, v209
	v_add_u32_e32 v32, s76, v32
	v_med3_i32 v32, v32, 0, s75
	v_lshl_add_u32 v32, v32, 9, v158
	global_load_dwordx4 v[60:63], v32, s[100:101]
	global_load_dwordx4 v[56:59], v32, s[100:101] offset:64
	v_or_b32_e32 v32, 0xc0, v209
	v_add_u32_e32 v32, s76, v32
	v_med3_i32 v32, v32, 0, s75
	v_lshl_add_u32 v32, v32, 9, v158
	global_load_dwordx4 v[36:39], v32, s[100:101]
	s_nop 0
	global_load_dwordx4 v[32:35], v32, s[100:101] offset:64
	ds_read_b64_tr_b16 v[134:135], v169 offset:6912
	ds_read_b64_tr_b16 v[132:133], v169 offset:4608
	ds_read_b64_tr_b16 v[128:129], v169 offset:4640
	ds_read_b64_tr_b16 v[130:131], v169 offset:6944
	ds_read_b64_tr_b16 v[136:137], v169 offset:4672
	ds_read_b64_tr_b16 v[138:139], v169 offset:6976
	ds_read_b64_tr_b16 v[144:145], v169 offset:4704
	ds_read_b64_tr_b16 v[146:147], v169 offset:7008
	s_waitcnt vmcnt(15)
	ds_write_b128 v241, v[88:91]
	s_waitcnt vmcnt(14)
	ds_write_b128 v242, v[92:95]
	s_waitcnt vmcnt(13)
	ds_write_b128 v243, v[120:123]
	s_waitcnt vmcnt(12)
	ds_write_b128 v244, v[124:127]
	v_mfma_f32_16x16x32_bf16 v[88:91], v[52:55], v[4:7], 0
	v_mfma_f32_16x16x32_bf16 v[92:95], v[28:31], v[4:7], 0
	v_mfma_f32_16x16x32_bf16 v[28:31], v[28:31], v[12:15], 0
	v_mfma_f32_16x16x32_bf16 v[88:91], v[44:47], v[8:11], v[88:91]
	v_mfma_f32_16x16x32_bf16 v[92:95], v[20:23], v[8:11], v[92:95]
	v_mfma_f32_16x16x32_bf16 v[20:23], v[20:23], v[0:3], v[28:31]
	s_nop 4
	v_sub_u32_e32 v28, v187, v176
	v_mfma_f32_16x16x32_bf16 v[52:55], v[52:55], v[12:15], 0
	v_add_u32_e32 v31, 1, v28
	v_cmp_gt_u32_e64 s[0:1], v31, v175
	v_cmp_gt_u32_e32 vcc, v28, v175
	s_nop 0
	v_cndmask_b32_e64 v89, v89, v246, s[0:1]
	s_nop 0
	v_cndmask_b32_e32 v88, v88, v246, vcc
	v_mfma_f32_16x16x32_bf16 v[44:47], v[44:47], v[0:3], v[52:55]
	v_max_f32_e32 v30, v88, v89
	v_add_u32_e32 v31, 2, v28
	v_cmp_gt_u32_e64 s[22:23], v31, v175
	v_add_u32_e32 v52, 3, v28
	v_cmp_gt_u32_e64 s[24:25], v52, v175
	v_cndmask_b32_e64 v90, v90, v246, s[22:23]
	v_sub_u32_e32 v29, v187, v181
	v_cndmask_b32_e64 v91, v91, v246, s[24:25]
	v_max3_f32 v30, v30, v90, v91
	v_add_u32_e32 v31, 16, v28
	v_add_u32_e32 v52, 17, v28
	v_cmp_gt_u32_e64 s[26:27], v31, v175
	v_cmp_gt_u32_e64 s[28:29], v52, v175
	v_cmp_gt_u32_e64 s[38:39], v29, v252
	v_cndmask_b32_e64 v92, v92, v246, s[26:27]
	v_cndmask_b32_e64 v93, v93, v246, s[28:29]
	v_max3_f32 v30, v30, v92, v93
	v_add_u32_e32 v31, 18, v28
	v_add_u32_e32 v28, 19, v28
	v_cmp_gt_u32_e64 s[30:31], v31, v175
	v_cmp_gt_u32_e64 s[34:35], v28, v175
	v_add_u32_e32 v52, 3, v29
	v_cndmask_b32_e64 v94, v94, v246, s[30:31]
	v_cndmask_b32_e64 v95, v95, v246, s[34:35]
	v_max3_f32 v28, v30, v94, v95
	v_add_u32_e32 v31, 1, v29
	v_cmp_gt_u32_e64 s[40:41], v31, v252
	v_cndmask_b32_e64 v44, v44, v246, s[38:39]
	s_nop 0
	v_cndmask_b32_e64 v45, v45, v246, s[40:41]
	v_max_f32_e32 v30, v44, v45
	v_add_u32_e32 v31, 2, v29
	v_cmp_gt_u32_e64 s[42:43], v31, v252
	v_cmp_gt_u32_e64 s[44:45], v52, v252
	s_nop 0
	v_cndmask_b32_e64 v46, v46, v246, s[42:43]
	v_cndmask_b32_e64 v47, v47, v246, s[44:45]
	v_max3_f32 v30, v30, v46, v47
	v_add_u32_e32 v31, 16, v29
	v_add_u32_e32 v52, 17, v29
	v_cmp_gt_u32_e64 s[46:47], v31, v252
	v_cmp_gt_u32_e64 s[48:49], v52, v252
	s_nop 0
	v_cndmask_b32_e64 v20, v20, v246, s[46:47]
	v_cndmask_b32_e64 v21, v21, v246, s[48:49]
	v_max3_f32 v30, v30, v20, v21
	v_add_u32_e32 v31, 18, v29
	v_add_u32_e32 v29, 19, v29
	v_cmp_gt_u32_e64 s[50:51], v31, v252
	v_cmp_gt_u32_e64 s[52:53], v29, v252
	s_nop 0
	v_cndmask_b32_e64 v22, v22, v246, s[50:51]
	v_cndmask_b32_e64 v23, v23, v246, s[52:53]
	v_max3_f32 v29, v30, v22, v23
	v_mov_b32_e32 v30, v28
	s_nop 1
	v_permlane32_swap_b32_e32 v30, v28
	v_max_f32_e32 v28, v28, v30
	v_mov_b32_e32 v30, v29
	s_nop 1
	v_permlane32_swap_b32_e32 v30, v29
	v_max_f32_e32 v29, v29, v30
	v_mov_b32_e32 v30, v28
	s_nop 1
	v_permlane16_swap_b32_e32 v30, v28
	v_max_f32_e32 v28, v28, v30
	v_mov_b32_e32 v30, v29
	v_max_f32_e32 v183, v148, v28
	s_nop 0
	v_permlane16_swap_b32_e32 v30, v29
	v_sub_f32_e32 v28, v148, v183
	v_exp_f32_e32 v52, v28
	v_sub_f32_e32 v28, v88, v183
	v_max_f32_e32 v54, v29, v30
	v_exp_f32_e32 v28, v28
	v_sub_f32_e32 v30, v89, v183
	v_exp_f32_e32 v30, v30
	v_sub_f32_e32 v31, v90, v183
	v_exp_f32_e32 v31, v31
	v_sub_f32_e32 v55, v91, v183
	v_max_f32_e32 v185, v150, v54
	v_exp_f32_e32 v55, v55
	v_sub_f32_e32 v88, v92, v183
	v_sub_f32_e32 v44, v44, v185
	v_exp_f32_e32 v88, v88
	v_sub_f32_e32 v89, v93, v183
	v_exp_f32_e32 v44, v44
	v_sub_f32_e32 v45, v45, v185
	v_exp_f32_e32 v89, v89
	v_sub_f32_e32 v90, v94, v183
	v_exp_f32_e32 v45, v45
	v_sub_f32_e32 v46, v46, v185
	v_add_f32_e32 v29, v30, v28
	v_exp_f32_e32 v90, v90
	v_sub_f32_e32 v91, v95, v183
	v_exp_f32_e32 v46, v46
	v_sub_f32_e32 v47, v47, v185
	v_add_f32_e32 v29, v31, v29
	v_exp_f32_e32 v91, v91
	v_exp_f32_e32 v47, v47
	v_sub_f32_e32 v20, v20, v185
	v_add_f32_e32 v29, v55, v29
	v_sub_f32_e32 v53, v150, v185
	v_exp_f32_e32 v20, v20
	v_sub_f32_e32 v21, v21, v185
	v_add_f32_e32 v29, v88, v29
	v_exp_f32_e32 v54, v53
	v_exp_f32_e32 v21, v21
	v_add_f32_e32 v29, v89, v29
	v_add_f32_e32 v53, v45, v44
	v_add_f32_e32 v29, v90, v29
	v_add_f32_e32 v53, v46, v53
	v_add_f32_e32 v184, v91, v29
	v_cvt_pk_bf16_f32 v29, v31, v55
	v_add_f32_e32 v53, v47, v53
	v_cndmask_b32_e64 v55, v20, 0, s[46:47]
	v_add_f32_e32 v20, v55, v53
	v_cndmask_b32_e64 v53, v21, 0, s[48:49]
	v_sub_f32_e32 v21, v22, v185
	v_exp_f32_e32 v21, v21
	v_cvt_pk_bf16_f32 v28, v28, v30
	v_cvt_pk_bf16_f32 v30, v88, v89
	v_add_f32_e32 v20, v53, v20
	v_cndmask_b32_e64 v88, v21, 0, s[50:51]
	v_sub_f32_e32 v21, v23, v185
	v_exp_f32_e32 v21, v21
	v_add_f32_e32 v20, v88, v20
	v_cvt_pk_bf16_f32 v31, v90, v91
	v_cvt_pk_bf16_f32 v22, v55, v53
	v_cndmask_b32_e64 v23, v21, 0, s[52:53]
	v_add_f32_e32 v186, v23, v20
	v_cvt_pk_bf16_f32 v20, v44, v45
	v_cvt_pk_bf16_f32 v21, v46, v47
	v_pk_mul_f32 v[46:47], v[82:83], v[52:53] op_sel_hi:[1,0]
	v_pk_mul_f32 v[44:45], v[80:81], v[52:53] op_sel_hi:[1,0]
	v_cvt_pk_bf16_f32 v23, v88, v23
	v_fmac_f32_e32 v184, v149, v52
	s_waitcnt lgkmcnt(10)
	v_mfma_f32_16x16x32_bf16 v[120:123], v[132:135], v[28:31], v[44:47]
	v_fmac_f32_e32 v186, v151, v54
	s_nop 1
	v_pk_mul_f32 v[46:47], v[86:87], v[54:55] op_sel_hi:[1,0]
	v_pk_mul_f32 v[44:45], v[84:85], v[54:55] op_sel_hi:[1,0]
	s_nop 1
	v_mfma_f32_16x16x32_bf16 v[124:127], v[132:135], v[20:23], v[44:47]
	s_nop 2
	v_mul_f32_e64 v46, v98, v52
	v_mul_f32_e64 v47, v99, v52
	v_pk_mul_f32 v[44:45], v[96:97], v[52:53] op_sel_hi:[1,0]
	s_waitcnt lgkmcnt(8)
	s_nop 0
	v_mfma_f32_16x16x32_bf16 v[96:99], v[128:131], v[28:31], v[44:47]
	s_nop 2
	v_mul_f32_e64 v46, v102, v54
	v_mul_f32_e64 v47, v103, v54
	v_pk_mul_f32 v[44:45], v[100:101], v[54:55] op_sel_hi:[1,0]
	s_nop 1
	v_mfma_f32_16x16x32_bf16 v[128:131], v[128:131], v[20:23], v[44:47]
	s_nop 2
	v_mul_f32_e64 v46, v106, v52
	v_mul_f32_e64 v47, v107, v52
	v_pk_mul_f32 v[44:45], v[104:105], v[52:53] op_sel_hi:[1,0]
	s_waitcnt lgkmcnt(6)
	s_nop 0
	v_mfma_f32_16x16x32_bf16 v[132:135], v[136:139], v[28:31], v[44:47]
	s_nop 2
	v_mul_f32_e64 v46, v110, v54
	v_mul_f32_e64 v47, v111, v54
	v_pk_mul_f32 v[44:45], v[108:109], v[54:55] op_sel_hi:[1,0]
	s_nop 1
	v_mfma_f32_16x16x32_bf16 v[136:139], v[136:139], v[20:23], v[44:47]
	s_nop 2
	v_mul_f32_e64 v46, v114, v52
	v_mul_f32_e64 v47, v115, v52
	v_pk_mul_f32 v[44:45], v[112:113], v[52:53] op_sel_hi:[1,0]
	s_waitcnt lgkmcnt(4)
	s_nop 0
	v_mfma_f32_16x16x32_bf16 v[140:143], v[144:147], v[28:31], v[44:47]
	v_mul_f32_e64 v30, v118, v54
	v_mul_f32_e64 v31, v119, v54
	v_pk_mul_f32 v[28:29], v[116:117], v[54:55] op_sel_hi:[1,0]
	s_nop 1
	v_mfma_f32_16x16x32_bf16 v[144:147], v[144:147], v[20:23], v[28:31]
	v_lshl_add_u32 v20, v155, 1, v155
	v_add_u32_e32 v20, v180, v20
	v_med3_i32 v20, v20, 0, s75
	v_lshl_add_u32 v20, v20, 9, v152
	global_load_dwordx4 v[80:83], v20, s[98:99]
	v_lshl_add_u32 v20, v172, 1, v172
	v_add_u32_e32 v20, v179, v20
	v_med3_i32 v20, v20, 0, s75
	v_lshl_add_u32 v20, v20, 9, v152
	global_load_dwordx4 v[84:87], v20, s[98:99]
	v_lshl_add_u32 v20, v173, 1, v173
	v_add_u32_e32 v20, v178, v20
	v_med3_i32 v20, v20, 0, s75
	v_lshl_add_u32 v20, v20, 9, v152
	global_load_dwordx4 v[88:91], v20, s[98:99]
	v_lshl_add_u32 v20, v182, 1, v182
	v_add_u32_e32 v20, v177, v20
	v_med3_i32 v20, v20, 0, s75
	v_lshl_add_u32 v20, v20, 9, v152
	global_load_dwordx4 v[92:95], v20, s[98:99]
	v_or_b32_e32 v20, 0x100, v209
	v_add_u32_e32 v20, s76, v20
	v_med3_i32 v20, v20, 0, s75
	v_lshl_add_u32 v20, v20, 9, v158
	global_load_dwordx4 v[52:55], v20, s[100:101]
	global_load_dwordx4 v[44:47], v20, s[100:101] offset:64
	v_or_b32_e32 v20, 0x140, v209
	v_add_u32_e32 v20, s76, v20
	v_med3_i32 v20, v20, 0, s75
	v_lshl_add_u32 v20, v20, 9, v158
	global_load_dwordx4 v[28:31], v20, s[100:101]
	s_nop 0
	global_load_dwordx4 v[20:23], v20, s[100:101] offset:64
	ds_read_b64_tr_b16 v[102:103], v169 offset:2304
	ds_read_b64_tr_b16 v[100:101], v169
	ds_read_b64_tr_b16 v[108:109], v169 offset:32
	ds_read_b64_tr_b16 v[110:111], v169 offset:2336
	ds_read_b64_tr_b16 v[116:117], v169 offset:64
	ds_read_b64_tr_b16 v[118:119], v169 offset:2368
	ds_read_b64_tr_b16 v[148:149], v169 offset:96
	ds_read_b64_tr_b16 v[150:151], v169 offset:2400
	s_waitcnt vmcnt(15)
	ds_write_b128 v241, v[64:67] offset:4608
	s_waitcnt vmcnt(14)
	ds_write_b128 v242, v[68:71] offset:4608
	s_waitcnt vmcnt(13)
	ds_write_b128 v243, v[72:75] offset:4608
	s_waitcnt vmcnt(12)
	ds_write_b128 v244, v[76:79] offset:4608
	v_mfma_f32_16x16x32_bf16 v[64:67], v[48:51], v[4:7], 0
	v_mfma_f32_16x16x32_bf16 v[68:71], v[24:27], v[4:7], 0
	v_mfma_f32_16x16x32_bf16 v[24:27], v[24:27], v[12:15], 0
	v_mfma_f32_16x16x32_bf16 v[64:67], v[40:43], v[8:11], v[64:67]
	v_mfma_f32_16x16x32_bf16 v[68:71], v[16:19], v[8:11], v[68:71]
	v_mfma_f32_16x16x32_bf16 v[16:19], v[16:19], v[0:3], v[24:27]
	s_nop 4
	v_sub_u32_e32 v24, v192, v176
	v_mfma_f32_16x16x32_bf16 v[48:51], v[48:51], v[12:15], 0
	v_add_u32_e32 v27, 1, v24
	v_cmp_gt_u32_e64 s[0:1], v27, v175
	v_cmp_gt_u32_e32 vcc, v24, v175
	s_nop 0
	v_cndmask_b32_e64 v65, v65, v246, s[0:1]
	s_nop 0
	v_cndmask_b32_e32 v64, v64, v246, vcc
	v_mfma_f32_16x16x32_bf16 v[40:43], v[40:43], v[0:3], v[48:51]
	v_max_f32_e32 v26, v64, v65
	v_add_u32_e32 v27, 2, v24
	v_cmp_gt_u32_e64 s[22:23], v27, v175
	v_add_u32_e32 v48, 3, v24
	v_cmp_gt_u32_e64 s[24:25], v48, v175
	v_cndmask_b32_e64 v66, v66, v246, s[22:23]
	v_sub_u32_e32 v25, v192, v181
	v_cndmask_b32_e64 v67, v67, v246, s[24:25]
	v_max3_f32 v26, v26, v66, v67
	v_add_u32_e32 v27, 16, v24
	v_add_u32_e32 v48, 17, v24
	v_cmp_gt_u32_e64 s[26:27], v27, v175
	v_cmp_gt_u32_e64 s[28:29], v48, v175
	v_cmp_gt_u32_e64 s[38:39], v25, v252
	v_cndmask_b32_e64 v68, v68, v246, s[26:27]
	v_cndmask_b32_e64 v69, v69, v246, s[28:29]
	v_max3_f32 v26, v26, v68, v69
	v_add_u32_e32 v27, 18, v24
	v_add_u32_e32 v24, 19, v24
	v_cmp_gt_u32_e64 s[30:31], v27, v175
	v_cmp_gt_u32_e64 s[34:35], v24, v175
	v_add_u32_e32 v48, 3, v25
	v_cndmask_b32_e64 v70, v70, v246, s[30:31]
	v_cndmask_b32_e64 v71, v71, v246, s[34:35]
	v_max3_f32 v24, v26, v70, v71
	v_add_u32_e32 v27, 1, v25
	v_cmp_gt_u32_e64 s[40:41], v27, v252
	v_cndmask_b32_e64 v40, v40, v246, s[38:39]
	s_nop 0
	v_cndmask_b32_e64 v41, v41, v246, s[40:41]
	v_max_f32_e32 v26, v40, v41
	v_add_u32_e32 v27, 2, v25
	v_cmp_gt_u32_e64 s[42:43], v27, v252
	v_cmp_gt_u32_e64 s[44:45], v48, v252
	s_nop 0
	v_cndmask_b32_e64 v42, v42, v246, s[42:43]
	v_cndmask_b32_e64 v43, v43, v246, s[44:45]
	v_max3_f32 v26, v26, v42, v43
	v_add_u32_e32 v27, 16, v25
	v_add_u32_e32 v48, 17, v25
	v_cmp_gt_u32_e64 s[46:47], v27, v252
	v_cmp_gt_u32_e64 s[48:49], v48, v252
	s_nop 0
	v_cndmask_b32_e64 v16, v16, v246, s[46:47]
	v_cndmask_b32_e64 v17, v17, v246, s[48:49]
	v_max3_f32 v26, v26, v16, v17
	v_add_u32_e32 v27, 18, v25
	v_add_u32_e32 v25, 19, v25
	v_cmp_gt_u32_e64 s[50:51], v27, v252
	v_cmp_gt_u32_e64 s[52:53], v25, v252
	s_nop 0
	v_cndmask_b32_e64 v18, v18, v246, s[50:51]
	v_cndmask_b32_e64 v19, v19, v246, s[52:53]
	v_max3_f32 v25, v26, v18, v19
	v_mov_b32_e32 v26, v24
	s_nop 1
	v_permlane32_swap_b32_e32 v26, v24
	v_max_f32_e32 v24, v24, v26
	v_mov_b32_e32 v26, v25
	s_nop 1
	v_permlane32_swap_b32_e32 v26, v25
	v_max_f32_e32 v25, v25, v26
	v_mov_b32_e32 v26, v24
	s_nop 1
	v_permlane16_swap_b32_e32 v26, v24
	v_max3_f32 v177, v183, v24, v26
	v_sub_f32_e32 v48, v66, v177
	v_exp_f32_e32 v48, v48
	v_sub_f32_e32 v24, v183, v177
	v_exp_f32_e32 v72, v24
	v_sub_f32_e32 v24, v64, v177
	v_cndmask_b32_e64 v49, v48, 0, s[22:23]
	v_sub_f32_e32 v48, v67, v177
	v_exp_f32_e32 v48, v48
	v_exp_f32_e32 v24, v24
	v_sub_f32_e32 v27, v65, v177
	v_exp_f32_e32 v27, v27
	v_cndmask_b32_e64 v50, v48, 0, s[24:25]
	v_sub_f32_e32 v48, v68, v177
	v_exp_f32_e32 v48, v48
	v_mov_b32_e32 v26, v25
	s_nop 1
	v_permlane16_swap_b32_e32 v26, v25
	v_cndmask_b32_e64 v51, v48, 0, s[26:27]
	v_sub_f32_e32 v48, v69, v177
	v_exp_f32_e32 v48, v48
	v_max_f32_e32 v25, v25, v26
	v_cndmask_b32_e64 v64, v48, 0, s[28:29]
	v_sub_f32_e32 v48, v70, v177
	v_exp_f32_e32 v48, v48
	v_add_f32_e32 v26, v27, v24
	v_cndmask_b32_e64 v65, v48, 0, s[30:31]
	v_sub_f32_e32 v48, v71, v177
	v_exp_f32_e32 v48, v48
	v_add_f32_e32 v26, v49, v26
	v_add_f32_e32 v26, v50, v26
	v_add_f32_e32 v26, v51, v26
	v_max_f32_e32 v179, v185, v25
	v_add_f32_e32 v26, v64, v26
	v_cndmask_b32_e64 v66, v48, 0, s[34:35]
	v_cvt_pk_bf16_f32 v48, v24, v27
	v_sub_f32_e32 v24, v185, v179
	v_add_f32_e32 v26, v65, v26
	v_cvt_pk_bf16_f32 v49, v49, v50
	v_cvt_pk_bf16_f32 v50, v51, v64
	v_exp_f32_e32 v64, v24
	v_sub_f32_e32 v24, v40, v179
	v_add_f32_e32 v178, v66, v26
	v_exp_f32_e32 v24, v24
	v_sub_f32_e32 v26, v41, v179
	v_exp_f32_e32 v26, v26
	v_sub_f32_e32 v27, v42, v179
	v_exp_f32_e32 v27, v27
	v_sub_f32_e32 v40, v43, v179
	v_exp_f32_e32 v40, v40
	v_sub_f32_e32 v16, v16, v179
	v_exp_f32_e32 v16, v16
	v_sub_f32_e32 v17, v17, v179
	v_exp_f32_e32 v17, v17
	v_add_f32_e32 v25, v26, v24
	v_add_f32_e32 v25, v27, v25
	v_add_f32_e32 v25, v40, v25
	v_cndmask_b32_e64 v41, v16, 0, s[46:47]
	v_add_f32_e32 v16, v41, v25
	v_cndmask_b32_e64 v25, v17, 0, s[48:49]
	v_sub_f32_e32 v17, v18, v179
	v_exp_f32_e32 v17, v17
	v_add_f32_e32 v16, v25, v16
	v_cvt_pk_bf16_f32 v51, v65, v66
	v_cvt_pk_bf16_f32 v18, v41, v25
	v_cndmask_b32_e64 v42, v17, 0, s[50:51]
	v_sub_f32_e32 v17, v19, v179
	v_exp_f32_e32 v17, v17
	v_add_f32_e32 v16, v42, v16
	v_fmac_f32_e32 v178, v184, v72
	v_cndmask_b32_e64 v19, v17, 0, s[52:53]
	v_add_f32_e32 v180, v19, v16
	v_cvt_pk_bf16_f32 v16, v24, v26
	v_cvt_pk_bf16_f32 v17, v27, v40
	v_cvt_pk_bf16_f32 v19, v42, v19
	v_pk_mul_f32 v[26:27], v[122:123], v[72:73] op_sel_hi:[1,0]
	v_pk_mul_f32 v[24:25], v[120:121], v[72:73] op_sel_hi:[1,0]
	v_pk_mul_f32 v[42:43], v[126:127], v[64:65] op_sel_hi:[1,0]
	v_pk_mul_f32 v[40:41], v[124:125], v[64:65] op_sel_hi:[1,0]
	s_waitcnt lgkmcnt(10)
	v_mfma_f32_16x16x32_bf16 v[24:27], v[100:103], v[48:51], v[24:27]
	v_fmac_f32_e32 v180, v186, v64
	v_mfma_f32_16x16x32_bf16 v[100:103], v[100:103], v[16:19], v[40:43]
	s_nop 2
	v_mul_f32_e64 v42, v98, v72
	v_mul_f32_e64 v43, v99, v72
	v_pk_mul_f32 v[40:41], v[96:97], v[72:73] op_sel_hi:[1,0]
	s_waitcnt lgkmcnt(8)
	s_nop 0
	v_mfma_f32_16x16x32_bf16 v[104:107], v[108:111], v[48:51], v[40:43]
	s_nop 2
	v_mul_f32_e64 v42, v130, v64
	v_mul_f32_e64 v43, v131, v64
	v_pk_mul_f32 v[40:41], v[128:129], v[64:65] op_sel_hi:[1,0]
	s_nop 1
	v_mfma_f32_16x16x32_bf16 v[108:111], v[108:111], v[16:19], v[40:43]
	s_nop 2
	v_mul_f32_e64 v42, v134, v72
	v_mul_f32_e64 v43, v135, v72
	v_pk_mul_f32 v[40:41], v[132:133], v[72:73] op_sel_hi:[1,0]
	s_waitcnt lgkmcnt(6)
	s_nop 0
	v_mfma_f32_16x16x32_bf16 v[112:115], v[116:119], v[48:51], v[40:43]
	s_nop 2
	v_mul_f32_e64 v42, v138, v64
	v_mul_f32_e64 v43, v139, v64
	v_pk_mul_f32 v[40:41], v[136:137], v[64:65] op_sel_hi:[1,0]
	s_nop 1
	v_mfma_f32_16x16x32_bf16 v[116:119], v[116:119], v[16:19], v[40:43]
	s_nop 2
	v_mul_f32_e64 v42, v142, v72
	v_mul_f32_e64 v43, v143, v72
	v_pk_mul_f32 v[40:41], v[140:141], v[72:73] op_sel_hi:[1,0]
	s_waitcnt lgkmcnt(4)
	s_nop 0
	v_mfma_f32_16x16x32_bf16 v[120:123], v[148:151], v[48:51], v[40:43]
	s_nop 2
	v_mul_f32_e64 v42, v146, v64
	v_mul_f32_e64 v43, v147, v64
	v_pk_mul_f32 v[40:41], v[144:145], v[64:65] op_sel_hi:[1,0]
	s_nop 1
	v_mfma_f32_16x16x32_bf16 v[124:127], v[148:151], v[16:19], v[40:43]
	v_lshlrev_b32_e32 v16, 2, v196
	v_add_u32_e32 v16, s76, v16
	v_med3_i32 v16, v16, 0, s75
	v_lshl_add_u32 v16, v16, 9, v152
	global_load_dwordx4 v[68:71], v16, s[98:99]
	v_lshlrev_b32_e32 v16, 2, v168
	v_add_u32_e32 v16, s76, v16
	v_med3_i32 v16, v16, 0, s75
	v_lshl_add_u32 v16, v16, 9, v152
	global_load_dwordx4 v[72:75], v16, s[98:99]
	v_lshlrev_b32_e32 v16, 2, v193
	v_add_u32_e32 v16, s76, v16
	v_med3_i32 v16, v16, 0, s75
	v_lshl_add_u32 v16, v16, 9, v152
	global_load_dwordx4 v[76:79], v16, s[98:99]
	v_lshlrev_b32_e32 v16, 2, v194
	v_add_u32_e32 v16, s76, v16
	v_med3_i32 v16, v16, 0, s75
	v_lshl_add_u32 v16, v16, 9, v152
	global_load_dwordx4 v[96:99], v16, s[98:99]
	v_or_b32_e32 v16, 0x180, v209
	v_add_u32_e32 v16, s76, v16
	v_med3_i32 v16, v16, 0, s75
	v_lshl_add_u32 v16, v16, 9, v158
	global_load_dwordx4 v[64:67], v16, s[100:101]
	global_load_dwordx4 v[48:51], v16, s[100:101] offset:64
	v_or_b32_e32 v16, 0x1c0, v209
	v_add_u32_e32 v16, s76, v16
	v_med3_i32 v16, v16, 0, s75
	v_lshl_add_u32 v16, v16, 9, v158
	global_load_dwordx4 v[40:43], v16, s[100:101]
	s_nop 0
	global_load_dwordx4 v[16:19], v16, s[100:101] offset:64
	ds_read_b64_tr_b16 v[142:143], v169 offset:6912
	ds_read_b64_tr_b16 v[140:141], v169 offset:4608
	ds_read_b64_tr_b16 v[136:137], v169 offset:4640
	ds_read_b64_tr_b16 v[138:139], v169 offset:6944
	ds_read_b64_tr_b16 v[132:133], v169 offset:4672
	ds_read_b64_tr_b16 v[134:135], v169 offset:6976
	ds_read_b64_tr_b16 v[128:129], v169 offset:4704
	ds_read_b64_tr_b16 v[130:131], v169 offset:7008
	s_waitcnt vmcnt(15)
	ds_write_b128 v241, v[80:83]
	s_waitcnt vmcnt(14)
	ds_write_b128 v242, v[84:87]
	s_waitcnt vmcnt(13)
	ds_write_b128 v243, v[88:91]
	s_waitcnt vmcnt(12)
	ds_write_b128 v244, v[92:95]
	v_mfma_f32_16x16x32_bf16 v[80:83], v[60:63], v[4:7], 0
	v_mfma_f32_16x16x32_bf16 v[84:87], v[36:39], v[4:7], 0
	v_mfma_f32_16x16x32_bf16 v[36:39], v[36:39], v[12:15], 0
	v_mfma_f32_16x16x32_bf16 v[80:83], v[56:59], v[8:11], v[80:83]
	v_mfma_f32_16x16x32_bf16 v[84:87], v[32:35], v[8:11], v[84:87]
	v_mfma_f32_16x16x32_bf16 v[32:35], v[32:35], v[0:3], v[36:39]
	s_nop 4
	v_sub_u32_e32 v36, v197, v176
	v_mfma_f32_16x16x32_bf16 v[60:63], v[60:63], v[12:15], 0
	v_add_u32_e32 v39, 1, v36
	v_cmp_gt_u32_e64 s[0:1], v39, v175
	v_cmp_gt_u32_e32 vcc, v36, v175
	s_nop 0
	v_cndmask_b32_e64 v81, v81, v246, s[0:1]
	s_nop 0
	v_cndmask_b32_e32 v80, v80, v246, vcc
	v_mfma_f32_16x16x32_bf16 v[56:59], v[56:59], v[0:3], v[60:63]
	v_max_f32_e32 v38, v80, v81
	v_add_u32_e32 v39, 2, v36
	v_cmp_gt_u32_e64 s[22:23], v39, v175
	v_add_u32_e32 v60, 3, v36
	v_cmp_gt_u32_e64 s[24:25], v60, v175
	v_cndmask_b32_e64 v82, v82, v246, s[22:23]
	v_sub_u32_e32 v37, v197, v181
	v_cndmask_b32_e64 v83, v83, v246, s[24:25]
	v_max3_f32 v38, v38, v82, v83
	v_add_u32_e32 v39, 16, v36
	v_add_u32_e32 v60, 17, v36
	v_cmp_gt_u32_e64 s[26:27], v39, v175
	v_cmp_gt_u32_e64 s[28:29], v60, v175
	v_cmp_gt_u32_e64 s[38:39], v37, v252
	v_cndmask_b32_e64 v84, v84, v246, s[26:27]
	v_cndmask_b32_e64 v85, v85, v246, s[28:29]
	v_max3_f32 v38, v38, v84, v85
	v_add_u32_e32 v39, 18, v36
	v_add_u32_e32 v36, 19, v36
	v_cmp_gt_u32_e64 s[30:31], v39, v175
	v_cmp_gt_u32_e64 s[34:35], v36, v175
	v_add_u32_e32 v60, 3, v37
	v_cndmask_b32_e64 v86, v86, v246, s[30:31]
	v_cndmask_b32_e64 v87, v87, v246, s[34:35]
	v_max3_f32 v36, v38, v86, v87
	v_add_u32_e32 v39, 1, v37
	v_cmp_gt_u32_e64 s[40:41], v39, v252
	v_cndmask_b32_e64 v56, v56, v246, s[38:39]
	s_nop 0
	v_cndmask_b32_e64 v57, v57, v246, s[40:41]
	v_max_f32_e32 v38, v56, v57
	v_add_u32_e32 v39, 2, v37
	v_cmp_gt_u32_e64 s[42:43], v39, v252
	v_cmp_gt_u32_e64 s[44:45], v60, v252
	s_nop 0
	v_cndmask_b32_e64 v58, v58, v246, s[42:43]
	v_cndmask_b32_e64 v59, v59, v246, s[44:45]
	v_max3_f32 v38, v38, v58, v59
	v_add_u32_e32 v39, 16, v37
	v_add_u32_e32 v60, 17, v37
	v_cmp_gt_u32_e64 s[46:47], v39, v252
	v_cmp_gt_u32_e64 s[48:49], v60, v252
	s_nop 0
	v_cndmask_b32_e64 v32, v32, v246, s[46:47]
	v_cndmask_b32_e64 v33, v33, v246, s[48:49]
	v_max3_f32 v38, v38, v32, v33
	v_add_u32_e32 v39, 18, v37
	v_add_u32_e32 v37, 19, v37
	v_cmp_gt_u32_e64 s[50:51], v39, v252
	v_cmp_gt_u32_e64 s[52:53], v37, v252
	s_nop 0
	v_cndmask_b32_e64 v34, v34, v246, s[50:51]
	v_cndmask_b32_e64 v35, v35, v246, s[52:53]
	v_max3_f32 v37, v38, v34, v35
	v_mov_b32_e32 v38, v36
	s_nop 1
	v_permlane32_swap_b32_e32 v38, v36
	v_max_f32_e32 v36, v36, v38
	v_mov_b32_e32 v38, v37
	s_nop 1
	v_permlane32_swap_b32_e32 v38, v37
	v_max_f32_e32 v37, v37, v38
	v_mov_b32_e32 v38, v36
	s_nop 1
	v_permlane16_swap_b32_e32 v38, v36
	v_max_f32_e32 v36, v36, v38
	v_mov_b32_e32 v38, v37
	v_max_f32_e32 v144, v177, v36
	s_nop 0
	v_permlane16_swap_b32_e32 v38, v37
	v_sub_f32_e32 v36, v177, v144
	v_exp_f32_e32 v60, v36
	v_sub_f32_e32 v36, v80, v144
	v_max_f32_e32 v62, v37, v38
	v_exp_f32_e32 v36, v36
	v_sub_f32_e32 v38, v81, v144
	v_exp_f32_e32 v38, v38
	v_sub_f32_e32 v39, v82, v144
	v_exp_f32_e32 v39, v39
	v_sub_f32_e32 v63, v83, v144
	v_max_f32_e32 v146, v179, v62
	v_exp_f32_e32 v63, v63
	v_sub_f32_e32 v80, v84, v144
	v_sub_f32_e32 v56, v56, v146
	v_exp_f32_e32 v80, v80
	v_sub_f32_e32 v81, v85, v144
	v_exp_f32_e32 v56, v56
	v_sub_f32_e32 v57, v57, v146
	v_exp_f32_e32 v81, v81
	v_sub_f32_e32 v82, v86, v144
	v_exp_f32_e32 v57, v57
	v_sub_f32_e32 v58, v58, v146
	v_add_f32_e32 v37, v38, v36
	v_exp_f32_e32 v82, v82
	v_sub_f32_e32 v83, v87, v144
	v_exp_f32_e32 v58, v58
	v_sub_f32_e32 v59, v59, v146
	v_add_f32_e32 v37, v39, v37
	v_exp_f32_e32 v83, v83
	v_exp_f32_e32 v59, v59
	v_sub_f32_e32 v32, v32, v146
	v_add_f32_e32 v37, v63, v37
	v_sub_f32_e32 v61, v179, v146
	v_exp_f32_e32 v32, v32
	v_sub_f32_e32 v33, v33, v146
	v_add_f32_e32 v37, v80, v37
	v_exp_f32_e32 v62, v61
	v_exp_f32_e32 v33, v33
	v_add_f32_e32 v37, v81, v37
	v_add_f32_e32 v61, v57, v56
	v_add_f32_e32 v37, v82, v37
	v_add_f32_e32 v61, v58, v61
	v_add_f32_e32 v145, v83, v37
	v_cvt_pk_bf16_f32 v37, v39, v63
	v_add_f32_e32 v61, v59, v61
	v_cndmask_b32_e64 v63, v32, 0, s[46:47]
	v_add_f32_e32 v32, v63, v61
	v_cndmask_b32_e64 v61, v33, 0, s[48:49]
	v_sub_f32_e32 v33, v34, v146
	v_exp_f32_e32 v33, v33
	v_cvt_pk_bf16_f32 v36, v36, v38
	v_cvt_pk_bf16_f32 v38, v80, v81
	v_add_f32_e32 v32, v61, v32
	v_cndmask_b32_e64 v80, v33, 0, s[50:51]
	v_sub_f32_e32 v33, v35, v146
	v_exp_f32_e32 v33, v33
	v_cvt_pk_bf16_f32 v39, v82, v83
	v_add_f32_e32 v32, v80, v32
	v_pk_mul_f32 v[26:27], v[26:27], v[60:61] op_sel_hi:[1,0]
	v_cndmask_b32_e64 v35, v33, 0, s[52:53]
	v_pk_mul_f32 v[24:25], v[24:25], v[60:61] op_sel_hi:[1,0]
	v_add_f32_e32 v147, v35, v32
	v_cvt_pk_bf16_f32 v32, v56, v57
	v_cvt_pk_bf16_f32 v33, v58, v59
	v_cvt_pk_bf16_f32 v34, v63, v61
	v_cvt_pk_bf16_f32 v35, v80, v35
	s_waitcnt lgkmcnt(10)
	v_mfma_f32_16x16x32_bf16 v[92:95], v[140:143], v[36:39], v[24:27]
	v_fmac_f32_e32 v145, v178, v60
	v_fmac_f32_e32 v147, v180, v62
	s_nop 0
	v_pk_mul_f32 v[26:27], v[102:103], v[62:63] op_sel_hi:[1,0]
	v_pk_mul_f32 v[24:25], v[100:101], v[62:63] op_sel_hi:[1,0]
	s_nop 1
	v_mfma_f32_16x16x32_bf16 v[100:103], v[140:143], v[32:35], v[24:27]
	s_nop 2
	v_mul_f32_e64 v26, v106, v60
	v_mul_f32_e64 v27, v107, v60
	v_pk_mul_f32 v[24:25], v[104:105], v[60:61] op_sel_hi:[1,0]
	s_waitcnt lgkmcnt(8)
	s_nop 0
	v_mfma_f32_16x16x32_bf16 v[104:107], v[136:139], v[36:39], v[24:27]
	s_nop 2
	v_mul_f32_e64 v26, v110, v62
	v_mul_f32_e64 v27, v111, v62
	v_pk_mul_f32 v[24:25], v[108:109], v[62:63] op_sel_hi:[1,0]
	s_nop 1
	v_mfma_f32_16x16x32_bf16 v[108:111], v[136:139], v[32:35], v[24:27]
	s_nop 2
	v_mul_f32_e64 v26, v114, v60
	v_mul_f32_e64 v27, v115, v60
	v_pk_mul_f32 v[24:25], v[112:113], v[60:61] op_sel_hi:[1,0]
	s_waitcnt lgkmcnt(6)
	s_nop 0
	v_mfma_f32_16x16x32_bf16 v[112:115], v[132:135], v[36:39], v[24:27]
	s_nop 2
	v_mul_f32_e64 v26, v118, v62
	v_mul_f32_e64 v27, v119, v62
	v_pk_mul_f32 v[24:25], v[116:117], v[62:63] op_sel_hi:[1,0]
	s_nop 1
	v_mfma_f32_16x16x32_bf16 v[116:119], v[132:135], v[32:35], v[24:27]
	s_nop 2
	v_mul_f32_e64 v26, v122, v60
	v_mul_f32_e64 v27, v123, v60
	v_pk_mul_f32 v[24:25], v[120:121], v[60:61] op_sel_hi:[1,0]
	s_waitcnt lgkmcnt(4)
	s_nop 0
	v_mfma_f32_16x16x32_bf16 v[120:123], v[128:131], v[36:39], v[24:27]
	s_nop 2
	v_mul_f32_e64 v26, v126, v62
	v_mul_f32_e64 v27, v127, v62
	v_pk_mul_f32 v[24:25], v[124:125], v[62:63] op_sel_hi:[1,0]
	s_nop 1
	v_mfma_f32_16x16x32_bf16 v[124:127], v[128:131], v[32:35], v[24:27]
	s_nop 2
	v_add_u32_e32 v24, s76, v214
	v_med3_i32 v24, v24, 0, s75
	v_lshl_add_u32 v24, v24, 9, v152
	global_load_dwordx4 v[60:63], v24, s[98:99]
	v_add_u32_e32 v24, s76, v216
	v_med3_i32 v24, v24, 0, s75
	v_lshl_add_u32 v24, v24, 9, v152
	global_load_dwordx4 v[80:83], v24, s[98:99]
	v_add_u32_e32 v24, s76, v218
	v_med3_i32 v24, v24, 0, s75
	v_lshl_add_u32 v24, v24, 9, v152
	global_load_dwordx4 v[84:87], v24, s[98:99]
	v_add_u32_e32 v24, s76, v220
	v_med3_i32 v24, v24, 0, s75
	v_lshl_add_u32 v24, v24, 9, v152
	global_load_dwordx4 v[88:91], v24, s[98:99]
	v_add_u32_e32 v24, s76, v221
	v_med3_i32 v24, v24, 0, s75
	v_lshl_add_u32 v24, v24, 9, v158
	global_load_dwordx4 v[56:59], v24, s[100:101]
	global_load_dwordx4 v[36:39], v24, s[100:101] offset:64
	v_or_b32_e32 v24, 0x100, v221
	v_add_u32_e32 v24, s76, v24
	v_med3_i32 v24, v24, 0, s75
	v_lshl_add_u32 v24, v24, 9, v158
	global_load_dwordx4 v[32:35], v24, s[100:101]
	s_nop 0
	global_load_dwordx4 v[24:27], v24, s[100:101] offset:64
	ds_read_b64_tr_b16 v[142:143], v169 offset:2304
	ds_read_b64_tr_b16 v[140:141], v169
	ds_read_b64_tr_b16 v[136:137], v169 offset:32
	ds_read_b64_tr_b16 v[138:139], v169 offset:2336
	ds_read_b64_tr_b16 v[132:133], v169 offset:64
	ds_read_b64_tr_b16 v[134:135], v169 offset:2368
	ds_read_b64_tr_b16 v[128:129], v169 offset:96
	ds_read_b64_tr_b16 v[130:131], v169 offset:2400
	s_waitcnt vmcnt(15)
	ds_write_b128 v241, v[68:71] offset:4608
	s_waitcnt vmcnt(14)
	ds_write_b128 v242, v[72:75] offset:4608
	s_waitcnt vmcnt(13)
	ds_write_b128 v243, v[76:79] offset:4608
	s_waitcnt vmcnt(12)
	ds_write_b128 v244, v[96:99] offset:4608
	v_mfma_f32_16x16x32_bf16 v[68:71], v[52:55], v[4:7], 0
	v_mfma_f32_16x16x32_bf16 v[72:75], v[28:31], v[4:7], 0
	v_mfma_f32_16x16x32_bf16 v[28:31], v[28:31], v[12:15], 0
	v_mfma_f32_16x16x32_bf16 v[68:71], v[44:47], v[8:11], v[68:71]
	v_mfma_f32_16x16x32_bf16 v[72:75], v[20:23], v[8:11], v[72:75]
	v_mfma_f32_16x16x32_bf16 v[20:23], v[20:23], v[0:3], v[28:31]
	s_nop 4
	v_sub_u32_e32 v28, v198, v176
	v_mfma_f32_16x16x32_bf16 v[52:55], v[52:55], v[12:15], 0
	v_add_u32_e32 v31, 1, v28
	v_cmp_gt_u32_e64 s[0:1], v31, v175
	v_cmp_gt_u32_e32 vcc, v28, v175
	s_nop 0
	v_cndmask_b32_e64 v69, v69, v246, s[0:1]
	s_nop 0
	v_cndmask_b32_e32 v68, v68, v246, vcc
	v_mfma_f32_16x16x32_bf16 v[44:47], v[44:47], v[0:3], v[52:55]
	v_max_f32_e32 v30, v68, v69
	v_add_u32_e32 v31, 2, v28
	v_cmp_gt_u32_e64 s[22:23], v31, v175
	v_add_u32_e32 v52, 3, v28
	v_cmp_gt_u32_e64 s[24:25], v52, v175
	v_cndmask_b32_e64 v70, v70, v246, s[22:23]
	v_sub_u32_e32 v29, v198, v181
	v_cndmask_b32_e64 v71, v71, v246, s[24:25]
	v_max3_f32 v30, v30, v70, v71
	v_add_u32_e32 v31, 16, v28
	v_add_u32_e32 v52, 17, v28
	v_cmp_gt_u32_e64 s[26:27], v31, v175
	v_cmp_gt_u32_e64 s[28:29], v52, v175
	v_cmp_gt_u32_e64 s[38:39], v29, v252
	v_cndmask_b32_e64 v72, v72, v246, s[26:27]
	v_cndmask_b32_e64 v73, v73, v246, s[28:29]
	v_max3_f32 v30, v30, v72, v73
	v_add_u32_e32 v31, 18, v28
	v_add_u32_e32 v28, 19, v28
	v_cmp_gt_u32_e64 s[30:31], v31, v175
	v_cmp_gt_u32_e64 s[34:35], v28, v175
	v_add_u32_e32 v52, 3, v29
	v_cndmask_b32_e64 v74, v74, v246, s[30:31]
	v_cndmask_b32_e64 v75, v75, v246, s[34:35]
	v_max3_f32 v28, v30, v74, v75
	v_add_u32_e32 v31, 1, v29
	v_cmp_gt_u32_e64 s[40:41], v31, v252
	v_cndmask_b32_e64 v44, v44, v246, s[38:39]
	s_nop 0
	v_cndmask_b32_e64 v45, v45, v246, s[40:41]
	v_max_f32_e32 v30, v44, v45
	v_add_u32_e32 v31, 2, v29
	v_cmp_gt_u32_e64 s[42:43], v31, v252
	v_cmp_gt_u32_e64 s[44:45], v52, v252
	s_nop 0
	v_cndmask_b32_e64 v46, v46, v246, s[42:43]
	v_cndmask_b32_e64 v47, v47, v246, s[44:45]
	v_max3_f32 v30, v30, v46, v47
	v_add_u32_e32 v31, 16, v29
	v_add_u32_e32 v52, 17, v29
	v_cmp_gt_u32_e64 s[46:47], v31, v252
	v_cmp_gt_u32_e64 s[48:49], v52, v252
	s_nop 0
	v_cndmask_b32_e64 v20, v20, v246, s[46:47]
	v_cndmask_b32_e64 v21, v21, v246, s[48:49]
	v_max3_f32 v30, v30, v20, v21
	v_add_u32_e32 v31, 18, v29
	v_add_u32_e32 v29, 19, v29
	v_cmp_gt_u32_e64 s[50:51], v31, v252
	v_cmp_gt_u32_e64 s[52:53], v29, v252
	s_nop 0
	v_cndmask_b32_e64 v22, v22, v246, s[50:51]
	v_cndmask_b32_e64 v23, v23, v246, s[52:53]
	v_max3_f32 v29, v30, v22, v23
	v_mov_b32_e32 v30, v28
	s_nop 1
	v_permlane32_swap_b32_e32 v30, v28
	v_max_f32_e32 v28, v28, v30
	v_mov_b32_e32 v30, v29
	s_nop 1
	v_permlane32_swap_b32_e32 v30, v29
	v_max_f32_e32 v29, v29, v30
	v_mov_b32_e32 v30, v28
	s_nop 1
	v_permlane16_swap_b32_e32 v30, v28
	v_max_f32_e32 v28, v28, v30
	v_mov_b32_e32 v30, v29
	v_max_f32_e32 v148, v144, v28
	s_nop 0
	v_permlane16_swap_b32_e32 v30, v29
	v_sub_f32_e32 v28, v144, v148
	v_exp_f32_e32 v52, v28
	v_sub_f32_e32 v28, v68, v148
	v_max_f32_e32 v54, v29, v30
	v_exp_f32_e32 v28, v28
	v_sub_f32_e32 v30, v69, v148
	v_exp_f32_e32 v30, v30
	v_sub_f32_e32 v31, v70, v148
	v_exp_f32_e32 v31, v31
	v_sub_f32_e32 v55, v71, v148
	v_max_f32_e32 v149, v146, v54
	v_exp_f32_e32 v55, v55
	v_sub_f32_e32 v68, v72, v148
	v_sub_f32_e32 v44, v44, v149
	v_exp_f32_e32 v68, v68
	v_sub_f32_e32 v69, v73, v148
	v_exp_f32_e32 v44, v44
	v_sub_f32_e32 v45, v45, v149
	v_exp_f32_e32 v69, v69
	v_sub_f32_e32 v70, v74, v148
	v_exp_f32_e32 v45, v45
	v_sub_f32_e32 v46, v46, v149
	v_add_f32_e32 v29, v30, v28
	v_exp_f32_e32 v70, v70
	v_sub_f32_e32 v71, v75, v148
	v_exp_f32_e32 v46, v46
	v_sub_f32_e32 v47, v47, v149
	v_add_f32_e32 v29, v31, v29
	v_exp_f32_e32 v71, v71
	v_exp_f32_e32 v47, v47
	v_sub_f32_e32 v20, v20, v149
	v_add_f32_e32 v29, v55, v29
	v_sub_f32_e32 v53, v146, v149
	v_exp_f32_e32 v20, v20
	v_sub_f32_e32 v21, v21, v149
	v_add_f32_e32 v29, v68, v29
	v_exp_f32_e32 v54, v53
	v_exp_f32_e32 v21, v21
	v_add_f32_e32 v29, v69, v29
	v_add_f32_e32 v53, v45, v44
	v_add_f32_e32 v29, v70, v29
	v_add_f32_e32 v53, v46, v53
	v_add_f32_e32 v144, v71, v29
	v_cvt_pk_bf16_f32 v29, v31, v55
	v_add_f32_e32 v53, v47, v53
	v_cndmask_b32_e64 v55, v20, 0, s[46:47]
	v_add_f32_e32 v20, v55, v53
	v_cndmask_b32_e64 v53, v21, 0, s[48:49]
	v_sub_f32_e32 v21, v22, v149
	v_exp_f32_e32 v21, v21
	v_cvt_pk_bf16_f32 v28, v28, v30
	v_cvt_pk_bf16_f32 v30, v68, v69
	v_add_f32_e32 v20, v53, v20
	v_cndmask_b32_e64 v68, v21, 0, s[50:51]
	v_sub_f32_e32 v21, v23, v149
	v_exp_f32_e32 v21, v21
	v_add_f32_e32 v20, v68, v20
	v_fmac_f32_e32 v144, v145, v52
	v_cvt_pk_bf16_f32 v31, v70, v71
	v_cndmask_b32_e64 v23, v21, 0, s[52:53]
	v_add_f32_e32 v145, v23, v20
	v_cvt_pk_bf16_f32 v20, v44, v45
	v_cvt_pk_bf16_f32 v21, v46, v47
	v_pk_mul_f32 v[46:47], v[94:95], v[52:53] op_sel_hi:[1,0]
	v_pk_mul_f32 v[44:45], v[92:93], v[52:53] op_sel_hi:[1,0]
	v_cvt_pk_bf16_f32 v22, v55, v53
	v_cvt_pk_bf16_f32 v23, v68, v23
	s_waitcnt lgkmcnt(10)
	v_mfma_f32_16x16x32_bf16 v[96:99], v[140:143], v[28:31], v[44:47]
	v_fmac_f32_e32 v145, v147, v54
	s_nop 1
	v_pk_mul_f32 v[46:47], v[102:103], v[54:55] op_sel_hi:[1,0]
	v_pk_mul_f32 v[44:45], v[100:101], v[54:55] op_sel_hi:[1,0]
	s_nop 1
	v_mfma_f32_16x16x32_bf16 v[100:103], v[140:143], v[20:23], v[44:47]
	s_nop 2
	v_mul_f32_e64 v46, v106, v52
	v_mul_f32_e64 v47, v107, v52
	v_pk_mul_f32 v[44:45], v[104:105], v[52:53] op_sel_hi:[1,0]
	s_waitcnt lgkmcnt(8)
	s_nop 0
	v_mfma_f32_16x16x32_bf16 v[104:107], v[136:139], v[28:31], v[44:47]
	s_nop 2
	v_mul_f32_e64 v46, v110, v54
	v_mul_f32_e64 v47, v111, v54
	v_pk_mul_f32 v[44:45], v[108:109], v[54:55] op_sel_hi:[1,0]
	s_nop 1
	v_mfma_f32_16x16x32_bf16 v[108:111], v[136:139], v[20:23], v[44:47]
	s_nop 2
	v_mul_f32_e64 v46, v114, v52
	v_mul_f32_e64 v47, v115, v52
	v_pk_mul_f32 v[44:45], v[112:113], v[52:53] op_sel_hi:[1,0]
	s_waitcnt lgkmcnt(6)
	s_nop 0
	v_mfma_f32_16x16x32_bf16 v[112:115], v[132:135], v[28:31], v[44:47]
	s_nop 2
	v_mul_f32_e64 v46, v118, v54
	v_mul_f32_e64 v47, v119, v54
	v_pk_mul_f32 v[44:45], v[116:117], v[54:55] op_sel_hi:[1,0]
	s_nop 1
	v_mfma_f32_16x16x32_bf16 v[116:119], v[132:135], v[20:23], v[44:47]
	s_nop 2
	v_mul_f32_e64 v46, v122, v52
	v_mul_f32_e64 v47, v123, v52
	v_pk_mul_f32 v[44:45], v[120:121], v[52:53] op_sel_hi:[1,0]
	s_waitcnt lgkmcnt(4)
	s_nop 0
	v_mfma_f32_16x16x32_bf16 v[120:123], v[128:131], v[28:31], v[44:47]
	v_mul_f32_e64 v30, v126, v54
	v_mul_f32_e64 v31, v127, v54
	v_pk_mul_f32 v[28:29], v[124:125], v[54:55] op_sel_hi:[1,0]
	s_nop 1
	v_mfma_f32_16x16x32_bf16 v[124:127], v[128:131], v[20:23], v[28:31]
	v_add_u32_e32 v20, s76, v222
	v_med3_i32 v20, v20, 0, s75
	v_lshl_add_u32 v20, v20, 9, v152
	global_load_dwordx4 v[68:71], v20, s[98:99]
	v_add_u32_e32 v20, s76, v223
	v_med3_i32 v20, v20, 0, s75
	v_lshl_add_u32 v20, v20, 9, v152
	global_load_dwordx4 v[72:75], v20, s[98:99]
	v_add_u32_e32 v20, s76, v224
	v_med3_i32 v20, v20, 0, s75
	v_lshl_add_u32 v20, v20, 9, v152
	global_load_dwordx4 v[76:79], v20, s[98:99]
	v_add_u32_e32 v20, s76, v225
	v_med3_i32 v20, v20, 0, s75
	v_lshl_add_u32 v20, v20, 9, v152
	global_load_dwordx4 v[92:95], v20, s[98:99]
	v_add_u32_e32 v20, s76, v226
	v_med3_i32 v20, v20, 0, s75
	v_lshl_add_u32 v20, v20, 9, v158
	global_load_dwordx4 v[52:55], v20, s[100:101]
	global_load_dwordx4 v[44:47], v20, s[100:101] offset:64
	v_add_u32_e32 v20, s76, v227
	v_med3_i32 v20, v20, 0, s75
	v_lshl_add_u32 v20, v20, 9, v158
	global_load_dwordx4 v[28:31], v20, s[100:101]
	s_nop 0
	global_load_dwordx4 v[20:23], v20, s[100:101] offset:64
	ds_read_b64_tr_b16 v[142:143], v169 offset:6912
	ds_read_b64_tr_b16 v[140:141], v169 offset:4608
	ds_read_b64_tr_b16 v[136:137], v169 offset:4640
	ds_read_b64_tr_b16 v[138:139], v169 offset:6944
	ds_read_b64_tr_b16 v[132:133], v169 offset:4672
	ds_read_b64_tr_b16 v[134:135], v169 offset:6976
	ds_read_b64_tr_b16 v[128:129], v169 offset:4704
	ds_read_b64_tr_b16 v[130:131], v169 offset:7008
	s_waitcnt vmcnt(15)
	ds_write_b128 v241, v[60:63]
	s_waitcnt vmcnt(14)
	ds_write_b128 v242, v[80:83]
	s_waitcnt vmcnt(13)
	ds_write_b128 v243, v[84:87]
	s_waitcnt vmcnt(12)
	ds_write_b128 v244, v[88:91]
	v_mfma_f32_16x16x32_bf16 v[60:63], v[64:67], v[4:7], 0
	v_mfma_f32_16x16x32_bf16 v[80:83], v[40:43], v[4:7], 0
	v_mfma_f32_16x16x32_bf16 v[40:43], v[40:43], v[12:15], 0
	v_mfma_f32_16x16x32_bf16 v[60:63], v[48:51], v[8:11], v[60:63]
	v_mfma_f32_16x16x32_bf16 v[80:83], v[16:19], v[8:11], v[80:83]
	v_mfma_f32_16x16x32_bf16 v[16:19], v[16:19], v[0:3], v[40:43]
	s_nop 4
	v_sub_u32_e32 v40, v199, v176
	v_mfma_f32_16x16x32_bf16 v[64:67], v[64:67], v[12:15], 0
	v_add_u32_e32 v43, 1, v40
	v_cmp_gt_u32_e64 s[0:1], v43, v175
	v_cmp_gt_u32_e32 vcc, v40, v175
	s_nop 0
	v_cndmask_b32_e64 v61, v61, v246, s[0:1]
	s_nop 0
	v_cndmask_b32_e32 v60, v60, v246, vcc
	v_mfma_f32_16x16x32_bf16 v[48:51], v[48:51], v[0:3], v[64:67]
	v_max_f32_e32 v42, v60, v61
	v_add_u32_e32 v43, 2, v40
	v_cmp_gt_u32_e64 s[22:23], v43, v175
	v_add_u32_e32 v64, 3, v40
	v_cmp_gt_u32_e64 s[24:25], v64, v175
	v_cndmask_b32_e64 v62, v62, v246, s[22:23]
	v_sub_u32_e32 v41, v199, v181
	v_cndmask_b32_e64 v63, v63, v246, s[24:25]
	v_max3_f32 v42, v42, v62, v63
	v_add_u32_e32 v43, 16, v40
	v_add_u32_e32 v64, 17, v40
	v_cmp_gt_u32_e64 s[26:27], v43, v175
	v_cmp_gt_u32_e64 s[28:29], v64, v175
	v_cmp_gt_u32_e64 s[38:39], v41, v252
	v_cndmask_b32_e64 v80, v80, v246, s[26:27]
	v_cndmask_b32_e64 v81, v81, v246, s[28:29]
	v_max3_f32 v42, v42, v80, v81
	v_add_u32_e32 v43, 18, v40
	v_add_u32_e32 v40, 19, v40
	v_cmp_gt_u32_e64 s[30:31], v43, v175
	v_cmp_gt_u32_e64 s[34:35], v40, v175
	v_add_u32_e32 v64, 3, v41
	v_cndmask_b32_e64 v82, v82, v246, s[30:31]
	v_cndmask_b32_e64 v83, v83, v246, s[34:35]
	v_max3_f32 v40, v42, v82, v83
	v_add_u32_e32 v43, 1, v41
	v_cmp_gt_u32_e64 s[40:41], v43, v252
	v_cndmask_b32_e64 v48, v48, v246, s[38:39]
	s_nop 0
	v_cndmask_b32_e64 v49, v49, v246, s[40:41]
	v_max_f32_e32 v42, v48, v49
	v_add_u32_e32 v43, 2, v41
	v_cmp_gt_u32_e64 s[42:43], v43, v252
	v_cmp_gt_u32_e64 s[44:45], v64, v252
	s_nop 0
	v_cndmask_b32_e64 v50, v50, v246, s[42:43]
	v_cndmask_b32_e64 v51, v51, v246, s[44:45]
	v_max3_f32 v42, v42, v50, v51
	v_add_u32_e32 v43, 16, v41
	v_add_u32_e32 v64, 17, v41
	v_cmp_gt_u32_e64 s[46:47], v43, v252
	v_cmp_gt_u32_e64 s[48:49], v64, v252
	s_nop 0
	v_cndmask_b32_e64 v16, v16, v246, s[46:47]
	v_cndmask_b32_e64 v17, v17, v246, s[48:49]
	v_max3_f32 v42, v42, v16, v17
	v_add_u32_e32 v43, 18, v41
	v_add_u32_e32 v41, 19, v41
	v_cmp_gt_u32_e64 s[50:51], v43, v252
	v_cmp_gt_u32_e64 s[52:53], v41, v252
	s_nop 0
	v_cndmask_b32_e64 v18, v18, v246, s[50:51]
	v_cndmask_b32_e64 v19, v19, v246, s[52:53]
	v_max3_f32 v41, v42, v18, v19
	v_mov_b32_e32 v42, v40
	s_nop 1
	v_permlane32_swap_b32_e32 v42, v40
	v_max_f32_e32 v40, v40, v42
	v_mov_b32_e32 v42, v41
	s_nop 1
	v_permlane32_swap_b32_e32 v42, v41
	v_max_f32_e32 v41, v41, v42
	v_mov_b32_e32 v42, v40
	s_nop 1
	v_permlane16_swap_b32_e32 v42, v40
	v_max3_f32 v147, v148, v40, v42
	v_sub_f32_e32 v40, v148, v147
	v_exp_f32_e32 v84, v40
	v_sub_f32_e32 v40, v60, v147
	v_exp_f32_e32 v40, v40
	v_mov_b32_e32 v42, v41
	s_nop 1
	v_permlane16_swap_b32_e32 v42, v41
	v_cndmask_b32_e64 v85, v40, 0, vcc
	v_sub_f32_e32 v40, v61, v147
	v_exp_f32_e32 v40, v40
	v_max3_f32 v146, v149, v41, v42
	v_cndmask_b32_e64 v61, v40, 0, s[0:1]
	v_sub_f32_e32 v40, v62, v147
	v_exp_f32_e32 v40, v40
	v_sub_f32_e32 v48, v48, v146
	v_sub_f32_e32 v16, v16, v146
	v_exp_f32_e32 v48, v48
	v_cndmask_b32_e64 v62, v40, 0, s[22:23]
	v_sub_f32_e32 v40, v63, v147
	v_exp_f32_e32 v40, v40
	v_exp_f32_e32 v16, v16
	v_cndmask_b32_e64 v86, v48, 0, s[38:39]
	v_sub_f32_e32 v48, v49, v146
	v_cndmask_b32_e64 v63, v40, 0, s[24:25]
	v_sub_f32_e32 v40, v80, v147
	v_exp_f32_e32 v40, v40
	v_cndmask_b32_e64 v90, v16, 0, s[46:47]
	v_sub_f32_e32 v16, v17, v146
	v_exp_f32_e32 v48, v48
	v_cndmask_b32_e64 v80, v40, 0, s[26:27]
	v_sub_f32_e32 v40, v81, v147
	v_exp_f32_e32 v40, v40
	v_exp_f32_e32 v16, v16
	v_cndmask_b32_e64 v87, v48, 0, s[40:41]
	v_sub_f32_e32 v48, v50, v146
	v_cndmask_b32_e64 v81, v40, 0, s[28:29]
	v_sub_f32_e32 v40, v82, v147
	v_exp_f32_e32 v40, v40
	v_cndmask_b32_e64 v91, v16, 0, s[48:49]
	v_sub_f32_e32 v16, v18, v146
	v_exp_f32_e32 v48, v48
	v_exp_f32_e32 v16, v16
	v_cndmask_b32_e64 v82, v40, 0, s[30:31]
	v_sub_f32_e32 v40, v83, v147
	v_exp_f32_e32 v40, v40
	v_cndmask_b32_e64 v88, v48, 0, s[42:43]
	v_sub_f32_e32 v48, v51, v146
	v_cndmask_b32_e64 v148, v16, 0, s[50:51]
	v_sub_f32_e32 v16, v19, v146
	v_sub_f32_e32 v60, v149, v146
	v_exp_f32_e32 v48, v48
	v_exp_f32_e32 v16, v16
	v_exp_f32_e32 v60, v60
	v_cndmask_b32_e64 v83, v40, 0, s[34:35]
	v_cvt_pk_bf16_f32 v40, v85, v61
	v_cvt_pk_bf16_f32 v41, v62, v63
	v_cvt_pk_bf16_f32 v42, v80, v81
	v_cvt_pk_bf16_f32 v43, v82, v83
	v_cndmask_b32_e64 v89, v48, 0, s[44:45]
	v_cndmask_b32_e64 v149, v16, 0, s[52:53]
	v_pk_mul_f32 v[50:51], v[98:99], v[84:85] op_sel_hi:[1,0]
	v_pk_mul_f32 v[48:49], v[96:97], v[84:85] op_sel_hi:[1,0]
	v_cvt_pk_bf16_f32 v16, v86, v87
	v_cvt_pk_bf16_f32 v17, v88, v89
	v_cvt_pk_bf16_f32 v18, v90, v91
	v_cvt_pk_bf16_f32 v19, v148, v149
	s_waitcnt lgkmcnt(10)
	v_mfma_f32_16x16x32_bf16 v[64:67], v[140:143], v[40:43], v[48:51]
	s_cselect_b64 s[38:39], -1, 0
	s_add_i32 s0, s76, 0xfffffc00
	s_min_i32 s1, s0, 0
	v_pk_mul_f32 v[50:51], v[102:103], v[60:61] op_sel_hi:[1,0]
	v_pk_mul_f32 v[48:49], v[100:101], v[60:61] op_sel_hi:[1,0]
	s_sub_i32 s1, 15, s1
	s_ashr_i32 s1, s1, 4
	v_mfma_f32_16x16x32_bf16 v[100:103], v[140:143], v[16:19], v[48:51]
	s_sub_i32 s0, s75, s0
	s_ashr_i32 s0, s0, 4
	s_or_b32 s40, s76, 8
	v_pk_mul_f32 v[50:51], v[106:107], v[84:85] op_sel_hi:[1,0]
	v_pk_mul_f32 v[48:49], v[104:105], v[84:85] op_sel_hi:[1,0]
	s_lshl_b32 s56, s56, 7
	s_add_i32 s71, s71, s78
	s_waitcnt lgkmcnt(8)
	v_mfma_f32_16x16x32_bf16 v[104:107], v[136:139], v[40:43], v[48:51]
	s_nop 2
	v_mul_f32_e64 v50, v110, v60
	v_mul_f32_e64 v51, v111, v60
	v_pk_mul_f32 v[48:49], v[108:109], v[60:61] op_sel_hi:[1,0]
	s_nop 1
	v_mfma_f32_16x16x32_bf16 v[108:111], v[136:139], v[16:19], v[48:51]
	s_nop 2
	v_mul_f32_e64 v50, v114, v84
	v_mul_f32_e64 v51, v115, v84
	v_pk_mul_f32 v[48:49], v[112:113], v[84:85] op_sel_hi:[1,0]
	s_waitcnt lgkmcnt(6)
	s_nop 0
	v_mfma_f32_16x16x32_bf16 v[112:115], v[132:135], v[40:43], v[48:51]
	s_nop 2
	v_mul_f32_e64 v50, v118, v60
	v_mul_f32_e64 v51, v119, v60
	v_pk_mul_f32 v[48:49], v[116:117], v[60:61] op_sel_hi:[1,0]
	s_nop 1
	v_mfma_f32_16x16x32_bf16 v[116:119], v[132:135], v[16:19], v[48:51]
	s_nop 2
	v_mul_f32_e64 v50, v122, v84
	v_mul_f32_e64 v51, v123, v84
	v_pk_mul_f32 v[48:49], v[120:121], v[84:85] op_sel_hi:[1,0]
	s_waitcnt lgkmcnt(4)
	s_nop 0
	v_mfma_f32_16x16x32_bf16 v[120:123], v[128:131], v[40:43], v[48:51]
	v_mul_f32_e64 v42, v126, v60
	v_mul_f32_e64 v43, v127, v60
	v_pk_mul_f32 v[40:41], v[124:125], v[60:61] op_sel_hi:[1,0]
	s_nop 1
	v_mfma_f32_16x16x32_bf16 v[124:127], v[128:131], v[16:19], v[40:43]
	v_add_f32_e32 v16, v87, v86
	v_add_f32_e32 v16, v88, v16
	v_add_f32_e32 v16, v89, v16
	v_add_f32_e32 v16, v90, v16
	v_add_f32_e32 v16, v91, v16
	v_add_f32_e32 v16, v148, v16
	v_add_f32_e32 v151, v149, v16
	v_add_f32_e32 v16, v61, v85
	v_add_f32_e32 v16, v62, v16
	v_add_f32_e32 v16, v63, v16
	v_add_f32_e32 v16, v80, v16
	v_add_f32_e32 v16, v81, v16
	v_add_f32_e32 v16, v82, v16
	v_fmac_f32_e32 v151, v145, v60
	v_add_f32_e32 v145, v83, v16
	v_add_u32_e32 v16, s76, v213
	v_fmac_f32_e32 v145, v144, v84
	v_ashrrev_i32_e32 v148, 4, v250
	v_med3_i32 v16, v16, 0, s75
	v_lshl_add_u32 v16, v16, 9, v152
	global_load_dwordx4 v[80:83], v16, s[98:99]
	v_add_u32_e32 v16, s76, v215
	v_max_i32_e32 v150, s1, v148
	s_nop 0
	v_med3_i32 v16, v16, 0, s75
	v_lshl_add_u32 v16, v16, 9, v152
	global_load_dwordx4 v[84:87], v16, s[98:99]
	v_add_u32_e32 v16, s76, v217
	v_med3_i32 v16, v16, 0, s75
	v_lshl_add_u32 v16, v16, 9, v152
	global_load_dwordx4 v[88:91], v16, s[98:99]
	v_add_u32_e32 v16, s76, v219
	v_med3_i32 v16, v16, 0, s75
	v_lshl_add_u32 v16, v16, 9, v152
	global_load_dwordx4 v[96:99], v16, s[98:99]
	v_min_i32_e32 v16, s75, v251
	v_cndmask_b32_e64 v16, v16, 0, s[38:39]
	v_lshl_add_u32 v16, v16, 9, v158
	global_load_dwordx4 v[48:51], v16, s[100:101]
	global_load_dwordx4 v[60:63], v16, s[100:101] offset:64
	v_add_u32_e32 v16, s76, v228
	v_med3_i32 v16, v16, 0, s75
	v_lshl_add_u32 v16, v16, 9, v158
	global_load_dwordx4 v[40:43], v16, s[100:101]
	s_nop 0
	global_load_dwordx4 v[16:19], v16, s[100:101] offset:64
	ds_read_b64_tr_b16 v[142:143], v169 offset:2304
	ds_read_b64_tr_b16 v[140:141], v169
	ds_read_b64_tr_b16 v[136:137], v169 offset:32
	ds_read_b64_tr_b16 v[138:139], v169 offset:2336
	ds_read_b64_tr_b16 v[132:133], v169 offset:64
	ds_read_b64_tr_b16 v[134:135], v169 offset:2368
	ds_read_b64_tr_b16 v[128:129], v169 offset:96
	ds_read_b64_tr_b16 v[130:131], v169 offset:2400
	s_waitcnt vmcnt(15)
	ds_write_b128 v241, v[68:71] offset:4608
	s_waitcnt vmcnt(14)
	ds_write_b128 v242, v[72:75] offset:4608
	s_waitcnt vmcnt(13)
	ds_write_b128 v243, v[76:79] offset:4608
	s_waitcnt vmcnt(12)
	ds_write_b128 v244, v[92:95] offset:4608
	v_mfma_f32_16x16x32_bf16 v[72:75], v[32:35], v[4:7], 0
	v_mfma_f32_16x16x32_bf16 v[68:71], v[56:59], v[4:7], 0
	v_mfma_f32_16x16x32_bf16 v[72:75], v[24:27], v[8:11], v[72:75]
	v_mfma_f32_16x16x32_bf16 v[68:71], v[36:39], v[8:11], v[68:71]
	s_nop 5
	v_add_u32_e32 v25, 0x800, v250
	v_ashrrev_i32_e32 v25, 4, v25
	v_min3_i32 v25, v25, s0, v248
	v_sub_u32_e32 v26, v154, v150
	v_sub_u32_e32 v149, v25, v150
	v_add_u32_e32 v27, 1, v26
	v_cmp_gt_u32_e64 s[0:1], v27, v149
	v_cmp_gt_u32_e32 vcc, v26, v149
	s_nop 0
	v_cndmask_b32_e64 v69, v69, v246, s[0:1]
	s_nop 0
	v_cndmask_b32_e32 v68, v68, v246, vcc
	v_max_f32_e32 v25, v68, v69
	v_add_u32_e32 v27, 2, v26
	v_add_u32_e32 v32, 3, v26
	v_cmp_gt_u32_e64 s[22:23], v27, v149
	v_cmp_gt_u32_e64 s[24:25], v32, v149
	s_nop 0
	v_cndmask_b32_e64 v70, v70, v246, s[22:23]
	s_nop 0
	v_cndmask_b32_e64 v71, v71, v246, s[24:25]
	v_max3_f32 v25, v25, v70, v71
	v_add_u32_e32 v27, 16, v26
	v_add_u32_e32 v32, 17, v26
	v_cmp_gt_u32_e64 s[26:27], v27, v149
	v_cmp_gt_u32_e64 s[28:29], v32, v149
	s_nop 0
	v_cndmask_b32_e64 v72, v72, v246, s[26:27]
	v_cndmask_b32_e64 v73, v73, v246, s[28:29]
	v_max3_f32 v25, v25, v72, v73
	v_add_u32_e32 v27, 18, v26
	v_add_u32_e32 v26, 19, v26
	v_cmp_gt_u32_e64 s[30:31], v27, v149
	v_cmp_gt_u32_e64 s[34:35], v26, v149
	s_nop 0
	v_cndmask_b32_e64 v74, v74, v246, s[30:31]
	v_cndmask_b32_e64 v75, v75, v246, s[34:35]
	v_max3_f32 v25, v25, v74, v75
	v_mov_b32_e32 v27, v25
	s_nop 1
	v_permlane32_swap_b32_e32 v27, v25
	v_max_f32_e32 v25, v25, v27
	s_nop 1
	v_mov_b32_e32 v27, v25
	s_nop 1
	v_permlane16_swap_b32_e32 v27, v25
	v_max3_f32 v144, v147, v25, v27
	v_sub_f32_e32 v25, v147, v144
	v_exp_f32_e32 v56, v25
	v_sub_f32_e32 v25, v68, v144
	v_exp_f32_e32 v25, v25
	v_sub_f32_e32 v32, v69, v144
	v_exp_f32_e32 v32, v32
	v_sub_f32_e32 v33, v70, v144
	v_exp_f32_e32 v33, v33
	v_sub_f32_e32 v34, v71, v144
	v_exp_f32_e32 v34, v34
	v_sub_f32_e32 v35, v72, v144
	v_exp_f32_e32 v35, v35
	v_sub_f32_e32 v38, v73, v144
	v_exp_f32_e32 v38, v38
	v_sub_f32_e32 v39, v74, v144
	v_add_f32_e32 v27, v32, v25
	v_exp_f32_e32 v39, v39
	v_sub_f32_e32 v57, v75, v144
	v_add_f32_e32 v27, v33, v27
	v_exp_f32_e32 v57, v57
	v_add_f32_e32 v27, v34, v27
	v_add_f32_e32 v27, v35, v27
	v_add_f32_e32 v27, v38, v27
	v_add_f32_e32 v27, v39, v27
	v_add_f32_e32 v147, v57, v27
	v_fmac_f32_e32 v147, v145, v56
	v_mov_b32_e32 v145, v146
	v_cvt_pk_bf16_f32 v32, v25, v32
	v_mov_b32_e32 v58, 1.0
	v_cvt_pk_bf16_f32 v33, v33, v34
	v_mov_b32_e32 v25, 0
	v_cvt_pk_bf16_f32 v34, v35, v38
	v_cvt_pk_bf16_f32 v35, v39, v57
	v_mov_b32_e32 v27, 0
	v_pk_mul_f32 v[38:39], v[66:67], v[56:57] op_sel_hi:[1,0]
	v_pk_mul_f32 v[36:37], v[64:65], v[56:57] op_sel_hi:[1,0]
	v_add_f32_e32 v146, v27, v25
	v_cvt_pk_bf16_f32 v24, v25, 0
	v_cvt_pk_bf16_f32 v26, v27, 0
	v_mov_b32_e32 v25, v153
	v_mov_b32_e32 v27, v153
	s_waitcnt lgkmcnt(10)
	v_mfma_f32_16x16x32_bf16 v[76:79], v[140:143], v[32:35], v[36:39]
	v_fmac_f32_e32 v146, v151, v58
	s_nop 1
	v_pk_mul_f32 v[38:39], v[102:103], v[58:59] op_sel_hi:[1,0]
	v_pk_mul_f32 v[36:37], v[100:101], v[58:59] op_sel_hi:[1,0]
	s_nop 1
	v_mfma_f32_16x16x32_bf16 v[100:103], v[140:143], v[24:27], v[36:39]
	s_nop 2
	v_mul_f32_e64 v38, v106, v56
	v_mul_f32_e64 v39, v107, v56
	v_pk_mul_f32 v[36:37], v[104:105], v[56:57] op_sel_hi:[1,0]
	s_waitcnt lgkmcnt(8)
	s_nop 0
	v_mfma_f32_16x16x32_bf16 v[104:107], v[136:139], v[32:35], v[36:39]
	s_nop 2
	v_mul_f32_e64 v38, v110, v58
	v_mul_f32_e64 v39, v111, v58
	v_pk_mul_f32 v[36:37], v[108:109], v[58:59] op_sel_hi:[1,0]
	s_nop 1
	v_mfma_f32_16x16x32_bf16 v[108:111], v[136:139], v[24:27], v[36:39]
	s_nop 2
	v_mul_f32_e64 v38, v114, v56
	v_mul_f32_e64 v39, v115, v56
	v_pk_mul_f32 v[36:37], v[112:113], v[56:57] op_sel_hi:[1,0]
	s_waitcnt lgkmcnt(6)
	s_nop 0
	v_mfma_f32_16x16x32_bf16 v[112:115], v[132:135], v[32:35], v[36:39]
	s_nop 2
	v_mul_f32_e64 v38, v118, v58
	v_mul_f32_e64 v39, v119, v58
	v_pk_mul_f32 v[36:37], v[116:117], v[58:59] op_sel_hi:[1,0]
	s_nop 1
	v_mfma_f32_16x16x32_bf16 v[116:119], v[132:135], v[24:27], v[36:39]
	s_nop 2
	v_mul_f32_e64 v38, v122, v56
	v_mul_f32_e64 v39, v123, v56
	v_pk_mul_f32 v[36:37], v[120:121], v[56:57] op_sel_hi:[1,0]
	v_add_u32_e32 v56, s76, v232
	s_waitcnt lgkmcnt(4)
	v_mfma_f32_16x16x32_bf16 v[120:123], v[128:131], v[32:35], v[36:39]
	v_mul_f32_e64 v34, v126, v58
	v_mul_f32_e64 v35, v127, v58
	v_pk_mul_f32 v[32:33], v[124:125], v[58:59] op_sel_hi:[1,0]
	v_add_u32_e32 v36, s76, v231
	s_nop 0
	v_mfma_f32_16x16x32_bf16 v[124:127], v[128:131], v[24:27], v[32:35]
	v_add_u32_e32 v24, s76, v229
	s_nop 1
	v_add_u32_e32 v32, s76, v230
	v_med3_i32 v24, v24, 0, s75
	v_med3_i32 v32, v32, 0, s75
	v_med3_i32 v36, v36, 0, s75
	v_med3_i32 v56, v56, 0, s75
	v_lshl_add_u32 v36, v36, 9, v152
	v_lshl_add_u32 v56, v56, 9, v152
	global_load_dwordx4 v[36:39], v36, s[98:99]
	global_load_dwordx4 v[92:95], v56, s[98:99]
	v_add_u32_e32 v56, s76, v233
	v_med3_i32 v56, v56, 0, s75
	v_lshl_add_u32 v24, v24, 9, v152
	v_lshl_add_u32 v32, v32, 9, v152
	v_lshl_add_u32 v56, v56, 9, v158
	global_load_dwordx4 v[24:27], v24, s[98:99]
	s_nop 0
	global_load_dwordx4 v[32:35], v32, s[98:99]
	s_nop 0
	global_load_dwordx4 v[72:75], v56, s[100:101]
	global_load_dwordx4 v[68:71], v56, s[100:101] offset:64
	v_add_u32_e32 v56, s76, v234
	v_med3_i32 v56, v56, 0, s75
	v_lshl_add_u32 v56, v56, 9, v158
	global_load_dwordx4 v[64:67], v56, s[100:101]
	s_nop 0
	global_load_dwordx4 v[56:59], v56, s[100:101] offset:64
	ds_read_b64_tr_b16 v[142:143], v169 offset:6912
	ds_read_b64_tr_b16 v[140:141], v169 offset:4608
	ds_read_b64_tr_b16 v[136:137], v169 offset:4640
	ds_read_b64_tr_b16 v[138:139], v169 offset:6944
	ds_read_b64_tr_b16 v[132:133], v169 offset:4672
	ds_read_b64_tr_b16 v[134:135], v169 offset:6976
	ds_read_b64_tr_b16 v[128:129], v169 offset:4704
	ds_read_b64_tr_b16 v[130:131], v169 offset:7008
	s_waitcnt vmcnt(15)
	ds_write_b128 v241, v[80:83]
	s_waitcnt vmcnt(14)
	ds_write_b128 v242, v[84:87]
	s_waitcnt vmcnt(13)
	ds_write_b128 v243, v[88:91]
	s_waitcnt vmcnt(12)
	ds_write_b128 v244, v[96:99]
	v_mfma_f32_16x16x32_bf16 v[80:83], v[52:55], v[4:7], 0
	v_mfma_f32_16x16x32_bf16 v[84:87], v[28:31], v[4:7], 0
	v_mfma_f32_16x16x32_bf16 v[80:83], v[44:47], v[8:11], v[80:83]
	v_mfma_f32_16x16x32_bf16 v[84:87], v[20:23], v[8:11], v[84:87]
	s_nop 5
	v_sub_u32_e32 v21, v187, v150
	v_add_u32_e32 v23, 1, v21
	v_cmp_gt_u32_e64 s[0:1], v23, v149
	v_cmp_gt_u32_e32 vcc, v21, v149
	s_nop 0
	v_cndmask_b32_e64 v81, v81, v246, s[0:1]
	s_nop 0
	v_cndmask_b32_e32 v80, v80, v246, vcc
	v_max_f32_e32 v22, v80, v81
	v_add_u32_e32 v23, 2, v21
	v_add_u32_e32 v28, 3, v21
	v_cmp_gt_u32_e64 s[22:23], v23, v149
	v_cmp_gt_u32_e64 s[24:25], v28, v149
	s_nop 0
	v_cndmask_b32_e64 v82, v82, v246, s[22:23]
	v_cndmask_b32_e64 v83, v83, v246, s[24:25]
	v_max3_f32 v22, v22, v82, v83
	v_add_u32_e32 v23, 16, v21
	v_add_u32_e32 v28, 17, v21
	v_cmp_gt_u32_e64 s[26:27], v23, v149
	v_cmp_gt_u32_e64 s[28:29], v28, v149
	s_nop 0
	v_cndmask_b32_e64 v84, v84, v246, s[26:27]
	v_cndmask_b32_e64 v85, v85, v246, s[28:29]
	v_max3_f32 v22, v22, v84, v85
	v_add_u32_e32 v23, 18, v21
	v_add_u32_e32 v21, 19, v21
	v_cmp_gt_u32_e64 s[30:31], v23, v149
	v_cmp_gt_u32_e64 s[34:35], v21, v149
	s_nop 0
	v_cndmask_b32_e64 v86, v86, v246, s[30:31]
	v_cndmask_b32_e64 v87, v87, v246, s[34:35]
	v_max3_f32 v21, v22, v86, v87
	v_mov_b32_e32 v23, v21
	s_nop 1
	v_permlane32_swap_b32_e32 v23, v21
	v_max_f32_e32 v21, v21, v23
	s_nop 1
	v_mov_b32_e32 v23, v21
	s_nop 1
	v_permlane16_swap_b32_e32 v23, v21
	v_max3_f32 v175, v144, v21, v23
	v_sub_f32_e32 v21, v144, v175
	v_exp_f32_e32 v144, v21
	v_sub_f32_e32 v21, v80, v175
	v_sub_f32_e32 v28, v81, v175
	v_exp_f32_e32 v21, v21
	v_exp_f32_e32 v28, v28
	v_sub_f32_e32 v30, v82, v175
	v_exp_f32_e32 v30, v30
	v_sub_f32_e32 v31, v83, v175
	v_exp_f32_e32 v31, v31
	v_sub_f32_e32 v45, v84, v175
	v_exp_f32_e32 v45, v45
	v_sub_f32_e32 v46, v85, v175
	v_mov_b32_e32 v176, v145
	v_exp_f32_e32 v46, v46
	v_sub_f32_e32 v47, v86, v175
	v_cvt_pk_bf16_f32 v80, v21, v28
	v_add_f32_e32 v23, v28, v21
	v_exp_f32_e32 v47, v47
	v_sub_f32_e32 v52, v87, v175
	v_mov_b32_e32 v84, 1.0
	v_add_f32_e32 v23, v30, v23
	v_exp_f32_e32 v52, v52
	v_add_f32_e32 v23, v31, v23
	v_add_f32_e32 v23, v45, v23
	v_add_f32_e32 v23, v46, v23
	v_add_f32_e32 v23, v47, v23
	v_mov_b32_e32 v21, 0
	v_add_f32_e32 v151, v52, v23
	v_mov_b32_e32 v23, 0
	v_fmac_f32_e32 v151, v147, v144
	v_cvt_pk_bf16_f32 v81, v30, v31
	v_add_f32_e32 v147, v23, v21
	v_cvt_pk_bf16_f32 v20, v21, 0
	v_cvt_pk_bf16_f32 v22, v23, 0
	v_mov_b32_e32 v21, v153
	v_mov_b32_e32 v23, v153
	v_pk_mul_f32 v[30:31], v[78:79], v[144:145] op_sel_hi:[1,0]
	v_pk_mul_f32 v[28:29], v[76:77], v[144:145] op_sel_hi:[1,0]
	v_pk_mul_f32 v[78:79], v[110:111], v[84:85] op_sel_hi:[1,0]
	v_pk_mul_f32 v[76:77], v[108:109], v[84:85] op_sel_hi:[1,0]
	v_cvt_pk_bf16_f32 v82, v45, v46
	v_cvt_pk_bf16_f32 v83, v47, v52
	s_waitcnt lgkmcnt(8)
	v_mfma_f32_16x16x32_bf16 v[88:91], v[136:139], v[20:23], v[76:79]
	v_mul_f32_e64 v46, v102, v84
	v_mul_f32_e64 v47, v103, v84
	v_pk_mul_f32 v[44:45], v[100:101], v[84:85] op_sel_hi:[1,0]
	v_pk_mul_f32 v[54:55], v[106:107], v[144:145] op_sel_hi:[1,0]
	v_pk_mul_f32 v[78:79], v[114:115], v[144:145] op_sel_hi:[1,0]
	v_pk_mul_f32 v[76:77], v[112:113], v[144:145] op_sel_hi:[1,0]
	v_pk_mul_f32 v[52:53], v[104:105], v[144:145] op_sel_hi:[1,0]
	v_mfma_f32_16x16x32_bf16 v[44:47], v[140:143], v[20:23], v[44:47]
	v_fmac_f32_e32 v147, v146, v84
	s_waitcnt lgkmcnt(6)
	v_mfma_f32_16x16x32_bf16 v[96:99], v[132:135], v[80:83], v[76:79]
	s_nop 2
	v_mul_f32_e64 v78, v118, v84
	v_mul_f32_e64 v79, v119, v84
	v_pk_mul_f32 v[76:77], v[116:117], v[84:85] op_sel_hi:[1,0]
	v_mfma_f32_16x16x32_bf16 v[28:31], v[140:143], v[80:83], v[28:31]
	s_nop 0
	v_mfma_f32_16x16x32_bf16 v[100:103], v[132:135], v[20:23], v[76:79]
	s_nop 2
	v_mul_f32_e64 v78, v122, v144
	v_mul_f32_e64 v79, v123, v144
	v_pk_mul_f32 v[76:77], v[120:121], v[144:145] op_sel_hi:[1,0]
	v_mfma_f32_16x16x32_bf16 v[52:55], v[136:139], v[80:83], v[52:55]
	s_waitcnt lgkmcnt(4)
	v_mfma_f32_16x16x32_bf16 v[104:107], v[128:131], v[80:83], v[76:79]
	s_nop 2
	v_mul_f32_e64 v78, v126, v84
	v_mul_f32_e64 v79, v127, v84
	v_pk_mul_f32 v[76:77], v[124:125], v[84:85] op_sel_hi:[1,0]
	s_nop 1
	v_mfma_f32_16x16x32_bf16 v[108:111], v[128:131], v[20:23], v[76:79]
	v_add_u32_e32 v20, s76, v235
	v_med3_i32 v20, v20, 0, s75
	v_lshl_add_u32 v20, v20, 9, v152
	global_load_dwordx4 v[112:115], v20, s[98:99]
	v_add_u32_e32 v20, s76, v236
	v_med3_i32 v20, v20, 0, s75
	v_lshl_add_u32 v20, v20, 9, v152
	global_load_dwordx4 v[116:119], v20, s[98:99]
	v_add_u32_e32 v20, s76, v237
	v_med3_i32 v20, v20, 0, s75
	v_lshl_add_u32 v20, v20, 9, v152
	global_load_dwordx4 v[120:123], v20, s[98:99]
	v_add_u32_e32 v20, s76, v238
	v_med3_i32 v20, v20, 0, s75
	v_lshl_add_u32 v20, v20, 9, v152
	global_load_dwordx4 v[124:127], v20, s[98:99]
	v_add_u32_e32 v20, s76, v239
	v_med3_i32 v20, v20, 0, s75
	v_lshl_add_u32 v20, v20, 9, v158
	global_load_dwordx4 v[84:87], v20, s[100:101]
	global_load_dwordx4 v[80:83], v20, s[100:101] offset:64
	v_add_u32_e32 v20, s76, v240
	s_addk_i32 s76, 0xfc08
	s_nop 0
	v_med3_i32 v20, v20, 0, s75
	v_lshl_add_u32 v20, v20, 9, v158
	global_load_dwordx4 v[76:79], v20, s[100:101]
	s_nop 0
	global_load_dwordx4 v[20:23], v20, s[100:101] offset:64
	ds_read_b64_tr_b16 v[142:143], v169 offset:2304
	ds_read_b64_tr_b16 v[140:141], v169
	ds_read_b64_tr_b16 v[136:137], v169 offset:32
	ds_read_b64_tr_b16 v[138:139], v169 offset:2336
	ds_read_b64_tr_b16 v[132:133], v169 offset:64
	ds_read_b64_tr_b16 v[134:135], v169 offset:2368
	ds_read_b64_tr_b16 v[128:129], v169 offset:96
	ds_read_b64_tr_b16 v[130:131], v169 offset:2400
	s_waitcnt vmcnt(13)
	ds_write_b128 v241, v[24:27] offset:4608
	s_waitcnt vmcnt(12)
	ds_write_b128 v242, v[32:35] offset:4608
	ds_write_b128 v243, v[36:39] offset:4608
	ds_write_b128 v244, v[92:95] offset:4608
	v_mfma_f32_16x16x32_bf16 v[24:27], v[48:51], v[4:7], 0
	v_mfma_f32_16x16x32_bf16 v[32:35], v[40:43], v[4:7], 0
	v_mfma_f32_16x16x32_bf16 v[24:27], v[60:63], v[8:11], v[24:27]
	v_mfma_f32_16x16x32_bf16 v[32:35], v[16:19], v[8:11], v[32:35]
	s_nop 7
	v_sub_u32_e32 v17, v192, v150
	v_add_u32_e32 v19, 1, v17
	v_cmp_gt_u32_e64 s[0:1], v19, v149
	v_cmp_gt_u32_e32 vcc, v17, v149
	s_nop 0
	v_cndmask_b32_e64 v25, v25, v246, s[0:1]
	s_nop 0
	v_cndmask_b32_e32 v24, v24, v246, vcc
	v_max_f32_e32 v18, v24, v25
	v_add_u32_e32 v19, 2, v17
	v_add_u32_e32 v37, 3, v17
	v_cmp_gt_u32_e64 s[22:23], v19, v149
	v_cmp_gt_u32_e64 s[24:25], v37, v149
	s_nop 0
	v_cndmask_b32_e64 v26, v26, v246, s[22:23]
	v_cndmask_b32_e64 v27, v27, v246, s[24:25]
	v_max3_f32 v18, v18, v26, v27
	v_add_u32_e32 v19, 16, v17
	v_add_u32_e32 v37, 17, v17
	v_cmp_gt_u32_e64 s[26:27], v19, v149
	v_cmp_gt_u32_e64 s[28:29], v37, v149
	s_nop 0
	v_cndmask_b32_e64 v32, v32, v246, s[26:27]
	v_cndmask_b32_e64 v33, v33, v246, s[28:29]
	v_max3_f32 v18, v18, v32, v33
	v_add_u32_e32 v19, 18, v17
	v_add_u32_e32 v17, 19, v17
	v_cmp_gt_u32_e64 s[30:31], v19, v149
	v_cmp_gt_u32_e64 s[34:35], v17, v149
	s_nop 0
	v_cndmask_b32_e64 v34, v34, v246, s[30:31]
	v_cndmask_b32_e64 v35, v35, v246, s[34:35]
	v_max3_f32 v17, v18, v34, v35
	v_mov_b32_e32 v19, v17
	s_nop 1
	v_permlane32_swap_b32_e32 v19, v17
	v_max_f32_e32 v17, v17, v19
	s_nop 1
	v_mov_b32_e32 v19, v17
	s_nop 1
	v_permlane16_swap_b32_e32 v19, v17
	v_max3_f32 v145, v175, v17, v19
	v_sub_f32_e32 v17, v175, v145
	v_exp_f32_e32 v38, v17
	v_sub_f32_e32 v17, v24, v145
	v_exp_f32_e32 v17, v17
	s_nop 1
	v_cndmask_b32_e64 v37, v17, 0, vcc
	v_sub_f32_e32 v17, v25, v145
	v_exp_f32_e32 v17, v17
	v_mov_b32_e32 v144, v176
	v_cndmask_b32_e64 v60, v17, 0, s[0:1]
	v_sub_f32_e32 v17, v26, v145
	v_exp_f32_e32 v17, v17
	v_cvt_pk_bf16_f32 v24, v37, v60
	v_cndmask_b32_e64 v61, v17, 0, s[22:23]
	v_sub_f32_e32 v17, v27, v145
	v_exp_f32_e32 v17, v17
	v_mov_b32_e32 v39, 0
	v_pk_mul_f32 v[30:31], v[30:31], v[38:39] op_sel_hi:[1,0]
	v_pk_mul_f32 v[28:29], v[28:29], v[38:39] op_sel_hi:[1,0]
	v_cndmask_b32_e64 v62, v17, 0, s[24:25]
	v_sub_f32_e32 v17, v32, v145
	v_exp_f32_e32 v17, v17
	v_cvt_pk_bf16_f32 v25, v61, v62
	v_cvt_pk_bf16_f32 v18, v39, 0
	v_mov_b32_e32 v19, v153
	v_cndmask_b32_e64 v63, v17, 0, s[26:27]
	v_sub_f32_e32 v17, v33, v145
	v_exp_f32_e32 v17, v17
	s_nop 0
	v_cndmask_b32_e64 v33, v17, 0, s[28:29]
	v_sub_f32_e32 v17, v34, v145
	v_exp_f32_e32 v17, v17
	v_cvt_pk_bf16_f32 v26, v63, v33
	v_cndmask_b32_e64 v34, v17, 0, s[30:31]
	v_sub_f32_e32 v17, v35, v145
	v_exp_f32_e32 v17, v17
	s_nop 0
	v_cndmask_b32_e64 v35, v17, 0, s[34:35]
	v_mov_b32_e32 v32, 1.0
	v_cvt_pk_bf16_f32 v27, v34, v35
	v_mov_b32_e32 v36, 0
	v_cvt_pk_bf16_f32 v16, v36, 0
	v_mov_b32_e32 v17, v153
	s_waitcnt lgkmcnt(10)
	v_mfma_f32_16x16x32_bf16 v[40:43], v[140:143], v[24:27], v[28:31]
	s_nop 2
	v_mul_f32_e64 v30, v46, v32
	v_mul_f32_e64 v31, v47, v32
	v_pk_mul_f32 v[28:29], v[44:45], v[32:33] op_sel_hi:[1,0]
	s_nop 1
	v_mfma_f32_16x16x32_bf16 v[44:47], v[140:143], v[16:19], v[28:31]
	s_nop 2
	v_mul_f32_e64 v30, v54, v38
	v_mul_f32_e64 v31, v55, v38
	v_pk_mul_f32 v[28:29], v[52:53], v[38:39] op_sel_hi:[1,0]
	s_waitcnt lgkmcnt(8)
	s_nop 0
	v_mfma_f32_16x16x32_bf16 v[48:51], v[136:139], v[24:27], v[28:31]
	s_nop 2
	v_mul_f32_e64 v30, v90, v32
	v_mul_f32_e64 v31, v91, v32
	v_pk_mul_f32 v[28:29], v[88:89], v[32:33] op_sel_hi:[1,0]
	s_nop 1
	v_mfma_f32_16x16x32_bf16 v[52:55], v[136:139], v[16:19], v[28:31]
	s_nop 2
	v_mul_f32_e64 v30, v98, v38
	v_mul_f32_e64 v31, v99, v38
	v_pk_mul_f32 v[28:29], v[96:97], v[38:39] op_sel_hi:[1,0]
	s_waitcnt lgkmcnt(6)
	s_nop 0
	v_mfma_f32_16x16x32_bf16 v[88:91], v[132:135], v[24:27], v[28:31]
	s_nop 2
	v_mul_f32_e64 v30, v102, v32
	v_mul_f32_e64 v31, v103, v32
	v_pk_mul_f32 v[28:29], v[100:101], v[32:33] op_sel_hi:[1,0]
	s_nop 1
	v_mfma_f32_16x16x32_bf16 v[100:103], v[132:135], v[16:19], v[28:31]
	s_nop 2
	v_mul_f32_e64 v30, v106, v38
	v_mul_f32_e64 v31, v107, v38
	v_pk_mul_f32 v[28:29], v[104:105], v[38:39] op_sel_hi:[1,0]
	s_waitcnt lgkmcnt(4)
	s_nop 0
	v_mfma_f32_16x16x32_bf16 v[104:107], v[128:131], v[24:27], v[28:31]
	v_mul_f32_e64 v26, v110, v32
	v_mul_f32_e64 v27, v111, v32
	v_pk_mul_f32 v[24:25], v[108:109], v[32:33] op_sel_hi:[1,0]
	s_nop 1
	v_mfma_f32_16x16x32_bf16 v[108:111], v[128:131], v[16:19], v[24:27]
	v_add_f32_e32 v146, v39, v36
	v_add_f32_e32 v16, v60, v37
	v_add_f32_e32 v16, v61, v16
	v_add_f32_e32 v16, v62, v16
	v_add_f32_e32 v16, v63, v16
	v_add_f32_e32 v16, v33, v16
	v_add_f32_e32 v16, v34, v16
	v_fmac_f32_e32 v146, v147, v32
	v_add_f32_e32 v147, v35, v16
	v_add_u32_e32 v16, s40, v214
	v_add_u32_e32 v24, s40, v216
	v_med3_i32 v16, v16, 0, s75
	v_med3_i32 v24, v24, 0, s75
	v_lshl_add_u32 v16, v16, 9, v152
	v_lshl_add_u32 v24, v24, 9, v152
	global_load_dwordx4 v[16:19], v16, s[98:99]
	v_or_b32_e32 v32, 0xfffffd00, v167
	global_load_dwordx4 v[60:63], v24, s[98:99]
	v_add_u32_e32 v24, s40, v218
	v_add_u32_e32 v32, s40, v32
	v_med3_i32 v24, v24, 0, s75
	v_lshl_add_u32 v24, v24, 9, v152
	global_load_dwordx4 v[92:95], v24, s[98:99]
	v_add_u32_e32 v24, s40, v220
	v_fmac_f32_e32 v147, v151, v38
	s_nop 0
	v_med3_i32 v24, v24, 0, s75
	v_lshl_add_u32 v24, v24, 9, v152
	global_load_dwordx4 v[96:99], v24, s[98:99]
	v_add_u32_e32 v24, s40, v221
	v_med3_i32 v24, v24, 0, s75
	v_med3_i32 v32, v32, 0, s75
	v_lshl_add_u32 v28, v24, 9, v158
	v_lshl_add_u32 v36, v32, 9, v158
	global_load_dwordx4 v[24:27], v28, s[100:101]
	s_nop 0
	global_load_dwordx4 v[28:31], v28, s[100:101] offset:64
	s_nop 0
	global_load_dwordx4 v[32:35], v36, s[100:101]
	s_nop 0
	global_load_dwordx4 v[36:39], v36, s[100:101] offset:64
	ds_read_b64_tr_b16 v[142:143], v169 offset:6912
	ds_read_b64_tr_b16 v[140:141], v169 offset:4608
	ds_read_b64_tr_b16 v[132:133], v169 offset:4640
	ds_read_b64_tr_b16 v[134:135], v169 offset:6944
	ds_read_b64_tr_b16 v[128:129], v169 offset:4672
	ds_read_b64_tr_b16 v[130:131], v169 offset:6976
	ds_read_b64_tr_b16 v[136:137], v169 offset:4704
	ds_read_b64_tr_b16 v[138:139], v169 offset:7008
	s_waitcnt vmcnt(15)
	ds_write_b128 v241, v[112:115]
	s_waitcnt vmcnt(14)
	ds_write_b128 v242, v[116:119]
	s_waitcnt vmcnt(13)
	ds_write_b128 v243, v[120:123]
	s_waitcnt vmcnt(12)
	ds_write_b128 v244, v[124:127]
	v_mfma_f32_16x16x32_bf16 v[112:115], v[72:75], v[4:7], 0
	v_mfma_f32_16x16x32_bf16 v[116:119], v[64:67], v[4:7], 0
	v_mfma_f32_16x16x32_bf16 v[112:115], v[68:71], v[8:11], v[112:115]
	v_mfma_f32_16x16x32_bf16 v[116:119], v[56:59], v[8:11], v[116:119]
	s_nop 5
	v_sub_u32_e32 v57, v197, v150
	v_add_u32_e32 v59, 1, v57
	v_cmp_gt_u32_e64 s[0:1], v59, v149
	v_cmp_gt_u32_e32 vcc, v57, v149
	s_nop 0
	v_cndmask_b32_e64 v113, v113, v246, s[0:1]
	s_nop 0
	v_cndmask_b32_e32 v112, v112, v246, vcc
	v_max_f32_e32 v58, v112, v113
	v_add_u32_e32 v59, 2, v57
	v_add_u32_e32 v64, 3, v57
	v_cmp_gt_u32_e64 s[22:23], v59, v149
	v_cmp_gt_u32_e64 s[24:25], v64, v149
	s_nop 0
	v_cndmask_b32_e64 v114, v114, v246, s[22:23]
	v_cndmask_b32_e64 v115, v115, v246, s[24:25]
	v_max3_f32 v58, v58, v114, v115
	v_add_u32_e32 v59, 16, v57
	v_add_u32_e32 v64, 17, v57
	v_cmp_gt_u32_e64 s[26:27], v59, v149
	v_cmp_gt_u32_e64 s[28:29], v64, v149
	s_nop 0
	v_cndmask_b32_e64 v116, v116, v246, s[26:27]
	v_cndmask_b32_e64 v117, v117, v246, s[28:29]
	v_max3_f32 v58, v58, v116, v117
	v_add_u32_e32 v59, 18, v57
	v_add_u32_e32 v57, 19, v57
	v_cmp_gt_u32_e64 s[30:31], v59, v149
	v_cmp_gt_u32_e64 s[34:35], v57, v149
	s_nop 0
	v_cndmask_b32_e64 v118, v118, v246, s[30:31]
	v_cndmask_b32_e64 v119, v119, v246, s[34:35]
	v_max3_f32 v57, v58, v118, v119
	v_mov_b32_e32 v59, v57
	s_nop 1
	v_permlane32_swap_b32_e32 v59, v57
	v_max_f32_e32 v57, v57, v59
	s_nop 1
	v_mov_b32_e32 v59, v57
	s_nop 1
	v_permlane16_swap_b32_e32 v59, v57
	v_max3_f32 v175, v145, v57, v59
	v_sub_f32_e32 v57, v145, v175
	v_exp_f32_e32 v72, v57
	v_sub_f32_e32 v57, v112, v175
	v_exp_f32_e32 v57, v57
	v_sub_f32_e32 v64, v113, v175
	v_exp_f32_e32 v64, v64
	s_nop 0
	v_sub_f32_e32 v65, v114, v175
	v_exp_f32_e32 v65, v65
	v_sub_f32_e32 v66, v115, v175
	v_exp_f32_e32 v66, v66
	v_sub_f32_e32 v67, v116, v175
	v_mov_b32_e32 v177, v144
	v_add_f32_e32 v59, v64, v57
	v_exp_f32_e32 v67, v67
	v_sub_f32_e32 v70, v117, v175
	v_cvt_pk_bf16_f32 v64, v57, v64
	v_exp_f32_e32 v70, v70
	v_sub_f32_e32 v71, v118, v175
	v_sub_f32_e32 v73, v119, v175
	v_mov_b32_e32 v74, 1.0
	v_exp_f32_e32 v71, v71
	v_exp_f32_e32 v73, v73
	v_add_f32_e32 v59, v65, v59
	v_add_f32_e32 v59, v66, v59
	v_add_f32_e32 v59, v67, v59
	v_add_f32_e32 v59, v70, v59
	v_mov_b32_e32 v57, 0
	v_add_f32_e32 v59, v71, v59
	v_cvt_pk_bf16_f32 v65, v65, v66
	v_cvt_pk_bf16_f32 v66, v67, v70
	v_cvt_pk_bf16_f32 v67, v71, v73
	v_mov_b32_e32 v56, 0
	v_pk_mul_f32 v[42:43], v[42:43], v[72:73] op_sel_hi:[1,0]
	v_pk_mul_f32 v[40:41], v[40:41], v[72:73] op_sel_hi:[1,0]
	v_add_f32_e32 v176, v73, v59
	v_add_f32_e32 v178, v56, v57
	v_cvt_pk_bf16_f32 v68, v57, 0
	v_cvt_pk_bf16_f32 v70, v56, 0
	v_mov_b32_e32 v69, v153
	v_mov_b32_e32 v71, v153
	s_waitcnt lgkmcnt(10)
	v_mfma_f32_16x16x32_bf16 v[56:59], v[140:143], v[64:67], v[40:43]
	v_fmac_f32_e32 v176, v147, v72
	v_fmac_f32_e32 v178, v146, v74
	s_nop 0
	v_pk_mul_f32 v[42:43], v[46:47], v[74:75] op_sel_hi:[1,0]
	v_pk_mul_f32 v[40:41], v[44:45], v[74:75] op_sel_hi:[1,0]
	s_nop 1
	v_mfma_f32_16x16x32_bf16 v[112:115], v[140:143], v[68:71], v[40:43]
	s_nop 2
	v_mul_f32_e64 v42, v50, v72
	v_mul_f32_e64 v43, v51, v72
	v_pk_mul_f32 v[40:41], v[48:49], v[72:73] op_sel_hi:[1,0]
	v_add_u32_e32 v48, s40, v227
	v_min_i32_e32 v49, s75, v48
	s_waitcnt lgkmcnt(8)
	v_mfma_f32_16x16x32_bf16 v[116:119], v[132:135], v[64:67], v[40:43]
	s_nop 2
	v_mul_f32_e64 v42, v54, v74
	v_mul_f32_e64 v43, v55, v74
	v_pk_mul_f32 v[40:41], v[52:53], v[74:75] op_sel_hi:[1,0]
	s_nop 1
	v_mfma_f32_16x16x32_bf16 v[120:123], v[132:135], v[68:71], v[40:43]
	s_nop 2
	v_mul_f32_e64 v42, v90, v72
	v_mul_f32_e64 v43, v91, v72
	v_pk_mul_f32 v[40:41], v[88:89], v[72:73] op_sel_hi:[1,0]
	s_waitcnt lgkmcnt(6)
	s_nop 0
	v_mfma_f32_16x16x32_bf16 v[124:127], v[128:131], v[64:67], v[40:43]
	s_nop 2
	v_mul_f32_e64 v42, v102, v74
	v_mul_f32_e64 v43, v103, v74
	v_pk_mul_f32 v[40:41], v[100:101], v[74:75] op_sel_hi:[1,0]
	s_nop 1
	v_mfma_f32_16x16x32_bf16 v[128:131], v[128:131], v[68:71], v[40:43]
	s_nop 2
	v_mul_f32_e64 v42, v106, v72
	v_mul_f32_e64 v43, v107, v72
	v_pk_mul_f32 v[40:41], v[104:105], v[72:73] op_sel_hi:[1,0]
	s_waitcnt lgkmcnt(4)
	s_nop 0
	v_mfma_f32_16x16x32_bf16 v[132:135], v[136:139], v[64:67], v[40:43]
	s_nop 2
	v_mul_f32_e64 v42, v110, v74
	v_mul_f32_e64 v43, v111, v74
	v_pk_mul_f32 v[40:41], v[108:109], v[74:75] op_sel_hi:[1,0]
	s_nop 1
	v_mfma_f32_16x16x32_bf16 v[136:139], v[136:139], v[68:71], v[40:43]
	s_nop 2
	v_add_u32_e32 v40, s40, v222
	v_med3_i32 v40, v40, 0, s75
	v_lshl_add_u32 v40, v40, 9, v152
	global_load_dwordx4 v[64:67], v40, s[98:99]
	v_add_u32_e32 v40, s40, v223
	v_med3_i32 v40, v40, 0, s75
	v_lshl_add_u32 v40, v40, 9, v152
	global_load_dwordx4 v[68:71], v40, s[98:99]
	v_add_u32_e32 v40, s40, v224
	v_med3_i32 v40, v40, 0, s75
	v_lshl_add_u32 v40, v40, 9, v152
	global_load_dwordx4 v[72:75], v40, s[98:99]
	v_add_u32_e32 v40, s40, v225
	v_med3_i32 v40, v40, 0, s75
	v_lshl_add_u32 v40, v40, 9, v152
	global_load_dwordx4 v[88:91], v40, s[98:99]
	v_add_u32_e32 v40, s40, v226
	v_med3_i32 v40, v40, 0, s75
	v_cmp_lt_i32_e32 vcc, -1, v48
	s_nop 1
	v_cndmask_b32_e32 v48, 0, v49, vcc
	v_lshl_add_u32 v44, v40, 9, v158
	v_lshl_add_u32 v52, v48, 9, v158
	global_load_dwordx4 v[40:43], v44, s[100:101]
	s_nop 0
	global_load_dwordx4 v[44:47], v44, s[100:101] offset:64
	s_nop 0
	global_load_dwordx4 v[48:51], v52, s[100:101]
	s_nop 0
	global_load_dwordx4 v[52:55], v52, s[100:101] offset:64
	ds_read_b64_tr_b16 v[102:103], v169 offset:2304
	ds_read_b64_tr_b16 v[100:101], v169
	ds_read_b64_tr_b16 v[108:109], v169 offset:32
	ds_read_b64_tr_b16 v[110:111], v169 offset:2336
	ds_read_b64_tr_b16 v[144:145], v169 offset:64
	ds_read_b64_tr_b16 v[146:147], v169 offset:2368
	ds_read_b64_tr_b16 v[140:141], v169 offset:96
	ds_read_b64_tr_b16 v[142:143], v169 offset:2400
	s_waitcnt vmcnt(15)
	ds_write_b128 v241, v[16:19] offset:4608
	s_waitcnt vmcnt(14)
	ds_write_b128 v242, v[60:63] offset:4608
	s_waitcnt vmcnt(13)
	ds_write_b128 v243, v[92:95] offset:4608
	s_waitcnt vmcnt(12)
	ds_write_b128 v244, v[96:99] offset:4608
	v_mfma_f32_16x16x32_bf16 v[16:19], v[84:87], v[4:7], 0
	v_mfma_f32_16x16x32_bf16 v[60:63], v[76:79], v[4:7], 0
	v_mfma_f32_16x16x32_bf16 v[16:19], v[80:83], v[8:11], v[16:19]
	v_mfma_f32_16x16x32_bf16 v[60:63], v[20:23], v[8:11], v[60:63]
	s_nop 5
	v_sub_u32_e32 v21, v198, v150
	v_add_u32_e32 v23, 1, v21
	v_cmp_gt_u32_e64 s[0:1], v23, v149
	v_cmp_gt_u32_e32 vcc, v21, v149
	s_nop 0
	v_cndmask_b32_e64 v17, v17, v246, s[0:1]
	s_nop 0
	v_cndmask_b32_e32 v16, v16, v246, vcc
	v_max_f32_e32 v22, v16, v17
	v_add_u32_e32 v23, 2, v21
	v_add_u32_e32 v76, 3, v21
	v_cmp_gt_u32_e64 s[22:23], v23, v149
	v_cmp_gt_u32_e64 s[24:25], v76, v149
	s_nop 0
	v_cndmask_b32_e64 v18, v18, v246, s[22:23]
	v_cndmask_b32_e64 v19, v19, v246, s[24:25]
	v_max3_f32 v22, v22, v18, v19
	v_add_u32_e32 v23, 16, v21
	v_add_u32_e32 v76, 17, v21
	v_cmp_gt_u32_e64 s[26:27], v23, v149
	v_cmp_gt_u32_e64 s[28:29], v76, v149
	s_nop 0
	v_cndmask_b32_e64 v60, v60, v246, s[26:27]
	v_cndmask_b32_e64 v61, v61, v246, s[28:29]
	v_max3_f32 v22, v22, v60, v61
	v_add_u32_e32 v23, 18, v21
	v_add_u32_e32 v21, 19, v21
	v_cmp_gt_u32_e64 s[30:31], v23, v149
	v_cmp_gt_u32_e64 s[34:35], v21, v149
	s_nop 0
	v_cndmask_b32_e64 v62, v62, v246, s[30:31]
	v_cndmask_b32_e64 v63, v63, v246, s[34:35]
	v_max3_f32 v21, v22, v62, v63
	v_mov_b32_e32 v23, v21
	s_nop 1
	v_permlane32_swap_b32_e32 v23, v21
	v_max_f32_e32 v21, v21, v23
	s_nop 1
	v_mov_b32_e32 v23, v21
	s_nop 1
	v_permlane16_swap_b32_e32 v23, v21
	v_max3_f32 v151, v175, v21, v23
	v_sub_f32_e32 v16, v16, v151
	v_exp_f32_e32 v16, v16
	v_sub_f32_e32 v17, v17, v151
	v_exp_f32_e32 v17, v17
	v_sub_f32_e32 v18, v18, v151
	v_exp_f32_e32 v18, v18
	v_sub_f32_e32 v19, v19, v151
	v_exp_f32_e32 v19, v19
	v_sub_f32_e32 v23, v60, v151
	v_sub_f32_e32 v21, v175, v151
	v_exp_f32_e32 v23, v23
	v_sub_f32_e32 v60, v61, v151
	v_exp_f32_e32 v76, v21
	v_exp_f32_e32 v60, v60
	v_sub_f32_e32 v61, v62, v151
	v_add_f32_e32 v21, v17, v16
	v_exp_f32_e32 v61, v61
	v_sub_f32_e32 v62, v63, v151
	v_add_f32_e32 v21, v18, v21
	v_exp_f32_e32 v62, v62
	v_add_f32_e32 v21, v19, v21
	v_add_f32_e32 v21, v23, v21
	v_add_f32_e32 v21, v60, v21
	v_add_f32_e32 v21, v61, v21
	v_mov_b32_e32 v175, v177
	v_add_f32_e32 v149, v62, v21
	v_cvt_pk_bf16_f32 v16, v16, v17
	v_cvt_pk_bf16_f32 v17, v18, v19
	v_cvt_pk_bf16_f32 v18, v23, v60
	v_mov_b32_e32 v60, 1.0
	v_cvt_pk_bf16_f32 v19, v61, v62
	v_mov_b32_e32 v21, 0
	v_mov_b32_e32 v23, 0
	v_pk_mul_f32 v[58:59], v[58:59], v[76:77] op_sel_hi:[1,0]
	v_pk_mul_f32 v[56:57], v[56:57], v[76:77] op_sel_hi:[1,0]
	v_add_f32_e32 v150, v23, v21
	v_cvt_pk_bf16_f32 v20, v21, 0
	v_cvt_pk_bf16_f32 v22, v23, 0
	v_mov_b32_e32 v21, v153
	v_mov_b32_e32 v23, v153
	s_waitcnt lgkmcnt(10)
	v_mfma_f32_16x16x32_bf16 v[96:99], v[100:103], v[16:19], v[56:59]
	v_fmac_f32_e32 v149, v176, v76
	v_fmac_f32_e32 v150, v178, v60
	s_min_i32 s0, s76, 0
	v_pk_mul_f32 v[58:59], v[114:115], v[60:61] op_sel_hi:[1,0]
	v_pk_mul_f32 v[56:57], v[112:113], v[60:61] op_sel_hi:[1,0]
	s_sub_i32 s0, 15, s0
	s_sub_i32 s1, s75, s76
	v_mfma_f32_16x16x32_bf16 v[100:103], v[100:103], v[20:23], v[56:59]
	s_ashr_i32 s0, s0, 4
	s_ashr_i32 s1, s1, 4
	s_cmpk_lt_i32 s71, 0x3000
	v_pk_mul_f32 v[58:59], v[118:119], v[76:77] op_sel_hi:[1,0]
	v_pk_mul_f32 v[56:57], v[116:117], v[76:77] op_sel_hi:[1,0]
	s_waitcnt lgkmcnt(8)
	s_nop 0
	v_mfma_f32_16x16x32_bf16 v[104:107], v[108:111], v[16:19], v[56:59]
	s_nop 2
	v_mul_f32_e64 v58, v122, v60
	v_mul_f32_e64 v59, v123, v60
	v_pk_mul_f32 v[56:57], v[120:121], v[60:61] op_sel_hi:[1,0]
	s_nop 1
	v_mfma_f32_16x16x32_bf16 v[108:111], v[108:111], v[20:23], v[56:59]
	s_nop 2
	v_mul_f32_e64 v58, v126, v76
	v_mul_f32_e64 v59, v127, v76
	v_pk_mul_f32 v[56:57], v[124:125], v[76:77] op_sel_hi:[1,0]
	s_waitcnt lgkmcnt(6)
	s_nop 0
	v_mfma_f32_16x16x32_bf16 v[112:115], v[144:147], v[16:19], v[56:59]
	s_nop 2
	v_mul_f32_e64 v58, v130, v60
	v_mul_f32_e64 v59, v131, v60
	v_pk_mul_f32 v[56:57], v[128:129], v[60:61] op_sel_hi:[1,0]
	s_nop 1
	v_mfma_f32_16x16x32_bf16 v[116:119], v[144:147], v[20:23], v[56:59]
	v_max_i32_e32 v145, s0, v148
	s_nop 1
	v_pk_mul_f32 v[58:59], v[134:135], v[76:77] op_sel_hi:[1,0]
	v_pk_mul_f32 v[56:57], v[132:133], v[76:77] op_sel_hi:[1,0]
	s_waitcnt lgkmcnt(4)
	s_nop 0
	v_mfma_f32_16x16x32_bf16 v[120:123], v[140:143], v[16:19], v[56:59]
	v_mul_f32_e64 v18, v138, v60
	v_mul_f32_e64 v19, v139, v60
	v_pk_mul_f32 v[16:17], v[136:137], v[60:61] op_sel_hi:[1,0]
	v_add_u32_e32 v56, s40, v228
	s_nop 0
	v_mfma_f32_16x16x32_bf16 v[124:127], v[140:143], v[20:23], v[16:19]
	s_nop 1
	s_nop 0
	v_add_u32_e32 v16, s40, v213
	v_med3_i32 v16, v16, 0, s75
	v_lshl_add_u32 v16, v16, 9, v152
	global_load_dwordx4 v[76:79], v16, s[98:99]
	v_add_u32_e32 v16, s40, v215
	v_med3_i32 v16, v16, 0, s75
	v_lshl_add_u32 v16, v16, 9, v152
	global_load_dwordx4 v[80:83], v16, s[98:99]
	v_add_u32_e32 v16, s40, v217
	v_med3_i32 v16, v16, 0, s75
	v_lshl_add_u32 v16, v16, 9, v152
	global_load_dwordx4 v[84:87], v16, s[98:99]
	v_add_u32_e32 v16, s40, v219
	v_med3_i32 v16, v16, 0, s75
	v_lshl_add_u32 v16, v16, 9, v152
	global_load_dwordx4 v[92:95], v16, s[98:99]
	v_or_b32_e32 v16, s40, v167
	v_min_i32_e32 v16, s75, v16
	v_cndmask_b32_e64 v16, v16, 0, s[38:39]
	v_med3_i32 v56, v56, 0, s75
	v_lshl_add_u32 v20, v16, 9, v158
	v_lshl_add_u32 v60, v56, 9, v158
	global_load_dwordx4 v[16:19], v20, s[100:101]
	s_nop 0
	global_load_dwordx4 v[20:23], v20, s[100:101] offset:64
	s_nop 0
	global_load_dwordx4 v[56:59], v60, s[100:101]
	s_nop 0
	global_load_dwordx4 v[60:63], v60, s[100:101] offset:64
	ds_read_b64_tr_b16 v[132:133], v169 offset:6912
	ds_read_b64_tr_b16 v[130:131], v169 offset:4608
	ds_read_b64_tr_b16 v[134:135], v169 offset:4640
	ds_read_b64_tr_b16 v[136:137], v169 offset:6944
	ds_read_b64_tr_b16 v[138:139], v169 offset:4672
	ds_read_b64_tr_b16 v[140:141], v169 offset:6976
	ds_read_b64_tr_b16 v[176:177], v169 offset:4704
	ds_read_b64_tr_b16 v[178:179], v169 offset:7008
	s_waitcnt vmcnt(15)
	ds_write_b128 v241, v[64:67]
	s_waitcnt vmcnt(14)
	ds_write_b128 v242, v[68:71]
	s_waitcnt vmcnt(13)
	ds_write_b128 v243, v[72:75]
	s_waitcnt vmcnt(12)
	ds_write_b128 v244, v[88:91]
	v_mfma_f32_16x16x32_bf16 v[24:27], v[24:27], v[12:15], 0
	v_mfma_f32_16x16x32_bf16 v[24:27], v[28:31], v[0:3], v[24:27]
	v_mfma_f32_16x16x32_bf16 v[28:31], v[32:35], v[12:15], 0
	v_add_u32_e32 v32, 0x7f8, v249
	v_ashrrev_i32_e32 v32, 4, v32
	v_min3_i32 v32, v32, s1, v248
	v_sub_u32_e32 v144, v32, v145
	v_sub_u32_e32 v33, v154, v145
	s_nop 2
	v_add_u32_e32 v35, 1, v33
	v_cmp_gt_u32_e64 s[0:1], v35, v144
	v_cmp_gt_u32_e32 vcc, v33, v144
	s_nop 0
	v_cndmask_b32_e64 v25, v25, v246, s[0:1]
	s_nop 0
	v_cndmask_b32_e32 v24, v24, v246, vcc
	v_mfma_f32_16x16x32_bf16 v[28:31], v[36:39], v[0:3], v[28:31]
	v_max_f32_e32 v34, v24, v25
	v_add_u32_e32 v35, 2, v33
	v_add_u32_e32 v36, 3, v33
	v_cmp_gt_u32_e64 s[22:23], v35, v144
	v_cmp_gt_u32_e64 s[24:25], v36, v144
	s_nop 0
	v_cndmask_b32_e64 v26, v26, v246, s[22:23]
	v_cndmask_b32_e64 v27, v27, v246, s[24:25]
	v_max3_f32 v34, v34, v26, v27
	v_add_u32_e32 v35, 16, v33
	v_add_u32_e32 v36, 17, v33
	v_cmp_gt_u32_e64 s[26:27], v35, v144
	v_cmp_gt_u32_e64 s[28:29], v36, v144
	s_nop 0
	v_cndmask_b32_e64 v28, v28, v246, s[26:27]
	v_cndmask_b32_e64 v29, v29, v246, s[28:29]
	v_max3_f32 v34, v34, v28, v29
	v_add_u32_e32 v35, 18, v33
	v_add_u32_e32 v33, 19, v33
	v_cmp_gt_u32_e64 s[30:31], v35, v144
	v_cmp_gt_u32_e64 s[34:35], v33, v144
	s_nop 0
	v_cndmask_b32_e64 v30, v30, v246, s[30:31]
	v_cndmask_b32_e64 v31, v31, v246, s[34:35]
	v_max3_f32 v33, v34, v30, v31
	s_nop 1
	v_mov_b32_e32 v34, v33
	s_nop 1
	v_permlane32_swap_b32_e32 v34, v33
	v_max_f32_e32 v33, v33, v34
	s_nop 1
	v_mov_b32_e32 v34, v33
	s_nop 1
	v_permlane16_swap_b32_e32 v34, v33
	v_max3_f32 v128, v175, v33, v34
	v_sub_f32_e32 v24, v24, v128
	v_exp_f32_e32 v24, v24
	v_sub_f32_e32 v37, v175, v128
	v_exp_f32_e32 v38, v37
	v_mov_b32_e32 v129, v151
	v_cndmask_b32_e64 v37, v24, 0, vcc
	v_sub_f32_e32 v24, v25, v128
	v_exp_f32_e32 v24, v24
	v_mov_b32_e32 v36, 1.0
	v_cndmask_b32_e64 v65, v24, 0, s[0:1]
	v_sub_f32_e32 v24, v26, v128
	v_exp_f32_e32 v24, v24
	v_mov_b32_e32 v33, v153
	v_mov_b32_e32 v35, v153
	v_mov_b32_e32 v39, 0
	v_cndmask_b32_e64 v66, v24, 0, s[22:23]
	v_sub_f32_e32 v24, v27, v128
	v_exp_f32_e32 v24, v24
	s_nop 0
	v_cndmask_b32_e64 v67, v24, 0, s[24:25]
	v_sub_f32_e32 v24, v28, v128
	v_exp_f32_e32 v24, v24
	v_mov_b32_e32 v64, 0
	v_cvt_pk_bf16_f32 v32, v39, 0
	v_cvt_pk_bf16_f32 v34, v64, 0
	v_cndmask_b32_e64 v68, v24, 0, s[26:27]
	v_sub_f32_e32 v24, v29, v128
	v_exp_f32_e32 v24, v24
	v_pk_mul_f32 v[28:29], v[96:97], v[36:37] op_sel_hi:[1,0]
	v_cvt_pk_bf16_f32 v25, v66, v67
	v_cndmask_b32_e64 v69, v24, 0, s[28:29]
	v_sub_f32_e32 v24, v30, v128
	v_exp_f32_e32 v24, v24
	v_cvt_pk_bf16_f32 v26, v68, v69
	v_cndmask_b32_e64 v70, v24, 0, s[30:31]
	v_sub_f32_e32 v24, v31, v128
	v_exp_f32_e32 v24, v24
	v_pk_mul_f32 v[30:31], v[98:99], v[36:37] op_sel_hi:[1,0]
	v_cndmask_b32_e64 v71, v24, 0, s[34:35]
	v_cvt_pk_bf16_f32 v24, v37, v65
	v_cvt_pk_bf16_f32 v27, v70, v71
	s_waitcnt lgkmcnt(10)
	v_mfma_f32_16x16x32_bf16 v[96:99], v[130:133], v[32:35], v[28:31]
	s_nop 2
	v_mul_f32_e64 v30, v102, v38
	v_mul_f32_e64 v31, v103, v38
	v_pk_mul_f32 v[28:29], v[100:101], v[38:39] op_sel_hi:[1,0]
	s_nop 1
	v_mfma_f32_16x16x32_bf16 v[100:103], v[130:133], v[24:27], v[28:31]
	s_nop 2
	v_mul_f32_e64 v30, v106, v36
	v_mul_f32_e64 v31, v107, v36
	v_pk_mul_f32 v[28:29], v[104:105], v[36:37] op_sel_hi:[1,0]
	s_waitcnt lgkmcnt(8)
	s_nop 0
	v_mfma_f32_16x16x32_bf16 v[104:107], v[134:137], v[32:35], v[28:31]
	s_nop 2
	v_mul_f32_e64 v30, v110, v38
	v_mul_f32_e64 v31, v111, v38
	v_pk_mul_f32 v[28:29], v[108:109], v[38:39] op_sel_hi:[1,0]
	s_nop 1
	v_mfma_f32_16x16x32_bf16 v[108:111], v[134:137], v[24:27], v[28:31]
	s_nop 2
	v_mul_f32_e64 v30, v114, v36
	v_mul_f32_e64 v31, v115, v36
	v_pk_mul_f32 v[28:29], v[112:113], v[36:37] op_sel_hi:[1,0]
	s_waitcnt lgkmcnt(6)
	s_nop 0
	v_mfma_f32_16x16x32_bf16 v[112:115], v[138:141], v[32:35], v[28:31]
	s_nop 2
	v_mul_f32_e64 v30, v118, v38
	v_mul_f32_e64 v31, v119, v38
	v_pk_mul_f32 v[28:29], v[116:117], v[38:39] op_sel_hi:[1,0]
	s_nop 1
	v_mfma_f32_16x16x32_bf16 v[116:119], v[138:141], v[24:27], v[28:31]
	s_nop 2
	v_mul_f32_e64 v30, v122, v36
	v_mul_f32_e64 v31, v123, v36
	v_pk_mul_f32 v[28:29], v[120:121], v[36:37] op_sel_hi:[1,0]
	s_waitcnt lgkmcnt(4)
	s_nop 0
	v_mfma_f32_16x16x32_bf16 v[120:123], v[176:179], v[32:35], v[28:31]
	v_add_u32_e32 v32, s40, v234
	s_nop 0
	s_nop 0
	v_pk_mul_f32 v[30:31], v[126:127], v[38:39] op_sel_hi:[1,0]
	v_pk_mul_f32 v[28:29], v[124:125], v[38:39] op_sel_hi:[1,0]
	s_nop 1
	v_mfma_f32_16x16x32_bf16 v[124:127], v[176:179], v[24:27], v[28:31]
	v_add_f32_e32 v24, v65, v37
	v_add_f32_e32 v24, v66, v24
	v_add_f32_e32 v24, v67, v24
	v_add_f32_e32 v24, v68, v24
	v_add_f32_e32 v24, v69, v24
	v_add_f32_e32 v24, v70, v24
	v_add_f32_e32 v130, v71, v24
	v_add_f32_e32 v131, v64, v39
	v_add_u32_e32 v24, s40, v229
	v_fmac_f32_e32 v131, v149, v36
	v_fmac_f32_e32 v130, v150, v38
	v_med3_i32 v24, v24, 0, s75
	v_lshl_add_u32 v24, v24, 9, v152
	global_load_dwordx4 v[64:67], v24, s[98:99]
	v_add_u32_e32 v24, s40, v230
	v_med3_i32 v24, v24, 0, s75
	v_lshl_add_u32 v24, v24, 9, v152
	global_load_dwordx4 v[68:71], v24, s[98:99]
	v_add_u32_e32 v24, s40, v231
	v_med3_i32 v24, v24, 0, s75
	v_lshl_add_u32 v24, v24, 9, v152
	global_load_dwordx4 v[72:75], v24, s[98:99]
	v_add_u32_e32 v24, s40, v232
	v_med3_i32 v24, v24, 0, s75
	v_lshl_add_u32 v24, v24, 9, v152
	global_load_dwordx4 v[88:91], v24, s[98:99]
	v_add_u32_e32 v24, s40, v233
	v_med3_i32 v24, v24, 0, s75
	v_med3_i32 v32, v32, 0, s75
	v_lshl_add_u32 v28, v24, 9, v158
	v_lshl_add_u32 v36, v32, 9, v158
	global_load_dwordx4 v[24:27], v28, s[100:101]
	s_nop 0
	global_load_dwordx4 v[28:31], v28, s[100:101] offset:64
	s_nop 0
	global_load_dwordx4 v[32:35], v36, s[100:101]
	s_nop 0
	global_load_dwordx4 v[36:39], v36, s[100:101] offset:64
	ds_read_b64_tr_b16 v[134:135], v169 offset:2304
	ds_read_b64_tr_b16 v[132:133], v169
	ds_read_b64_tr_b16 v[136:137], v169 offset:32
	ds_read_b64_tr_b16 v[138:139], v169 offset:2336
	ds_read_b64_tr_b16 v[140:141], v169 offset:64
	ds_read_b64_tr_b16 v[142:143], v169 offset:2368
	ds_read_b64_tr_b16 v[176:177], v169 offset:96
	ds_read_b64_tr_b16 v[178:179], v169 offset:2400
	s_waitcnt vmcnt(15)
	ds_write_b128 v241, v[76:79] offset:4608
	s_waitcnt vmcnt(14)
	ds_write_b128 v242, v[80:83] offset:4608
	s_waitcnt vmcnt(13)
	ds_write_b128 v243, v[84:87] offset:4608
	s_waitcnt vmcnt(12)
	ds_write_b128 v244, v[92:95] offset:4608
	v_mfma_f32_16x16x32_bf16 v[40:43], v[40:43], v[12:15], 0
	s_nop 5
	v_mov_b32_e32 v77, v153
	v_mfma_f32_16x16x32_bf16 v[40:43], v[44:47], v[0:3], v[40:43]
	v_mfma_f32_16x16x32_bf16 v[44:47], v[48:51], v[12:15], 0
	v_sub_u32_e32 v48, v187, v145
	s_nop 1
	v_add_u32_e32 v51, 1, v48
	v_cmp_gt_u32_e64 s[0:1], v51, v144
	v_cmp_gt_u32_e32 vcc, v48, v144
	s_nop 0
	v_cndmask_b32_e64 v41, v41, v246, s[0:1]
	s_nop 0
	v_cndmask_b32_e32 v40, v40, v246, vcc
	v_mfma_f32_16x16x32_bf16 v[44:47], v[52:55], v[0:3], v[44:47]
	v_max_f32_e32 v50, v40, v41
	v_add_u32_e32 v51, 2, v48
	v_add_u32_e32 v52, 3, v48
	v_cmp_gt_u32_e64 s[22:23], v51, v144
	v_cmp_gt_u32_e64 s[24:25], v52, v144
	v_mov_b32_e32 v79, v153
	v_cndmask_b32_e64 v42, v42, v246, s[22:23]
	v_cndmask_b32_e64 v43, v43, v246, s[24:25]
	v_max3_f32 v50, v50, v42, v43
	v_add_u32_e32 v51, 16, v48
	v_add_u32_e32 v52, 17, v48
	v_cmp_gt_u32_e64 s[26:27], v51, v144
	v_cmp_gt_u32_e64 s[28:29], v52, v144
	s_nop 0
	v_cndmask_b32_e64 v44, v44, v246, s[26:27]
	v_cndmask_b32_e64 v45, v45, v246, s[28:29]
	v_max3_f32 v50, v50, v44, v45
	v_add_u32_e32 v51, 18, v48
	v_add_u32_e32 v48, 19, v48
	v_cmp_gt_u32_e64 s[30:31], v51, v144
	v_cmp_gt_u32_e64 s[34:35], v48, v144
	s_nop 0
	v_cndmask_b32_e64 v46, v46, v246, s[30:31]
	v_cndmask_b32_e64 v47, v47, v246, s[34:35]
	v_max3_f32 v48, v50, v46, v47
	s_nop 1
	v_mov_b32_e32 v50, v48
	s_nop 1
	v_permlane32_swap_b32_e32 v50, v48
	v_max_f32_e32 v48, v48, v50
	s_nop 1
	v_mov_b32_e32 v50, v48
	s_nop 1
	v_permlane16_swap_b32_e32 v50, v48
	v_max3_f32 v148, v128, v48, v50
	v_sub_f32_e32 v40, v40, v148
	v_exp_f32_e32 v40, v40
	v_sub_f32_e32 v41, v41, v148
	v_exp_f32_e32 v41, v41
	v_sub_f32_e32 v42, v42, v148
	v_exp_f32_e32 v42, v42
	v_sub_f32_e32 v43, v43, v148
	v_exp_f32_e32 v43, v43
	v_sub_f32_e32 v44, v44, v148
	v_mov_b32_e32 v146, v129
	v_sub_f32_e32 v48, v128, v148
	v_exp_f32_e32 v44, v44
	v_sub_f32_e32 v45, v45, v148
	v_exp_f32_e32 v86, v48
	v_exp_f32_e32 v45, v45
	v_sub_f32_e32 v46, v46, v148
	v_sub_f32_e32 v47, v47, v148
	v_mov_b32_e32 v84, 1.0
	v_add_f32_e32 v48, v41, v40
	v_exp_f32_e32 v46, v46
	v_exp_f32_e32 v47, v47
	v_add_f32_e32 v48, v42, v48
	v_add_f32_e32 v48, v43, v48
	v_add_f32_e32 v48, v44, v48
	v_add_f32_e32 v48, v45, v48
	v_mov_b32_e32 v49, 0
	v_mov_b32_e32 v51, 0
	v_add_f32_e32 v48, v46, v48
	v_cvt_pk_bf16_f32 v40, v40, v41
	v_cvt_pk_bf16_f32 v41, v42, v43
	v_cvt_pk_bf16_f32 v42, v44, v45
	v_cvt_pk_bf16_f32 v43, v46, v47
	v_pk_mul_f32 v[82:83], v[110:111], v[86:87] op_sel_hi:[1,0]
	v_pk_mul_f32 v[80:81], v[108:109], v[86:87] op_sel_hi:[1,0]
	v_cvt_pk_bf16_f32 v76, v49, 0
	v_cvt_pk_bf16_f32 v78, v51, 0
	v_add_f32_e32 v149, v47, v48
	v_pk_mul_f32 v[46:47], v[98:99], v[84:85] op_sel_hi:[1,0]
	v_pk_mul_f32 v[44:45], v[96:97], v[84:85] op_sel_hi:[1,0]
	s_waitcnt lgkmcnt(8)
	v_mfma_f32_16x16x32_bf16 v[96:99], v[136:139], v[40:43], v[80:83]
	v_add_f32_e32 v147, v51, v49
	v_pk_mul_f32 v[50:51], v[102:103], v[86:87] op_sel_hi:[1,0]
	v_pk_mul_f32 v[48:49], v[100:101], v[86:87] op_sel_hi:[1,0]
	v_pk_mul_f32 v[82:83], v[114:115], v[84:85] op_sel_hi:[1,0]
	v_pk_mul_f32 v[80:81], v[112:113], v[84:85] op_sel_hi:[1,0]
	v_pk_mul_f32 v[54:55], v[106:107], v[84:85] op_sel_hi:[1,0]
	v_pk_mul_f32 v[52:53], v[104:105], v[84:85] op_sel_hi:[1,0]
	s_waitcnt lgkmcnt(6)
	v_mfma_f32_16x16x32_bf16 v[100:103], v[140:143], v[76:79], v[80:83]
	v_fmac_f32_e32 v147, v131, v84
	v_fmac_f32_e32 v149, v130, v86
	s_nop 0
	v_pk_mul_f32 v[82:83], v[118:119], v[86:87] op_sel_hi:[1,0]
	v_pk_mul_f32 v[80:81], v[116:117], v[86:87] op_sel_hi:[1,0]
	v_mfma_f32_16x16x32_bf16 v[44:47], v[132:135], v[76:79], v[44:47]
	s_nop 0
	v_mfma_f32_16x16x32_bf16 v[104:107], v[140:143], v[40:43], v[80:83]
	s_nop 2
	v_mul_f32_e64 v82, v122, v84
	v_mul_f32_e64 v83, v123, v84
	v_pk_mul_f32 v[80:81], v[120:121], v[84:85] op_sel_hi:[1,0]
	v_mfma_f32_16x16x32_bf16 v[52:55], v[136:139], v[76:79], v[52:55]
	v_add_u32_e32 v84, s40, v240
	s_waitcnt lgkmcnt(4)
	v_mfma_f32_16x16x32_bf16 v[108:111], v[176:179], v[76:79], v[80:83]
	v_mul_f32_e64 v78, v126, v86
	v_mul_f32_e64 v79, v127, v86
	v_pk_mul_f32 v[76:77], v[124:125], v[86:87] op_sel_hi:[1,0]
	v_mfma_f32_16x16x32_bf16 v[48:51], v[132:135], v[40:43], v[48:51]
	s_nop 0
	v_mfma_f32_16x16x32_bf16 v[112:115], v[176:179], v[40:43], v[76:79]
	v_add_u32_e32 v40, s40, v235
	s_nop 1
	v_add_u32_e32 v76, s40, v236
	v_med3_i32 v40, v40, 0, s75
	v_med3_i32 v76, v76, 0, s75
	v_lshl_add_u32 v40, v40, 9, v152
	v_lshl_add_u32 v76, v76, 9, v152
	global_load_dwordx4 v[40:43], v40, s[98:99]
	s_nop 0
	global_load_dwordx4 v[116:119], v76, s[98:99]
	v_add_u32_e32 v76, s40, v237
	v_med3_i32 v76, v76, 0, s75
	v_lshl_add_u32 v76, v76, 9, v152
	global_load_dwordx4 v[120:123], v76, s[98:99]
	v_add_u32_e32 v76, s40, v238
	v_med3_i32 v76, v76, 0, s75
	v_lshl_add_u32 v76, v76, 9, v152
	global_load_dwordx4 v[124:127], v76, s[98:99]
	v_add_u32_e32 v76, s40, v239
	v_med3_i32 v76, v76, 0, s75
	v_med3_i32 v84, v84, 0, s75
	v_lshl_add_u32 v80, v76, 9, v158
	v_lshl_add_u32 v84, v84, 9, v158
	global_load_dwordx4 v[76:79], v80, s[100:101]
	s_nop 0
	global_load_dwordx4 v[80:83], v80, s[100:101] offset:64
	s_nop 0
	global_load_dwordx4 v[92:95], v84, s[100:101]
	s_nop 0
	global_load_dwordx4 v[84:87], v84, s[100:101] offset:64
	ds_read_b64_tr_b16 v[142:143], v169 offset:6912
	ds_read_b64_tr_b16 v[140:141], v169 offset:4608
	ds_read_b64_tr_b16 v[136:137], v169 offset:4640
	ds_read_b64_tr_b16 v[138:139], v169 offset:6944
	ds_read_b64_tr_b16 v[132:133], v169 offset:4672
	ds_read_b64_tr_b16 v[134:135], v169 offset:6976
	ds_read_b64_tr_b16 v[128:129], v169 offset:4704
	ds_read_b64_tr_b16 v[130:131], v169 offset:7008
	s_waitcnt vmcnt(15)
	ds_write_b128 v241, v[64:67]
	s_waitcnt vmcnt(14)
	ds_write_b128 v242, v[68:71]
	s_waitcnt vmcnt(13)
	ds_write_b128 v243, v[72:75]
	s_waitcnt vmcnt(12)
	ds_write_b128 v244, v[88:91]
	v_mfma_f32_16x16x32_bf16 v[16:19], v[16:19], v[12:15], 0
	v_mfma_f32_16x16x32_bf16 v[16:19], v[20:23], v[0:3], v[16:19]
	v_mfma_f32_16x16x32_bf16 v[20:23], v[56:59], v[12:15], 0
	s_nop 2
	v_sub_u32_e32 v56, v192, v145
	v_add_u32_e32 v59, 1, v56
	v_cmp_gt_u32_e64 s[0:1], v59, v144
	v_cmp_gt_u32_e32 vcc, v56, v144
	s_nop 0
	v_cndmask_b32_e64 v17, v17, v246, s[0:1]
	s_nop 0
	v_cndmask_b32_e32 v16, v16, v246, vcc
	v_mfma_f32_16x16x32_bf16 v[20:23], v[60:63], v[0:3], v[20:23]
	v_max_f32_e32 v58, v16, v17
	v_add_u32_e32 v59, 2, v56
	v_add_u32_e32 v60, 3, v56
	v_cmp_gt_u32_e64 s[22:23], v59, v144
	v_cmp_gt_u32_e64 s[24:25], v60, v144
	v_mov_b32_e32 v61, v153
	v_cndmask_b32_e64 v18, v18, v246, s[22:23]
	v_cndmask_b32_e64 v19, v19, v246, s[24:25]
	v_max3_f32 v58, v58, v18, v19
	v_add_u32_e32 v59, 16, v56
	v_add_u32_e32 v60, 17, v56
	v_cmp_gt_u32_e64 s[26:27], v59, v144
	v_cmp_gt_u32_e64 s[28:29], v60, v144
	v_mov_b32_e32 v63, v153
	v_cndmask_b32_e64 v20, v20, v246, s[26:27]
	v_cndmask_b32_e64 v60, v21, v246, s[28:29]
	v_max3_f32 v58, v58, v20, v60
	v_add_u32_e32 v59, 18, v56
	v_add_u32_e32 v56, 19, v56
	v_cmp_gt_u32_e64 s[30:31], v59, v144
	v_cmp_gt_u32_e64 s[34:35], v56, v144
	s_nop 0
	v_cndmask_b32_e64 v22, v22, v246, s[30:31]
	v_cndmask_b32_e64 v23, v23, v246, s[34:35]
	v_max3_f32 v56, v58, v22, v23
	s_nop 1
	v_mov_b32_e32 v58, v56
	s_nop 1
	v_permlane32_swap_b32_e32 v58, v56
	v_max_f32_e32 v56, v56, v58
	s_nop 1
	v_mov_b32_e32 v58, v56
	s_nop 1
	v_permlane16_swap_b32_e32 v58, v56
	v_max3_f32 v151, v148, v56, v58
	v_sub_f32_e32 v16, v16, v151
	v_exp_f32_e32 v16, v16
	v_sub_f32_e32 v17, v17, v151
	v_mov_b32_e32 v150, v146
	v_exp_f32_e32 v17, v17
	v_sub_f32_e32 v18, v18, v151
	v_exp_f32_e32 v18, v18
	v_sub_f32_e32 v19, v19, v151
	v_mov_b32_e32 v68, 1.0
	v_exp_f32_e32 v19, v19
	v_sub_f32_e32 v20, v20, v151
	v_sub_f32_e32 v56, v148, v151
	v_exp_f32_e32 v20, v20
	v_sub_f32_e32 v21, v21, v151
	v_exp_f32_e32 v72, v56
	v_exp_f32_e32 v21, v21
	v_sub_f32_e32 v22, v22, v151
	v_add_f32_e32 v56, v17, v16
	v_exp_f32_e32 v22, v22
	v_sub_f32_e32 v23, v23, v151
	v_add_f32_e32 v56, v18, v56
	v_exp_f32_e32 v23, v23
	v_mov_b32_e32 v57, 0
	v_add_f32_e32 v56, v19, v56
	v_mov_b32_e32 v59, 0
	v_add_f32_e32 v56, v20, v56
	v_cndmask_b32_e64 v21, v21, 0, s[28:29]
	v_add_f32_e32 v146, v59, v57
	v_add_f32_e32 v56, v21, v56
	v_fmac_f32_e32 v146, v147, v68
	v_cvt_pk_bf16_f32 v60, v57, 0
	v_cvt_pk_bf16_f32 v62, v59, 0
	v_add_f32_e32 v56, v22, v56
	v_cvt_pk_bf16_f32 v64, v16, v17
	v_cvt_pk_bf16_f32 v65, v18, v19
	v_pk_mul_f32 v[18:19], v[46:47], v[68:69] op_sel_hi:[1,0]
	v_pk_mul_f32 v[16:17], v[44:45], v[68:69] op_sel_hi:[1,0]
	v_pk_mul_f32 v[46:47], v[54:55], v[68:69] op_sel_hi:[1,0]
	v_pk_mul_f32 v[44:45], v[52:53], v[68:69] op_sel_hi:[1,0]
	v_pk_mul_f32 v[54:55], v[102:103], v[68:69] op_sel_hi:[1,0]
	v_pk_mul_f32 v[52:53], v[100:101], v[68:69] op_sel_hi:[1,0]
	v_pk_mul_f32 v[70:71], v[110:111], v[68:69] op_sel_hi:[1,0]
	v_pk_mul_f32 v[68:69], v[108:109], v[68:69] op_sel_hi:[1,0]
	v_add_f32_e32 v147, v23, v56
	v_cvt_pk_bf16_f32 v66, v20, v21
	v_cvt_pk_bf16_f32 v67, v22, v23
	s_waitcnt lgkmcnt(10)
	v_mfma_f32_16x16x32_bf16 v[16:19], v[140:143], v[60:63], v[16:19]
	v_mul_f32_e64 v22, v50, v72
	v_mul_f32_e64 v23, v51, v72
	v_pk_mul_f32 v[20:21], v[48:49], v[72:73] op_sel_hi:[1,0]
	v_pk_mul_f32 v[50:51], v[98:99], v[72:73] op_sel_hi:[1,0]
	s_waitcnt lgkmcnt(8)
	v_mfma_f32_16x16x32_bf16 v[44:47], v[136:139], v[60:63], v[44:47]
	v_mul_f32_e64 v48, v96, v72
	v_mul_f32_e64 v49, v97, v72
	v_pk_mul_f32 v[58:59], v[106:107], v[72:73] op_sel_hi:[1,0]
	v_pk_mul_f32 v[56:57], v[104:105], v[72:73] op_sel_hi:[1,0]
	s_waitcnt lgkmcnt(6)
	v_mfma_f32_16x16x32_bf16 v[52:55], v[132:135], v[60:63], v[52:55]
	v_fmac_f32_e32 v147, v149, v72
	s_waitcnt lgkmcnt(4)
	v_mfma_f32_16x16x32_bf16 v[60:63], v[128:131], v[60:63], v[68:71]
	s_nop 2
	v_mul_f32_e64 v70, v114, v72
	v_mul_f32_e64 v71, v115, v72
	v_pk_mul_f32 v[68:69], v[112:113], v[72:73] op_sel_hi:[1,0]
	v_mfma_f32_16x16x32_bf16 v[20:23], v[140:143], v[64:67], v[20:23]
	v_mfma_f32_16x16x32_bf16 v[48:51], v[136:139], v[64:67], v[48:51]
	v_mfma_f32_16x16x32_bf16 v[56:59], v[132:135], v[64:67], v[56:59]
	v_mfma_f32_16x16x32_bf16 v[64:67], v[128:131], v[64:67], v[68:71]
	ds_read_b64_tr_b16 v[98:99], v169 offset:2304
	ds_read_b64_tr_b16 v[96:97], v169
	ds_read_b64_tr_b16 v[88:89], v169 offset:32
	ds_read_b64_tr_b16 v[90:91], v169 offset:2336
	ds_read_b64_tr_b16 v[72:73], v169 offset:64
	ds_read_b64_tr_b16 v[74:75], v169 offset:2368
	ds_read_b64_tr_b16 v[68:69], v169 offset:96
	ds_read_b64_tr_b16 v[70:71], v169 offset:2400
	s_waitcnt vmcnt(7)
	ds_write_b128 v241, v[40:43] offset:4608
	s_waitcnt vmcnt(6)
	ds_write_b128 v242, v[116:119] offset:4608
	s_waitcnt vmcnt(5)
	ds_write_b128 v243, v[120:123] offset:4608
	s_waitcnt vmcnt(4)
	ds_write_b128 v244, v[124:127] offset:4608
	v_mfma_f32_16x16x32_bf16 v[24:27], v[24:27], v[12:15], 0
	v_mfma_f32_16x16x32_bf16 v[24:27], v[28:31], v[0:3], v[24:27]
	s_nop 5
	v_mov_b32_e32 v41, v153
	v_mov_b32_e32 v43, v153
	v_mfma_f32_16x16x32_bf16 v[28:31], v[32:35], v[12:15], 0
	v_sub_u32_e32 v32, v197, v145
	v_add_u32_e32 v35, 1, v32
	v_cmp_gt_u32_e64 s[0:1], v35, v144
	v_cmp_gt_u32_e32 vcc, v32, v144
	s_nop 0
	v_cndmask_b32_e64 v25, v25, v246, s[0:1]
	s_nop 0
	v_cndmask_b32_e32 v24, v24, v246, vcc
	v_mfma_f32_16x16x32_bf16 v[28:31], v[36:39], v[0:3], v[28:31]
	v_max_f32_e32 v34, v24, v25
	v_add_u32_e32 v35, 2, v32
	v_add_u32_e32 v36, 3, v32
	v_cmp_gt_u32_e64 s[22:23], v35, v144
	v_cmp_gt_u32_e64 s[24:25], v36, v144
	s_nop 0
	v_cndmask_b32_e64 v26, v26, v246, s[22:23]
	v_cndmask_b32_e64 v27, v27, v246, s[24:25]
	v_max3_f32 v34, v34, v26, v27
	v_add_u32_e32 v35, 16, v32
	v_add_u32_e32 v36, 17, v32
	v_cmp_gt_u32_e64 s[26:27], v35, v144
	v_cmp_gt_u32_e64 s[28:29], v36, v144
	s_nop 0
	v_cndmask_b32_e64 v28, v28, v246, s[26:27]
	v_cndmask_b32_e64 v29, v29, v246, s[28:29]
	v_max3_f32 v34, v34, v28, v29
	v_add_u32_e32 v35, 18, v32
	v_add_u32_e32 v32, 19, v32
	v_cmp_gt_u32_e64 s[30:31], v35, v144
	v_cmp_gt_u32_e64 s[34:35], v32, v144
	s_nop 0
	v_cndmask_b32_e64 v30, v30, v246, s[30:31]
	v_cndmask_b32_e64 v31, v31, v246, s[34:35]
	v_max3_f32 v32, v34, v30, v31
	s_nop 1
	v_mov_b32_e32 v34, v32
	s_nop 1
	v_permlane32_swap_b32_e32 v34, v32
	v_max_f32_e32 v32, v32, v34
	s_nop 1
	v_mov_b32_e32 v101, v150
	v_mov_b32_e32 v106, 1.0
	v_mov_b32_e32 v34, v32
	s_nop 0
	s_nop 0
	v_permlane16_swap_b32_e32 v34, v32
	v_mov_b32_e32 v107, 0
	v_max3_f32 v100, v151, v32, v34
	v_sub_f32_e32 v24, v24, v100
	v_exp_f32_e32 v24, v24
	v_sub_f32_e32 v32, v151, v100
	v_exp_f32_e32 v108, v32
	v_cndmask_b32_e64 v110, v24, 0, vcc
	v_sub_f32_e32 v24, v25, v100
	v_exp_f32_e32 v24, v24
	v_mov_b32_e32 v109, 0
	v_cvt_pk_bf16_f32 v40, v107, 0
	v_cvt_pk_bf16_f32 v42, v109, 0
	v_cndmask_b32_e64 v111, v24, 0, s[0:1]
	v_sub_f32_e32 v24, v26, v100
	v_exp_f32_e32 v24, v24
	v_pk_mul_f32 v[18:19], v[18:19], v[106:107] op_sel_hi:[1,0]
	v_pk_mul_f32 v[16:17], v[16:17], v[106:107] op_sel_hi:[1,0]
	v_pk_mul_f32 v[34:35], v[54:55], v[106:107] op_sel_hi:[1,0]
	v_cndmask_b32_e64 v112, v24, 0, s[22:23]
	v_sub_f32_e32 v24, v27, v100
	v_exp_f32_e32 v24, v24
	v_pk_mul_f32 v[26:27], v[46:47], v[106:107] op_sel_hi:[1,0]
	v_pk_mul_f32 v[32:33], v[52:53], v[106:107] op_sel_hi:[1,0]
	v_pk_mul_f32 v[46:47], v[62:63], v[106:107] op_sel_hi:[1,0]
	v_cndmask_b32_e64 v113, v24, 0, s[24:25]
	v_sub_f32_e32 v24, v28, v100
	v_exp_f32_e32 v24, v24
	s_waitcnt lgkmcnt(10)
	v_mfma_f32_16x16x32_bf16 v[16:19], v[96:99], v[40:43], v[16:19]
	v_cvt_pk_bf16_f32 v102, v110, v111
	v_cvt_pk_bf16_f32 v103, v112, v113
	v_cndmask_b32_e64 v114, v24, 0, s[26:27]
	v_sub_f32_e32 v24, v29, v100
	v_exp_f32_e32 v24, v24
	s_waitcnt lgkmcnt(6)
	v_mfma_f32_16x16x32_bf16 v[32:35], v[72:75], v[40:43], v[32:35]
	v_mul_f32_e64 v28, v48, v108
	v_mul_f32_e64 v29, v49, v108
	v_cndmask_b32_e64 v115, v24, 0, s[28:29]
	v_sub_f32_e32 v24, v30, v100
	v_exp_f32_e32 v24, v24
	v_add_f32_e32 v48, v111, v110
	v_add_f32_e32 v48, v112, v48
	v_add_f32_e32 v48, v113, v48
	v_cndmask_b32_e64 v116, v24, 0, s[30:31]
	v_sub_f32_e32 v24, v31, v100
	v_exp_f32_e32 v24, v24
	v_add_f32_e32 v48, v114, v48
	v_add_f32_e32 v48, v115, v48
	v_cvt_pk_bf16_f32 v104, v114, v115
	v_cndmask_b32_e64 v117, v24, 0, s[34:35]
	v_pk_mul_f32 v[24:25], v[44:45], v[106:107] op_sel_hi:[1,0]
	v_pk_mul_f32 v[44:45], v[60:61], v[106:107] op_sel_hi:[1,0]
	v_cvt_pk_bf16_f32 v105, v116, v117
	v_mfma_f32_16x16x32_bf16 v[24:27], v[88:91], v[40:43], v[24:27]
	v_add_f32_e32 v48, v116, v48
	v_pk_mul_f32 v[38:39], v[58:59], v[108:109] op_sel_hi:[1,0]
	v_pk_mul_f32 v[36:37], v[56:57], v[108:109] op_sel_hi:[1,0]
	s_waitcnt lgkmcnt(4)
	v_mfma_f32_16x16x32_bf16 v[40:43], v[68:71], v[40:43], v[44:47]
	v_mul_f32_e64 v30, v50, v108
	v_mul_f32_e64 v31, v51, v108
	v_pk_mul_f32 v[22:23], v[22:23], v[108:109] op_sel_hi:[1,0]
	v_pk_mul_f32 v[20:21], v[20:21], v[108:109] op_sel_hi:[1,0]
	v_pk_mul_f32 v[46:47], v[66:67], v[108:109] op_sel_hi:[1,0]
	v_pk_mul_f32 v[44:45], v[64:65], v[108:109] op_sel_hi:[1,0]
	s_waitcnt vmcnt(3)
	s_waitcnt vmcnt(1)
	s_waitcnt vmcnt(0)
	v_mfma_f32_16x16x32_bf16 v[4:7], v[76:79], v[12:15], 0
	v_mfma_f32_16x16x32_bf16 v[10:13], v[92:95], v[12:15], 0
	s_nop 5
	v_sub_u32_e32 v9, v198, v145
	v_cmp_gt_u32_e64 s[34:35], v9, v144
	v_mov_b32_e32 v15, v153
	v_mfma_f32_16x16x32_bf16 v[4:7], v[80:83], v[0:3], v[4:7]
	v_mfma_f32_16x16x32_bf16 v[0:3], v[84:87], v[0:3], v[10:13]
	s_nop 2
	v_add_u32_e32 v12, 1, v9
	v_cmp_gt_u32_e64 s[30:31], v12, v144
	s_nop 1
	v_cndmask_b32_e64 v4, v4, v246, s[34:35]
	s_nop 0
	v_cndmask_b32_e64 v5, v5, v246, s[30:31]
	v_max_f32_e32 v11, v4, v5
	v_add_u32_e32 v12, 2, v9
	v_add_u32_e32 v13, 3, v9
	v_cmp_gt_u32_e64 s[28:29], v12, v144
	v_cmp_gt_u32_e64 s[26:27], v13, v144
	v_mfma_f32_16x16x32_bf16 v[44:47], v[68:71], v[102:105], v[44:47]
	v_cndmask_b32_e64 v6, v6, v246, s[28:29]
	v_cndmask_b32_e64 v7, v7, v246, s[26:27]
	v_max3_f32 v11, v11, v6, v7
	v_add_u32_e32 v12, 16, v9
	v_add_u32_e32 v13, 17, v9
	v_cmp_gt_u32_e64 s[24:25], v12, v144
	v_cmp_gt_u32_e64 s[22:23], v13, v144
	v_add_f32_e32 v68, v117, v48
	v_cndmask_b32_e64 v0, v0, v246, s[24:25]
	v_cndmask_b32_e64 v13, v1, v246, s[22:23]
	v_max3_f32 v11, v11, v0, v13
	v_add_u32_e32 v12, 18, v9
	v_add_u32_e32 v9, 19, v9
	v_cmp_gt_u32_e64 s[0:1], v12, v144
	v_cmp_gt_u32_e32 vcc, v9, v144
	s_nop 0
	v_cndmask_b32_e64 v2, v2, v246, s[0:1]
	s_nop 0
	v_cndmask_b32_e64 v3, v3, v246, vcc
	v_max3_f32 v9, v11, v2, v3
	s_nop 1
	v_mov_b32_e32 v11, v9
	s_nop 1
	v_permlane32_swap_b32_e32 v11, v9
	v_max_f32_e32 v9, v9, v11
	s_nop 1
	v_mov_b32_e32 v11, v9
	s_nop 1
	v_permlane16_swap_b32_e32 v11, v9
	v_max_f32_e32 v9, v9, v11
	v_mov_b32_e32 v66, 1.0
	v_add_f32_e32 v69, v109, v107
	v_mov_b32_e32 v11, 0
	v_mov_b32_e32 v8, 0
	v_fmac_f32_e32 v69, v146, v106
	v_add_f32_e32 v65, v8, v11
	v_cvt_pk_bf16_f32 v14, v8, 0
	v_max_f32_e32 v8, v100, v9
	v_fmac_f32_e32 v65, v69, v66
	v_sub_f32_e32 v4, v4, v8
	v_cvt_pk_bf16_f32 v12, v11, 0
	v_exp_f32_e32 v4, v4
	v_sub_f32_e32 v5, v5, v8
	v_pk_mul_f32 v[10:11], v[34:35], v[66:67] op_sel_hi:[1,0]
	ds_bpermute_b32 v34, v170, v65
	v_exp_f32_e32 v5, v5
	v_sub_f32_e32 v6, v6, v8
	v_exp_f32_e32 v6, v6
	v_sub_f32_e32 v7, v7, v8
	v_exp_f32_e32 v7, v7
	v_sub_f32_e32 v0, v0, v8
	v_sub_f32_e32 v9, v100, v8
	v_exp_f32_e32 v0, v0
	v_sub_f32_e32 v1, v1, v8
	v_mfma_f32_16x16x32_bf16 v[36:39], v[72:75], v[102:105], v[36:39]
	v_exp_f32_e32 v72, v9
	v_exp_f32_e32 v1, v1
	v_sub_f32_e32 v2, v2, v8
	s_waitcnt lgkmcnt(0)
	v_add_f32_e32 v34, v65, v34
	v_add_f32_e32 v9, v5, v4
	v_exp_f32_e32 v2, v2
	v_sub_f32_e32 v3, v3, v8
	ds_bpermute_b32 v35, v171, v34
	v_add_f32_e32 v9, v6, v9
	v_exp_f32_e32 v3, v3
	v_add_f32_e32 v9, v7, v9
	v_add_f32_e32 v9, v0, v9
	v_cndmask_b32_e64 v1, v1, 0, s[22:23]
	ds_read_b64_tr_b16 v[62:63], v169 offset:6912
	ds_read_b64_tr_b16 v[60:61], v169 offset:4608
	ds_read_b64_tr_b16 v[56:57], v169 offset:4640
	ds_read_b64_tr_b16 v[58:59], v169 offset:6944
	ds_read_b64_tr_b16 v[52:53], v169 offset:4672
	ds_read_b64_tr_b16 v[54:55], v169 offset:6976
	ds_read_b64_tr_b16 v[48:49], v169 offset:4704
	ds_read_b64_tr_b16 v[50:51], v169 offset:7008
	v_add_f32_e32 v9, v1, v9
	v_add_f32_e32 v9, v2, v9
	s_waitcnt lgkmcnt(8)
	v_add_f32_e32 v34, v34, v35
	v_fmac_f32_e32 v68, v147, v108
	v_mov_b32_e32 v13, v153
	v_add_f32_e32 v64, v3, v9
	v_pk_mul_f32 v[8:9], v[32:33], v[66:67] op_sel_hi:[1,0]
	v_div_scale_f32 v35, s[0:1], v34, v34, 1.0
	v_fmac_f32_e32 v64, v68, v72
	v_cvt_pk_bf16_f32 v68, v4, v5
	v_cvt_pk_bf16_f32 v69, v6, v7
	v_pk_mul_f32 v[6:7], v[26:27], v[66:67] op_sel_hi:[1,0]
	v_pk_mul_f32 v[4:5], v[24:25], v[66:67] op_sel_hi:[1,0]
	s_waitcnt lgkmcnt(2)
	v_mfma_f32_16x16x32_bf16 v[24:27], v[52:55], v[12:15], v[8:11]
	v_cvt_pk_bf16_f32 v70, v0, v1
	v_cvt_pk_bf16_f32 v71, v2, v3
	v_pk_mul_f32 v[2:3], v[18:19], v[66:67] op_sel_hi:[1,0]
	v_pk_mul_f32 v[8:9], v[36:37], v[72:73] op_sel_hi:[1,0]
	v_rcp_f32_e32 v36, v35
	v_mfma_f32_16x16x32_bf16 v[20:23], v[96:99], v[102:105], v[20:23]
	v_mul_f32_e64 v10, v38, v72
	v_mul_f32_e64 v11, v39, v72
	v_pk_mul_f32 v[0:1], v[16:17], v[66:67] op_sel_hi:[1,0]
	v_fma_f32 v37, -v35, v36, 1.0
	v_fmac_f32_e32 v36, v37, v36
	v_div_scale_f32 v37, vcc, 1.0, v34, 1.0
	v_mul_f32_e32 v38, v37, v36
	v_fma_f32 v39, -v35, v38, v37
	v_mfma_f32_16x16x32_bf16 v[16:19], v[60:63], v[12:15], v[0:3]
	v_fmac_f32_e32 v38, v39, v36
	v_fma_f32 v35, -v35, v38, v37
	v_div_fmas_f32 v35, v35, v36, v38
	v_mfma_f32_16x16x32_bf16 v[28:31], v[88:91], v[102:105], v[28:31]
	v_mul_f32_e64 v2, v22, v72
	v_mul_f32_e64 v3, v23, v72
	v_pk_mul_f32 v[0:1], v[20:21], v[72:73] op_sel_hi:[1,0]
	v_div_fixup_f32 v34, v35, v34, 1.0
	v_mfma_f32_16x16x32_bf16 v[20:23], v[56:59], v[12:15], v[4:7]
	v_lshl_add_u64 v[32:33], v[156:157], 0, s[56:57]
	v_lshlrev_b64 v[36:37], 11, v[162:163]
	v_pk_mul_f32 v[16:17], v[16:17], v[34:35] op_sel_hi:[1,0]
	v_pk_mul_f32 v[18:19], v[18:19], v[34:35] op_sel_hi:[1,0]
	v_pk_mul_f32 v[6:7], v[30:31], v[72:73] op_sel_hi:[1,0]
	v_pk_mul_f32 v[4:5], v[28:29], v[72:73] op_sel_hi:[1,0]
	v_pk_mul_f32 v[30:31], v[42:43], v[66:67] op_sel_hi:[1,0]
	v_pk_mul_f32 v[28:29], v[40:41], v[66:67] op_sel_hi:[1,0]
	v_lshl_add_u64 v[36:37], v[32:33], 0, v[36:37]
	v_cvt_pk_bf16_f32 v16, v16, v17
	v_cvt_pk_bf16_f32 v17, v18, v19
	s_waitcnt lgkmcnt(0)
	v_mfma_f32_16x16x32_bf16 v[28:31], v[48:51], v[12:15], v[28:31]
	global_store_dwordx2 v[36:37], v[16:17], off
	v_pk_mul_f32 v[16:17], v[20:21], v[34:35] op_sel_hi:[1,0]
	v_pk_mul_f32 v[18:19], v[22:23], v[34:35] op_sel_hi:[1,0]
	v_cvt_pk_bf16_f32 v16, v16, v17
	v_cvt_pk_bf16_f32 v17, v18, v19
	global_store_dwordx2 v[36:37], v[16:17], off offset:32
	v_pk_mul_f32 v[16:17], v[24:25], v[34:35] op_sel_hi:[1,0]
	v_pk_mul_f32 v[18:19], v[26:27], v[34:35] op_sel_hi:[1,0]
	v_cvt_pk_bf16_f32 v16, v16, v17
	v_cvt_pk_bf16_f32 v17, v18, v19
	global_store_dwordx2 v[36:37], v[16:17], off offset:64
	v_pk_mul_f32 v[16:17], v[28:29], v[34:35] op_sel_hi:[1,0]
	v_pk_mul_f32 v[18:19], v[30:31], v[34:35] op_sel_hi:[1,0]
	v_cvt_pk_bf16_f32 v16, v16, v17
	v_cvt_pk_bf16_f32 v17, v18, v19
	global_store_dwordx2 v[36:37], v[16:17], off offset:96
	ds_bpermute_b32 v16, v170, v64
	v_mfma_f32_16x16x32_bf16 v[0:3], v[60:63], v[68:71], v[0:3]
	v_mul_f32_e64 v14, v46, v72
	v_mul_f32_e64 v15, v47, v72
	v_pk_mul_f32 v[12:13], v[44:45], v[72:73] op_sel_hi:[1,0]
	s_waitcnt lgkmcnt(0)
	v_add_f32_e32 v16, v64, v16
	ds_bpermute_b32 v17, v171, v16
	v_mfma_f32_16x16x32_bf16 v[4:7], v[56:59], v[68:71], v[4:7]
	s_waitcnt lgkmcnt(0)
	v_add_f32_e32 v16, v16, v17
	v_div_scale_f32 v17, s[0:1], v16, v16, 1.0
	v_rcp_f32_e32 v18, v17
	v_mfma_f32_16x16x32_bf16 v[8:11], v[52:55], v[68:71], v[8:11]
	v_fma_f32 v19, -v17, v18, 1.0
	v_fmac_f32_e32 v18, v19, v18
	v_div_scale_f32 v19, vcc, 1.0, v16, 1.0
	v_mul_f32_e32 v20, v19, v18
	v_fma_f32 v21, -v17, v20, v19
	v_fmac_f32_e32 v20, v21, v18
	v_fma_f32 v17, -v17, v20, v19
	v_div_fmas_f32 v17, v17, v18, v20
	v_div_fixup_f32 v16, v17, v16, 1.0
	v_lshlrev_b64 v[18:19], 11, v[160:161]
	v_pk_mul_f32 v[0:1], v[0:1], v[16:17] op_sel_hi:[1,0]
	v_pk_mul_f32 v[2:3], v[2:3], v[16:17] op_sel_hi:[1,0]
	v_lshl_add_u64 v[18:19], v[32:33], 0, v[18:19]
	v_cvt_pk_bf16_f32 v0, v0, v1
	v_cvt_pk_bf16_f32 v1, v2, v3
	v_mfma_f32_16x16x32_bf16 v[12:15], v[48:51], v[68:71], v[12:15]
	global_store_dwordx2 v[18:19], v[0:1], off
	v_pk_mul_f32 v[0:1], v[4:5], v[16:17] op_sel_hi:[1,0]
	v_pk_mul_f32 v[2:3], v[6:7], v[16:17] op_sel_hi:[1,0]
	v_cvt_pk_bf16_f32 v0, v0, v1
	v_cvt_pk_bf16_f32 v1, v2, v3
	global_store_dwordx2 v[18:19], v[0:1], off offset:32
	v_pk_mul_f32 v[0:1], v[8:9], v[16:17] op_sel_hi:[1,0]
	v_pk_mul_f32 v[2:3], v[10:11], v[16:17] op_sel_hi:[1,0]
	v_cvt_pk_bf16_f32 v0, v0, v1
	v_cvt_pk_bf16_f32 v1, v2, v3
	global_store_dwordx2 v[18:19], v[0:1], off offset:64
	v_pk_mul_f32 v[0:1], v[12:13], v[16:17] op_sel_hi:[1,0]
	v_pk_mul_f32 v[2:3], v[14:15], v[16:17] op_sel_hi:[1,0]
	v_cvt_pk_bf16_f32 v0, v0, v1
	v_cvt_pk_bf16_f32 v1, v2, v3
	global_store_dwordx2 v[18:19], v[0:1], off offset:96
	s_cbranch_scc1 .LBB0_246
	s_mov_b32 s76, s79
	v_readlane_b32 s72, v253, 43
	v_xor_b32_e32 v240, 32, v174
	v_xor_b32_e32 v241, 16, v174
	v_xor_b32_e32 v242, 8, v174
	v_xor_b32_e32 v243, 4, v174
	v_xor_b32_e32 v244, 2, v174
	v_xor_b32_e32 v245, 1, v174
	v_and_b32_e32 v246, 64, v174
